# GEMM mainloops: per-MFMA-block priority flips replaced by one static raise for waves 0..3 per GEMM phase
# baseline (speedup 1.0000x reference)
.LBB0_101:
	s_setprio 0
	s_cmp_lt_u32 s24, 0x100
	s_cbranch_scc0 .Lsprio_101
	s_setprio 1

.LBB0_121:
	ds_read_b128 v[128:131], v182
	ds_read_b128 v[132:135], v182 offset:1024
	ds_read_b128 v[136:139], v182 offset:2048
	ds_read_b128 v[140:143], v182 offset:3072
	ds_read_b128 v[144:147], v183
	ds_read_b128 v[174:177], v183 offset:1024
	ds_read_b128 v[190:193], v183 offset:2048
	ds_read_b128 v[194:197], v183 offset:3072
	s_add_u32 s38, s36, 0xfff80080
	s_addc_u32 s39, s37, -1
	s_cmp_eq_u32 s50, 28
	s_cselect_b32 s41, s7, s39
	s_cselect_b32 s40, s9, s38
	s_cselect_b32 s39, s79, vcc_hi
	s_cselect_b32 s38, s85, vcc_lo
	v_lshl_add_u64 v[230:231], s[36:37], 0, v[164:165]
	s_add_i32 m0, s45, 0xc000
	ds_read_b128 v[198:201], v184
	ds_read_b128 v[202:205], v184 offset:1024
	ds_read_b128 v[206:209], v184 offset:2048
	ds_read_b128 v[210:213], v184 offset:3072
	ds_read_b128 v[214:217], v184 offset:4096
	ds_read_b128 v[218:221], v184 offset:5120
	ds_read_b128 v[222:225], v184 offset:6144
	ds_read_b128 v[226:229], v184 offset:7168
	global_load_lds_dwordx4 v[230:231], off
	v_lshl_add_u64 v[230:231], s[36:37], 0, v[166:167]
	s_add_i32 m0, s45, 0xe000
	s_nop 0
	global_load_lds_dwordx4 v[230:231], off
	s_waitcnt vmcnt(8)
	s_waitcnt lgkmcnt(0)
	s_barrier
	s_waitcnt lgkmcnt(0)
	v_mfma_f32_16x16x32_bf16 v[124:127], v[128:131], v[198:201], v[124:127]
	v_mfma_f32_16x16x32_bf16 v[120:123], v[136:139], v[198:201], v[120:123]
	v_mfma_f32_16x16x32_bf16 v[108:111], v[128:131], v[206:209], v[108:111]
	v_mfma_f32_16x16x32_bf16 v[104:107], v[136:139], v[206:209], v[104:107]
	v_mfma_f32_16x16x32_bf16 v[92:95], v[128:131], v[214:217], v[92:95]
	v_mfma_f32_16x16x32_bf16 v[88:91], v[136:139], v[214:217], v[88:91]
	v_mfma_f32_16x16x32_bf16 v[76:79], v[128:131], v[222:225], v[76:79]
	v_mfma_f32_16x16x32_bf16 v[72:75], v[136:139], v[222:225], v[72:75]
	v_mfma_f32_16x16x32_bf16 v[124:127], v[132:135], v[202:205], v[124:127]
	v_mfma_f32_16x16x32_bf16 v[120:123], v[140:143], v[202:205], v[120:123]
	v_mfma_f32_16x16x32_bf16 v[108:111], v[132:135], v[210:213], v[108:111]
	v_mfma_f32_16x16x32_bf16 v[104:107], v[140:143], v[210:213], v[104:107]
	v_mfma_f32_16x16x32_bf16 v[92:95], v[132:135], v[218:221], v[92:95]
	v_mfma_f32_16x16x32_bf16 v[88:91], v[140:143], v[218:221], v[88:91]
	v_mfma_f32_16x16x32_bf16 v[76:79], v[132:135], v[226:229], v[76:79]
	v_mfma_f32_16x16x32_bf16 v[72:75], v[140:143], v[226:229], v[72:75]
	v_mfma_f32_16x16x32_bf16 v[116:119], v[144:147], v[198:201], v[116:119]
	v_mfma_f32_16x16x32_bf16 v[112:115], v[190:193], v[198:201], v[112:115]
	v_mfma_f32_16x16x32_bf16 v[100:103], v[144:147], v[206:209], v[100:103]
	v_mfma_f32_16x16x32_bf16 v[96:99], v[190:193], v[206:209], v[96:99]
	v_mfma_f32_16x16x32_bf16 v[84:87], v[144:147], v[214:217], v[84:87]
	v_mfma_f32_16x16x32_bf16 v[80:83], v[190:193], v[214:217], v[80:83]
	v_mfma_f32_16x16x32_bf16 v[68:71], v[144:147], v[222:225], v[68:71]
	v_mfma_f32_16x16x32_bf16 v[64:67], v[190:193], v[222:225], v[64:67]
	v_mfma_f32_16x16x32_bf16 v[116:119], v[174:177], v[202:205], v[116:119]
	v_mfma_f32_16x16x32_bf16 v[112:115], v[194:197], v[202:205], v[112:115]
	v_mfma_f32_16x16x32_bf16 v[100:103], v[174:177], v[210:213], v[100:103]
	v_mfma_f32_16x16x32_bf16 v[96:99], v[194:197], v[210:213], v[96:99]
	v_mfma_f32_16x16x32_bf16 v[84:87], v[174:177], v[218:221], v[84:87]
	v_mfma_f32_16x16x32_bf16 v[80:83], v[194:197], v[218:221], v[80:83]
	v_mfma_f32_16x16x32_bf16 v[68:71], v[174:177], v[226:229], v[68:71]
	v_mfma_f32_16x16x32_bf16 v[64:67], v[194:197], v[226:229], v[64:67]
	s_barrier
	s_add_i32 s56, s94, s44
	v_lshl_add_u64 v[230:231], s[38:39], 0, v[150:151]
	s_mov_b32 m0, s56
	ds_read_b128 v[198:201], v184 offset:16384
	ds_read_b128 v[202:205], v184 offset:17408
	ds_read_b128 v[206:209], v184 offset:18432
	ds_read_b128 v[210:213], v184 offset:19456
	ds_read_b128 v[214:217], v184 offset:20480
	ds_read_b128 v[218:221], v184 offset:21504
	ds_read_b128 v[222:225], v184 offset:22528
	ds_read_b128 v[226:229], v184 offset:23552
	global_load_lds_dwordx4 v[230:231], off
	s_add_i32 m0, s56, 0x2000
	s_add_u32 s56, s38, 0x80000
	v_lshl_add_u64 v[232:233], s[38:39], 0, v[154:155]
	s_addc_u32 s57, s39, 0
	s_add_i32 s34, s95, s44
	global_load_lds_dwordx4 v[232:233], off
	v_lshl_add_u64 v[234:235], s[56:57], 0, v[150:151]
	s_mov_b32 m0, s34
	v_lshl_add_u64 v[236:237], s[40:41], 0, v[152:153]
	global_load_lds_dwordx4 v[234:235], off
	v_lshl_add_u64 v[234:235], s[56:57], 0, v[154:155]
	s_add_i32 m0, s34, 0x2000
	s_nop 0
	global_load_lds_dwordx4 v[234:235], off
	v_lshl_add_u64 v[234:235], s[40:41], 0, v[148:149]
	s_mov_b32 m0, s45
	s_nop 0
	global_load_lds_dwordx4 v[234:235], off
	s_mov_b32 m0, s46
	s_nop 0
	global_load_lds_dwordx4 v[236:237], off
	s_waitcnt vmcnt(8)
	s_waitcnt lgkmcnt(0)
	s_barrier
	s_waitcnt lgkmcnt(0)
	v_mfma_f32_16x16x32_bf16 v[60:63], v[128:131], v[198:201], v[60:63]
	v_mfma_f32_16x16x32_bf16 v[56:59], v[136:139], v[198:201], v[56:59]
	v_mfma_f32_16x16x32_bf16 v[44:47], v[128:131], v[206:209], v[44:47]
	v_mfma_f32_16x16x32_bf16 v[40:43], v[136:139], v[206:209], v[40:43]
	v_mfma_f32_16x16x32_bf16 v[28:31], v[128:131], v[214:217], v[28:31]
	v_mfma_f32_16x16x32_bf16 v[24:27], v[136:139], v[214:217], v[24:27]
	v_mfma_f32_16x16x32_bf16 v[12:15], v[128:131], v[222:225], v[12:15]
	v_mfma_f32_16x16x32_bf16 v[8:11], v[136:139], v[222:225], v[8:11]
	v_mfma_f32_16x16x32_bf16 v[60:63], v[132:135], v[202:205], v[60:63]
	v_mfma_f32_16x16x32_bf16 v[56:59], v[140:143], v[202:205], v[56:59]
	v_mfma_f32_16x16x32_bf16 v[44:47], v[132:135], v[210:213], v[44:47]
	v_mfma_f32_16x16x32_bf16 v[40:43], v[140:143], v[210:213], v[40:43]
	v_mfma_f32_16x16x32_bf16 v[28:31], v[132:135], v[218:221], v[28:31]
	v_mfma_f32_16x16x32_bf16 v[24:27], v[140:143], v[218:221], v[24:27]
	v_mfma_f32_16x16x32_bf16 v[12:15], v[132:135], v[226:229], v[12:15]
	v_mfma_f32_16x16x32_bf16 v[8:11], v[140:143], v[226:229], v[8:11]
	v_mfma_f32_16x16x32_bf16 v[52:55], v[144:147], v[198:201], v[52:55]
	v_mfma_f32_16x16x32_bf16 v[48:51], v[190:193], v[198:201], v[48:51]
	v_mfma_f32_16x16x32_bf16 v[36:39], v[144:147], v[206:209], v[36:39]
	v_mfma_f32_16x16x32_bf16 v[32:35], v[190:193], v[206:209], v[32:35]
	v_mfma_f32_16x16x32_bf16 v[20:23], v[144:147], v[214:217], v[20:23]
	v_mfma_f32_16x16x32_bf16 v[16:19], v[190:193], v[214:217], v[16:19]
	v_mfma_f32_16x16x32_bf16 v[4:7], v[144:147], v[222:225], v[4:7]
	v_mfma_f32_16x16x32_bf16 v[0:3], v[190:193], v[222:225], v[0:3]
	v_mfma_f32_16x16x32_bf16 v[52:55], v[174:177], v[202:205], v[52:55]
	v_mfma_f32_16x16x32_bf16 v[48:51], v[194:197], v[202:205], v[48:51]
	v_mfma_f32_16x16x32_bf16 v[36:39], v[174:177], v[210:213], v[36:39]
	v_mfma_f32_16x16x32_bf16 v[32:35], v[194:197], v[210:213], v[32:35]
	v_mfma_f32_16x16x32_bf16 v[20:23], v[174:177], v[218:221], v[20:23]
	v_mfma_f32_16x16x32_bf16 v[16:19], v[194:197], v[218:221], v[16:19]
	v_mfma_f32_16x16x32_bf16 v[4:7], v[174:177], v[226:229], v[4:7]
	v_mfma_f32_16x16x32_bf16 v[0:3], v[194:197], v[226:229], v[0:3]
	s_barrier
	s_add_i32 s34, 0, 0x18000
	s_add_i32 s35, 0, 0x1c000
	v_add_u32_e32 v140, s34, v180
	v_add_u32_e32 v156, s35, v180
	ds_read_b128 v[128:131], v140
	ds_read_b128 v[132:135], v140 offset:1024
	ds_read_b128 v[136:139], v140 offset:2048
	ds_read_b128 v[140:143], v140 offset:3072
	ds_read_b128 v[144:147], v156
	ds_read_b128 v[174:177], v156 offset:1024
	ds_read_b128 v[190:193], v156 offset:2048
	ds_read_b128 v[194:197], v156 offset:3072
	s_add_u32 s40, s40, 0x80000
	s_addc_u32 s41, s41, 0
	s_mov_b32 m0, s47
	v_lshl_add_u64 v[238:239], s[40:41], 0, v[148:149]
	ds_read_b128 v[198:201], v184 offset:32768
	ds_read_b128 v[202:205], v184 offset:33792
	ds_read_b128 v[206:209], v184 offset:34816
	ds_read_b128 v[210:213], v184 offset:35840
	ds_read_b128 v[214:217], v184 offset:36864
	ds_read_b128 v[218:221], v184 offset:37888
	ds_read_b128 v[222:225], v184 offset:38912
	ds_read_b128 v[226:229], v184 offset:39936
	global_load_lds_dwordx4 v[238:239], off
	v_lshl_add_u64 v[238:239], s[40:41], 0, v[152:153]
	s_mov_b32 m0, s48
	s_nop 0
	global_load_lds_dwordx4 v[238:239], off
	s_waitcnt vmcnt(8)
	s_waitcnt lgkmcnt(0)
	s_barrier
	s_waitcnt lgkmcnt(0)
	v_mfma_f32_16x16x32_bf16 v[124:127], v[128:131], v[198:201], v[124:127]
	v_mfma_f32_16x16x32_bf16 v[120:123], v[136:139], v[198:201], v[120:123]
	v_mfma_f32_16x16x32_bf16 v[108:111], v[128:131], v[206:209], v[108:111]
	v_mfma_f32_16x16x32_bf16 v[104:107], v[136:139], v[206:209], v[104:107]
	v_mfma_f32_16x16x32_bf16 v[92:95], v[128:131], v[214:217], v[92:95]
	v_mfma_f32_16x16x32_bf16 v[88:91], v[136:139], v[214:217], v[88:91]
	v_mfma_f32_16x16x32_bf16 v[76:79], v[128:131], v[222:225], v[76:79]
	v_mfma_f32_16x16x32_bf16 v[72:75], v[136:139], v[222:225], v[72:75]
	v_mfma_f32_16x16x32_bf16 v[124:127], v[132:135], v[202:205], v[124:127]
	v_mfma_f32_16x16x32_bf16 v[120:123], v[140:143], v[202:205], v[120:123]
	v_mfma_f32_16x16x32_bf16 v[108:111], v[132:135], v[210:213], v[108:111]
	v_mfma_f32_16x16x32_bf16 v[104:107], v[140:143], v[210:213], v[104:107]
	v_mfma_f32_16x16x32_bf16 v[92:95], v[132:135], v[218:221], v[92:95]
	v_mfma_f32_16x16x32_bf16 v[88:91], v[140:143], v[218:221], v[88:91]
	v_mfma_f32_16x16x32_bf16 v[76:79], v[132:135], v[226:229], v[76:79]
	v_mfma_f32_16x16x32_bf16 v[72:75], v[140:143], v[226:229], v[72:75]
	v_mfma_f32_16x16x32_bf16 v[116:119], v[144:147], v[198:201], v[116:119]
	v_mfma_f32_16x16x32_bf16 v[112:115], v[190:193], v[198:201], v[112:115]
	v_mfma_f32_16x16x32_bf16 v[100:103], v[144:147], v[206:209], v[100:103]
	v_mfma_f32_16x16x32_bf16 v[96:99], v[190:193], v[206:209], v[96:99]
	v_mfma_f32_16x16x32_bf16 v[84:87], v[144:147], v[214:217], v[84:87]
	v_mfma_f32_16x16x32_bf16 v[80:83], v[190:193], v[214:217], v[80:83]
	v_mfma_f32_16x16x32_bf16 v[68:71], v[144:147], v[222:225], v[68:71]
	v_mfma_f32_16x16x32_bf16 v[64:67], v[190:193], v[222:225], v[64:67]
	v_mfma_f32_16x16x32_bf16 v[116:119], v[174:177], v[202:205], v[116:119]
	v_mfma_f32_16x16x32_bf16 v[112:115], v[194:197], v[202:205], v[112:115]
	v_mfma_f32_16x16x32_bf16 v[100:103], v[174:177], v[210:213], v[100:103]
	v_mfma_f32_16x16x32_bf16 v[96:99], v[194:197], v[210:213], v[96:99]
	v_mfma_f32_16x16x32_bf16 v[84:87], v[174:177], v[218:221], v[84:87]
	v_mfma_f32_16x16x32_bf16 v[80:83], v[194:197], v[218:221], v[80:83]
	v_mfma_f32_16x16x32_bf16 v[68:71], v[174:177], v[226:229], v[68:71]
	v_mfma_f32_16x16x32_bf16 v[64:67], v[194:197], v[226:229], v[64:67]
	s_barrier
	s_add_i32 s34, s34, s44
	v_lshl_add_u64 v[230:231], v[230:231], 0, s[26:27]
	s_mov_b32 m0, s34
	ds_read_b128 v[198:201], v184 offset:49152
	ds_read_b128 v[202:205], v184 offset:50176
	ds_read_b128 v[206:209], v184 offset:51200
	ds_read_b128 v[210:213], v184 offset:52224
	ds_read_b128 v[214:217], v184 offset:53248
	ds_read_b128 v[218:221], v184 offset:54272
	ds_read_b128 v[222:225], v184 offset:55296
	ds_read_b128 v[226:229], v184 offset:56320
	global_load_lds_dwordx4 v[230:231], off
	s_add_i32 m0, s34, 0x2000
	s_add_u32 s38, s38, 0x80080
	v_lshl_add_u64 v[230:231], v[232:233], 0, s[26:27]
	s_addc_u32 s39, s39, 0
	s_add_i32 s34, s35, s44
	global_load_lds_dwordx4 v[230:231], off
	v_lshl_add_u64 v[230:231], s[38:39], 0, v[150:151]
	s_mov_b32 m0, s34
	s_nop 0
	global_load_lds_dwordx4 v[230:231], off
	v_lshl_add_u64 v[230:231], s[38:39], 0, v[154:155]
	s_add_i32 m0, s34, 0x2000
	s_nop 0
	global_load_lds_dwordx4 v[230:231], off
	v_lshl_add_u64 v[230:231], v[234:235], 0, s[26:27]
	s_mov_b32 m0, s90
	s_nop 0
	global_load_lds_dwordx4 v[230:231], off
	v_lshl_add_u64 v[230:231], v[236:237], 0, s[26:27]
	s_mov_b32 m0, s91
	s_nop 0
	global_load_lds_dwordx4 v[230:231], off
	s_waitcnt vmcnt(8)
	s_waitcnt lgkmcnt(0)
	s_barrier
	s_waitcnt lgkmcnt(0)
	v_mfma_f32_16x16x32_bf16 v[60:63], v[128:131], v[198:201], v[60:63]
	v_mfma_f32_16x16x32_bf16 v[56:59], v[136:139], v[198:201], v[56:59]
	v_mfma_f32_16x16x32_bf16 v[44:47], v[128:131], v[206:209], v[44:47]
	v_mfma_f32_16x16x32_bf16 v[40:43], v[136:139], v[206:209], v[40:43]
	v_mfma_f32_16x16x32_bf16 v[28:31], v[128:131], v[214:217], v[28:31]
	v_mfma_f32_16x16x32_bf16 v[24:27], v[136:139], v[214:217], v[24:27]
	v_mfma_f32_16x16x32_bf16 v[12:15], v[128:131], v[222:225], v[12:15]
	v_mfma_f32_16x16x32_bf16 v[8:11], v[136:139], v[222:225], v[8:11]
	v_mfma_f32_16x16x32_bf16 v[60:63], v[132:135], v[202:205], v[60:63]
	v_mfma_f32_16x16x32_bf16 v[56:59], v[140:143], v[202:205], v[56:59]
	v_mfma_f32_16x16x32_bf16 v[44:47], v[132:135], v[210:213], v[44:47]
	v_mfma_f32_16x16x32_bf16 v[40:43], v[140:143], v[210:213], v[40:43]
	v_mfma_f32_16x16x32_bf16 v[28:31], v[132:135], v[218:221], v[28:31]
	v_mfma_f32_16x16x32_bf16 v[24:27], v[140:143], v[218:221], v[24:27]
	v_mfma_f32_16x16x32_bf16 v[12:15], v[132:135], v[226:229], v[12:15]
	v_mfma_f32_16x16x32_bf16 v[8:11], v[140:143], v[226:229], v[8:11]
	v_mfma_f32_16x16x32_bf16 v[52:55], v[144:147], v[198:201], v[52:55]
	v_mfma_f32_16x16x32_bf16 v[48:51], v[190:193], v[198:201], v[48:51]
	v_mfma_f32_16x16x32_bf16 v[36:39], v[144:147], v[206:209], v[36:39]
	v_mfma_f32_16x16x32_bf16 v[32:35], v[190:193], v[206:209], v[32:35]
	v_mfma_f32_16x16x32_bf16 v[20:23], v[144:147], v[214:217], v[20:23]
	v_mfma_f32_16x16x32_bf16 v[16:19], v[190:193], v[214:217], v[16:19]
	v_mfma_f32_16x16x32_bf16 v[4:7], v[144:147], v[222:225], v[4:7]
	v_mfma_f32_16x16x32_bf16 v[0:3], v[190:193], v[222:225], v[0:3]
	v_mfma_f32_16x16x32_bf16 v[52:55], v[174:177], v[202:205], v[52:55]
	v_mfma_f32_16x16x32_bf16 v[48:51], v[194:197], v[202:205], v[48:51]
	v_mfma_f32_16x16x32_bf16 v[36:39], v[174:177], v[210:213], v[36:39]
	v_mfma_f32_16x16x32_bf16 v[32:35], v[194:197], v[210:213], v[32:35]
	v_mfma_f32_16x16x32_bf16 v[20:23], v[174:177], v[218:221], v[20:23]
	v_mfma_f32_16x16x32_bf16 v[16:19], v[194:197], v[218:221], v[16:19]
	v_mfma_f32_16x16x32_bf16 v[4:7], v[174:177], v[226:229], v[4:7]
	v_mfma_f32_16x16x32_bf16 v[0:3], v[194:197], v[226:229], v[0:3]
	s_barrier
	s_add_i32 s50, s50, 2
	s_add_u32 s36, s36, 0x100
	s_addc_u32 s37, s37, 0
	s_add_u32 vcc_lo, vcc_lo, 0x100
	s_addc_u32 vcc_hi, vcc_hi, 0
	s_cmp_gt_u32 s50, 29
	s_cbranch_scc0 .LBB0_121
	s_and_b64 vcc, exec, s[28:29]
	s_cbranch_vccz .LBB0_125
	s_barrier
	v_lshl_or_b32 v174, s6, 8, v181
	s_cmp_gt_i32 s6, 35
	s_mov_b64 s[36:37], -1
	s_cbranch_scc1 .LBB0_126

.LBB0_641:
	s_setprio 0
	s_cmp_lt_i32 s18, 3
	s_cselect_b64 s[4:5], -1, 0
	s_and_b64 s[26:27], s[4:5], s[0:1]
	s_andn2_b64 vcc, exec, s[26:27]
	s_cbranch_vccnz .LBB0_787
	s_mov_b32 s32, 0
	s_add_i32 s79, s2, 0x600
	s_mov_b64 exec, -1
	s_add_u32 s28, s22, 0xa6aa000
	s_addc_u32 s29, s23, 0
	s_add_u32 s84, s22, 0x64aa000
	s_addc_u32 s85, s23, 0
	v_mbcnt_lo_u32_b32 v0, -1, 0
	v_mbcnt_hi_u32_b32 v0, -1, v0
	v_or_b32_e32 v1, s24, v0
	v_lshl_add_u32 v2, s2, 9, v1
	s_mov_b32 s86, 0
	v_lshrrev_b32_e32 v3, 5, v2
	v_lshl_or_b32 v3, v3, 1, 1
	v_and_b32_e32 v4, 0x7ff, v3
	v_and_b32_e32 v5, 31, v2
	v_lshlrev_b32_e32 v5, 4, v5
	v_mul_u32_u24_e32 v6, 0x4800, v3
	v_add_u32_e32 v6, v6, v5
	v_lshl_add_u32 v7, v3, 11, v5
	v_mov_b32_e32 v16, v6
	v_mov_b32_e32 v33, 1.0
	v_cmp_le_u32_e32 vcc, 1, v4
	v_mov_b32_e32 v8, 0x4800
	s_nop 0
	v_cndmask_b32_e32 v8, 0, v8, vcc
	v_sub_u32_e32 v17, v6, v8
	v_cndmask_b32_e64 v34, 0, 1.0, vcc
	v_cmp_le_u32_e32 vcc, 2, v4
	v_mov_b32_e32 v8, 0x9000
	s_nop 0
	v_cndmask_b32_e32 v8, 0, v8, vcc
	v_sub_u32_e32 v18, v6, v8
	v_cndmask_b32_e64 v35, 0, 1.0, vcc
	v_cmp_le_u32_e32 vcc, 3, v4
	v_mov_b32_e32 v8, 0xd800
	s_nop 0
	v_cndmask_b32_e32 v8, 0, v8, vcc
	v_sub_u32_e32 v19, v6, v8
	v_cndmask_b32_e64 v36, 0, 1.0, vcc
	v_cmp_le_u32_e32 vcc, 4, v4
	v_mov_b32_e32 v8, 0x12000
	s_nop 0
	v_cndmask_b32_e32 v8, 0, v8, vcc
	v_sub_u32_e32 v20, v6, v8
	v_cndmask_b32_e64 v37, 0, 1.0, vcc
	v_cmp_le_u32_e32 vcc, 5, v4
	v_mov_b32_e32 v8, 0x16800
	s_nop 0
	v_cndmask_b32_e32 v8, 0, v8, vcc
	v_sub_u32_e32 v21, v6, v8
	v_cndmask_b32_e64 v38, 0, 1.0, vcc
	v_cmp_le_u32_e32 vcc, 6, v4
	v_mov_b32_e32 v8, 0x1b000
	s_nop 0
	v_cndmask_b32_e32 v8, 0, v8, vcc
	v_sub_u32_e32 v22, v6, v8
	v_cndmask_b32_e64 v39, 0, 1.0, vcc
	v_cmp_le_u32_e32 vcc, 7, v4
	v_mov_b32_e32 v8, 0x1f800
	s_nop 0
	v_cndmask_b32_e32 v8, 0, v8, vcc
	v_sub_u32_e32 v23, v6, v8
	v_cndmask_b32_e64 v40, 0, 1.0, vcc
	v_cmp_le_u32_e32 vcc, 8, v4
	v_mov_b32_e32 v8, 0x24000
	s_nop 0
	v_cndmask_b32_e32 v8, 0, v8, vcc
	v_sub_u32_e32 v24, v6, v8
	v_cndmask_b32_e64 v41, 0, 1.0, vcc
	v_cmp_le_u32_e32 vcc, 9, v4
	v_mov_b32_e32 v8, 0x28800
	s_nop 0
	v_cndmask_b32_e32 v8, 0, v8, vcc
	v_sub_u32_e32 v25, v6, v8
	v_cndmask_b32_e64 v42, 0, 1.0, vcc
	v_cmp_le_u32_e32 vcc, 10, v4
	v_mov_b32_e32 v8, 0x2d000
	s_nop 0
	v_cndmask_b32_e32 v8, 0, v8, vcc
	v_sub_u32_e32 v26, v6, v8
	v_cndmask_b32_e64 v43, 0, 1.0, vcc
	v_cmp_le_u32_e32 vcc, 11, v4
	v_mov_b32_e32 v8, 0x31800
	s_nop 0
	v_cndmask_b32_e32 v8, 0, v8, vcc
	v_sub_u32_e32 v27, v6, v8
	v_cndmask_b32_e64 v44, 0, 1.0, vcc
	v_cmp_le_u32_e32 vcc, 12, v4
	v_mov_b32_e32 v8, 0x36000
	s_nop 0
	v_cndmask_b32_e32 v8, 0, v8, vcc
	v_sub_u32_e32 v28, v6, v8
	v_cndmask_b32_e64 v45, 0, 1.0, vcc
	v_cmp_le_u32_e32 vcc, 13, v4
	v_mov_b32_e32 v8, 0x3a800
	s_nop 0
	v_cndmask_b32_e32 v8, 0, v8, vcc
	v_sub_u32_e32 v29, v6, v8
	v_cndmask_b32_e64 v46, 0, 1.0, vcc
	v_cmp_le_u32_e32 vcc, 14, v4
	v_mov_b32_e32 v8, 0x3f000
	s_nop 0
	v_cndmask_b32_e32 v8, 0, v8, vcc
	v_sub_u32_e32 v30, v6, v8
	v_cndmask_b32_e64 v47, 0, 1.0, vcc
	v_cmp_le_u32_e32 vcc, 15, v4
	v_mov_b32_e32 v8, 0x43800
	s_nop 0
	v_cndmask_b32_e32 v8, 0, v8, vcc
	v_sub_u32_e32 v31, v6, v8
	v_cndmask_b32_e64 v48, 0, 1.0, vcc
	v_cmp_le_u32_e32 vcc, 16, v4
	v_mov_b32_e32 v8, 0x48000
	s_nop 0
	v_cndmask_b32_e32 v8, 0, v8, vcc
	v_sub_u32_e32 v32, v6, v8
	v_cndmask_b32_e64 v49, 0, 1.0, vcc
	global_load_dwordx4 v[64:67], v16, s[28:29]
	global_load_dwordx4 v[68:71], v17, s[28:29]
	global_load_dwordx4 v[72:75], v18, s[28:29]
	global_load_dwordx4 v[76:79], v16, s[28:29] offset:512
	global_load_dwordx4 v[80:83], v17, s[28:29] offset:512
	global_load_dwordx4 v[84:87], v18, s[28:29] offset:512
	global_load_dwordx4 v[88:91], v19, s[28:29] offset:512
	global_load_dwordx4 v[92:95], v20, s[28:29] offset:512
	global_load_dwordx4 v[96:99], v16, s[28:29] offset:1024
	global_load_dwordx4 v[100:103], v17, s[28:29] offset:1024
	global_load_dwordx4 v[104:107], v18, s[28:29] offset:1024
	global_load_dwordx4 v[108:111], v19, s[28:29] offset:1024
	global_load_dwordx4 v[112:115], v20, s[28:29] offset:1024
	global_load_dwordx4 v[116:119], v21, s[28:29] offset:1024
	global_load_dwordx4 v[120:123], v22, s[28:29] offset:1024
	global_load_dwordx4 v[124:127], v23, s[28:29] offset:1024
	global_load_dwordx4 v[128:131], v24, s[28:29] offset:1024
	global_load_dwordx4 v[132:135], v16, s[28:29] offset:1536
	global_load_dwordx4 v[136:139], v17, s[28:29] offset:1536
	global_load_dwordx4 v[140:143], v18, s[28:29] offset:1536
	global_load_dwordx4 v[144:147], v19, s[28:29] offset:1536
	global_load_dwordx4 v[148:151], v20, s[28:29] offset:1536
	global_load_dwordx4 v[152:155], v21, s[28:29] offset:1536
	global_load_dwordx4 v[156:159], v22, s[28:29] offset:1536
	global_load_dwordx4 v[160:163], v23, s[28:29] offset:1536
	global_load_dwordx4 v[164:167], v24, s[28:29] offset:1536
	global_load_dwordx4 v[168:171], v25, s[28:29] offset:1536
	global_load_dwordx4 v[172:175], v26, s[28:29] offset:1536
	global_load_dwordx4 v[176:179], v27, s[28:29] offset:1536
	global_load_dwordx4 v[180:183], v28, s[28:29] offset:1536
	global_load_dwordx4 v[184:187], v29, s[28:29] offset:1536
	global_load_dwordx4 v[188:191], v30, s[28:29] offset:1536
	global_load_dwordx4 v[192:195], v31, s[28:29] offset:1536
	global_load_dwordx4 v[196:199], v32, s[28:29] offset:1536
	v_add_u32_e32 v9, 1, v4
	v_min_u32_e32 v10, 2, v9
	v_cvt_f32_u32_e32 v11, v10
	v_div_scale_f32 v200, s[88:89], v11, v11, 1.0
	v_rcp_f32_e32 v201, v200
	v_div_scale_f32 v202, vcc, 1.0, v11, 1.0
	v_fma_f32 v203, -v200, v201, 1.0
	v_fmac_f32_e32 v201, v203, v201
	v_mul_f32_e32 v203, v202, v201
	v_fma_f32 v204, -v200, v203, v202
	v_fmac_f32_e32 v203, v204, v201
	v_fma_f32 v200, -v200, v203, v202
	v_div_fmas_f32 v200, v200, v201, v203
	v_div_fixup_f32 v50, v200, v11, 1.0
	v_min_u32_e32 v10, 2, v4
	v_cvt_f32_u32_e32 v11, v10
	v_div_scale_f32 v200, s[88:89], v11, v11, 1.0
	v_rcp_f32_e32 v201, v200
	v_div_scale_f32 v202, vcc, 1.0, v11, 1.0
	v_fma_f32 v203, -v200, v201, 1.0
	v_fmac_f32_e32 v201, v203, v201
	v_mul_f32_e32 v203, v202, v201
	v_fma_f32 v204, -v200, v203, v202
	v_fmac_f32_e32 v203, v204, v201
	v_fma_f32 v200, -v200, v203, v202
	v_div_fmas_f32 v200, v200, v201, v203
	v_div_fixup_f32 v54, v200, v11, 1.0
	v_min_u32_e32 v10, 4, v9
	v_cvt_f32_u32_e32 v11, v10
	v_div_scale_f32 v200, s[88:89], v11, v11, 1.0
	v_rcp_f32_e32 v201, v200
	v_div_scale_f32 v202, vcc, 1.0, v11, 1.0
	v_fma_f32 v203, -v200, v201, 1.0
	v_fmac_f32_e32 v201, v203, v201
	v_mul_f32_e32 v203, v202, v201
	v_fma_f32 v204, -v200, v203, v202
	v_fmac_f32_e32 v203, v204, v201
	v_fma_f32 v200, -v200, v203, v202
	v_div_fmas_f32 v200, v200, v201, v203
	v_div_fixup_f32 v51, v200, v11, 1.0
	v_min_u32_e32 v10, 4, v4
	v_cvt_f32_u32_e32 v11, v10
	v_div_scale_f32 v200, s[88:89], v11, v11, 1.0
	v_rcp_f32_e32 v201, v200
	v_div_scale_f32 v202, vcc, 1.0, v11, 1.0
	v_fma_f32 v203, -v200, v201, 1.0
	v_fmac_f32_e32 v201, v203, v201
	v_mul_f32_e32 v203, v202, v201
	v_fma_f32 v204, -v200, v203, v202
	v_fmac_f32_e32 v203, v204, v201
	v_fma_f32 v200, -v200, v203, v202
	v_div_fmas_f32 v200, v200, v201, v203
	v_div_fixup_f32 v55, v200, v11, 1.0
	v_min_u32_e32 v10, 8, v9
	v_cvt_f32_u32_e32 v11, v10
	v_div_scale_f32 v200, s[88:89], v11, v11, 1.0
	v_rcp_f32_e32 v201, v200
	v_div_scale_f32 v202, vcc, 1.0, v11, 1.0
	v_fma_f32 v203, -v200, v201, 1.0
	v_fmac_f32_e32 v201, v203, v201
	v_mul_f32_e32 v203, v202, v201
	v_fma_f32 v204, -v200, v203, v202
	v_fmac_f32_e32 v203, v204, v201
	v_fma_f32 v200, -v200, v203, v202
	v_div_fmas_f32 v200, v200, v201, v203
	v_div_fixup_f32 v52, v200, v11, 1.0
	v_min_u32_e32 v10, 8, v4
	v_cvt_f32_u32_e32 v11, v10
	v_div_scale_f32 v200, s[88:89], v11, v11, 1.0
	v_rcp_f32_e32 v201, v200
	v_div_scale_f32 v202, vcc, 1.0, v11, 1.0
	v_fma_f32 v203, -v200, v201, 1.0
	v_fmac_f32_e32 v201, v203, v201
	v_mul_f32_e32 v203, v202, v201
	v_fma_f32 v204, -v200, v203, v202
	v_fmac_f32_e32 v203, v204, v201
	v_fma_f32 v200, -v200, v203, v202
	v_div_fmas_f32 v200, v200, v201, v203
	v_div_fixup_f32 v56, v200, v11, 1.0
	v_min_u32_e32 v10, 16, v9
	v_cvt_f32_u32_e32 v11, v10
	v_div_scale_f32 v200, s[88:89], v11, v11, 1.0
	v_rcp_f32_e32 v201, v200
	v_div_scale_f32 v202, vcc, 1.0, v11, 1.0
	v_fma_f32 v203, -v200, v201, 1.0
	v_fmac_f32_e32 v201, v203, v201
	v_mul_f32_e32 v203, v202, v201
	v_fma_f32 v204, -v200, v203, v202
	v_fmac_f32_e32 v203, v204, v201
	v_fma_f32 v200, -v200, v203, v202
	v_div_fmas_f32 v200, v200, v201, v203
	v_div_fixup_f32 v53, v200, v11, 1.0
	v_min_u32_e32 v10, 16, v4
	v_cvt_f32_u32_e32 v11, v10
	v_div_scale_f32 v200, s[88:89], v11, v11, 1.0
	v_rcp_f32_e32 v201, v200
	v_div_scale_f32 v202, vcc, 1.0, v11, 1.0
	v_fma_f32 v203, -v200, v201, 1.0
	v_fmac_f32_e32 v201, v203, v201
	v_mul_f32_e32 v203, v202, v201
	v_fma_f32 v204, -v200, v203, v202
	v_fmac_f32_e32 v203, v204, v201
	v_fma_f32 v200, -v200, v203, v202
	v_div_fmas_f32 v200, v200, v201, v203
	v_div_fixup_f32 v57, v200, v11, 1.0
	s_waitcnt vmcnt(31)
	v_lshlrev_b32_e32 v206, 16, v64
	v_and_b32_e32 v207, 0xffff0000, v64
	v_lshlrev_b32_e32 v208, 16, v65
	v_and_b32_e32 v209, 0xffff0000, v65
	v_lshlrev_b32_e32 v210, 16, v66
	v_and_b32_e32 v211, 0xffff0000, v66
	v_lshlrev_b32_e32 v212, 16, v67
	v_and_b32_e32 v213, 0xffff0000, v67
	v_lshlrev_b32_e32 v214, 16, v68
	v_and_b32_e32 v215, 0xffff0000, v68
	v_lshlrev_b32_e32 v216, 16, v69
	v_and_b32_e32 v217, 0xffff0000, v69
	v_lshlrev_b32_e32 v218, 16, v70
	v_and_b32_e32 v219, 0xffff0000, v70
	v_lshlrev_b32_e32 v220, 16, v71
	v_and_b32_e32 v221, 0xffff0000, v71
	v_mov_b32_e32 v222, v206
	v_mov_b32_e32 v230, v214
	v_mov_b32_e32 v223, v207
	v_mov_b32_e32 v231, v215
	v_mov_b32_e32 v224, v208
	v_mov_b32_e32 v232, v216
	v_mov_b32_e32 v225, v209
	v_mov_b32_e32 v233, v217
	v_mov_b32_e32 v226, v210
	v_mov_b32_e32 v234, v218
	v_mov_b32_e32 v227, v211
	v_mov_b32_e32 v235, v219
	v_mov_b32_e32 v228, v212
	v_mov_b32_e32 v236, v220
	v_mov_b32_e32 v229, v213
	v_mov_b32_e32 v237, v221
	v_fmac_f32_e32 v222, v214, v34
	v_fmac_f32_e32 v223, v215, v34
	v_fmac_f32_e32 v224, v216, v34
	v_fmac_f32_e32 v225, v217, v34
	v_fmac_f32_e32 v226, v218, v34
	v_fmac_f32_e32 v227, v219, v34
	v_fmac_f32_e32 v228, v220, v34
	v_fmac_f32_e32 v229, v221, v34
	v_lshlrev_b32_e32 v238, 16, v72
	v_and_b32_e32 v239, 0xffff0000, v72
	v_lshlrev_b32_e32 v240, 16, v73
	v_and_b32_e32 v241, 0xffff0000, v73
	v_lshlrev_b32_e32 v242, 16, v74
	v_and_b32_e32 v243, 0xffff0000, v74
	v_lshlrev_b32_e32 v244, 16, v75
	v_and_b32_e32 v245, 0xffff0000, v75
	v_fmac_f32_e32 v230, v238, v35
	v_fmac_f32_e32 v231, v239, v35
	v_fmac_f32_e32 v232, v240, v35
	v_fmac_f32_e32 v233, v241, v35
	v_fmac_f32_e32 v234, v242, v35
	v_fmac_f32_e32 v235, v243, v35
	v_fmac_f32_e32 v236, v244, v35
	v_fmac_f32_e32 v237, v245, v35
	v_fma_f32 v222, v222, v50, -v206
	v_fma_f32 v230, v230, v54, -v214
	v_fma_f32 v223, v223, v50, -v207
	v_fma_f32 v231, v231, v54, -v215
	v_fma_f32 v224, v224, v50, -v208
	v_fma_f32 v232, v232, v54, -v216
	v_fma_f32 v225, v225, v50, -v209
	v_fma_f32 v233, v233, v54, -v217
	v_fma_f32 v226, v226, v50, -v210
	v_fma_f32 v234, v234, v54, -v218
	v_fma_f32 v227, v227, v50, -v211
	v_fma_f32 v235, v235, v54, -v219
	v_fma_f32 v228, v228, v50, -v212
	v_fma_f32 v236, v236, v54, -v220
	v_fma_f32 v229, v229, v50, -v213
	v_fma_f32 v237, v237, v54, -v221
	v_cvt_pk_bf16_f32 v246, v222, v223
	v_cvt_pk_bf16_f32 v247, v224, v225
	v_cvt_pk_bf16_f32 v248, v226, v227
	v_cvt_pk_bf16_f32 v249, v228, v229
	global_store_dwordx4 v7, v[246:249], s[84:85]
	s_nop 1
	v_cvt_pk_bf16_f32 v250, v230, v231
	v_cvt_pk_bf16_f32 v251, v232, v233
	v_cvt_pk_bf16_f32 v252, v234, v235
	v_cvt_pk_bf16_f32 v253, v236, v237
	global_store_dwordx4 v7, v[250:253], s[84:85] offset:-2048
	s_nop 1
	s_waitcnt vmcnt(28)
	v_lshlrev_b32_e32 v206, 16, v76
	v_and_b32_e32 v207, 0xffff0000, v76
	v_lshlrev_b32_e32 v208, 16, v77
	v_and_b32_e32 v209, 0xffff0000, v77
	v_lshlrev_b32_e32 v210, 16, v78
	v_and_b32_e32 v211, 0xffff0000, v78
	v_lshlrev_b32_e32 v212, 16, v79
	v_and_b32_e32 v213, 0xffff0000, v79
	v_lshlrev_b32_e32 v214, 16, v80
	v_and_b32_e32 v215, 0xffff0000, v80
	v_lshlrev_b32_e32 v216, 16, v81
	v_and_b32_e32 v217, 0xffff0000, v81
	v_lshlrev_b32_e32 v218, 16, v82
	v_and_b32_e32 v219, 0xffff0000, v82
	v_lshlrev_b32_e32 v220, 16, v83
	v_and_b32_e32 v221, 0xffff0000, v83
	v_mov_b32_e32 v222, v206
	v_mov_b32_e32 v230, v214
	v_mov_b32_e32 v223, v207
	v_mov_b32_e32 v231, v215
	v_mov_b32_e32 v224, v208
	v_mov_b32_e32 v232, v216
	v_mov_b32_e32 v225, v209
	v_mov_b32_e32 v233, v217
	v_mov_b32_e32 v226, v210
	v_mov_b32_e32 v234, v218
	v_mov_b32_e32 v227, v211
	v_mov_b32_e32 v235, v219
	v_mov_b32_e32 v228, v212
	v_mov_b32_e32 v236, v220
	v_mov_b32_e32 v229, v213
	v_mov_b32_e32 v237, v221
	v_fmac_f32_e32 v222, v214, v34
	v_fmac_f32_e32 v223, v215, v34
	v_fmac_f32_e32 v224, v216, v34
	v_fmac_f32_e32 v225, v217, v34
	v_fmac_f32_e32 v226, v218, v34
	v_fmac_f32_e32 v227, v219, v34
	v_fmac_f32_e32 v228, v220, v34
	v_fmac_f32_e32 v229, v221, v34
	v_lshlrev_b32_e32 v238, 16, v84
	v_and_b32_e32 v239, 0xffff0000, v84
	v_lshlrev_b32_e32 v240, 16, v85
	v_and_b32_e32 v241, 0xffff0000, v85
	v_lshlrev_b32_e32 v242, 16, v86
	v_and_b32_e32 v243, 0xffff0000, v86
	v_lshlrev_b32_e32 v244, 16, v87
	v_and_b32_e32 v245, 0xffff0000, v87
	v_fmac_f32_e32 v222, v238, v35
	v_fmac_f32_e32 v230, v238, v35
	v_fmac_f32_e32 v223, v239, v35
	v_fmac_f32_e32 v231, v239, v35
	v_fmac_f32_e32 v224, v240, v35
	v_fmac_f32_e32 v232, v240, v35
	v_fmac_f32_e32 v225, v241, v35
	v_fmac_f32_e32 v233, v241, v35
	v_fmac_f32_e32 v226, v242, v35
	v_fmac_f32_e32 v234, v242, v35
	v_fmac_f32_e32 v227, v243, v35
	v_fmac_f32_e32 v235, v243, v35
	v_fmac_f32_e32 v228, v244, v35
	v_fmac_f32_e32 v236, v244, v35
	v_fmac_f32_e32 v229, v245, v35
	v_fmac_f32_e32 v237, v245, v35
	v_lshlrev_b32_e32 v238, 16, v88
	v_and_b32_e32 v239, 0xffff0000, v88
	v_lshlrev_b32_e32 v240, 16, v89
	v_and_b32_e32 v241, 0xffff0000, v89
	v_lshlrev_b32_e32 v242, 16, v90
	v_and_b32_e32 v243, 0xffff0000, v90
	v_lshlrev_b32_e32 v244, 16, v91
	v_and_b32_e32 v245, 0xffff0000, v91
	v_fmac_f32_e32 v222, v238, v36
	v_fmac_f32_e32 v230, v238, v36
	v_fmac_f32_e32 v223, v239, v36
	v_fmac_f32_e32 v231, v239, v36
	v_fmac_f32_e32 v224, v240, v36
	v_fmac_f32_e32 v232, v240, v36
	v_fmac_f32_e32 v225, v241, v36
	v_fmac_f32_e32 v233, v241, v36
	v_fmac_f32_e32 v226, v242, v36
	v_fmac_f32_e32 v234, v242, v36
	v_fmac_f32_e32 v227, v243, v36
	v_fmac_f32_e32 v235, v243, v36
	v_fmac_f32_e32 v228, v244, v36
	v_fmac_f32_e32 v236, v244, v36
	v_fmac_f32_e32 v229, v245, v36
	v_fmac_f32_e32 v237, v245, v36
	v_lshlrev_b32_e32 v238, 16, v92
	v_and_b32_e32 v239, 0xffff0000, v92
	v_lshlrev_b32_e32 v240, 16, v93
	v_and_b32_e32 v241, 0xffff0000, v93
	v_lshlrev_b32_e32 v242, 16, v94
	v_and_b32_e32 v243, 0xffff0000, v94
	v_lshlrev_b32_e32 v244, 16, v95
	v_and_b32_e32 v245, 0xffff0000, v95
	v_fmac_f32_e32 v230, v238, v37
	v_fmac_f32_e32 v231, v239, v37
	v_fmac_f32_e32 v232, v240, v37
	v_fmac_f32_e32 v233, v241, v37
	v_fmac_f32_e32 v234, v242, v37
	v_fmac_f32_e32 v235, v243, v37
	v_fmac_f32_e32 v236, v244, v37
	v_fmac_f32_e32 v237, v245, v37
	v_fma_f32 v222, v222, v51, -v206
	v_fma_f32 v230, v230, v55, -v214
	v_fma_f32 v223, v223, v51, -v207
	v_fma_f32 v231, v231, v55, -v215
	v_fma_f32 v224, v224, v51, -v208
	v_fma_f32 v232, v232, v55, -v216
	v_fma_f32 v225, v225, v51, -v209
	v_fma_f32 v233, v233, v55, -v217
	v_fma_f32 v226, v226, v51, -v210
	v_fma_f32 v234, v234, v55, -v218
	v_fma_f32 v227, v227, v51, -v211
	v_fma_f32 v235, v235, v55, -v219
	v_fma_f32 v228, v228, v51, -v212
	v_fma_f32 v236, v236, v55, -v220
	v_fma_f32 v229, v229, v51, -v213
	v_fma_f32 v237, v237, v55, -v221
	v_cvt_pk_bf16_f32 v246, v222, v223
	v_cvt_pk_bf16_f32 v247, v224, v225
	v_cvt_pk_bf16_f32 v248, v226, v227
	v_cvt_pk_bf16_f32 v249, v228, v229
	global_store_dwordx4 v7, v[246:249], s[84:85] offset:512
	s_nop 1
	v_cvt_pk_bf16_f32 v250, v230, v231
	v_cvt_pk_bf16_f32 v251, v232, v233
	v_cvt_pk_bf16_f32 v252, v234, v235
	v_cvt_pk_bf16_f32 v253, v236, v237
	global_store_dwordx4 v7, v[250:253], s[84:85] offset:-1536
	s_nop 1
	s_waitcnt vmcnt(21)
	v_lshlrev_b32_e32 v206, 16, v96
	v_and_b32_e32 v207, 0xffff0000, v96
	v_lshlrev_b32_e32 v208, 16, v97
	v_and_b32_e32 v209, 0xffff0000, v97
	v_lshlrev_b32_e32 v210, 16, v98
	v_and_b32_e32 v211, 0xffff0000, v98
	v_lshlrev_b32_e32 v212, 16, v99
	v_and_b32_e32 v213, 0xffff0000, v99
	v_lshlrev_b32_e32 v214, 16, v100
	v_and_b32_e32 v215, 0xffff0000, v100
	v_lshlrev_b32_e32 v216, 16, v101
	v_and_b32_e32 v217, 0xffff0000, v101
	v_lshlrev_b32_e32 v218, 16, v102
	v_and_b32_e32 v219, 0xffff0000, v102
	v_lshlrev_b32_e32 v220, 16, v103
	v_and_b32_e32 v221, 0xffff0000, v103
	v_mov_b32_e32 v222, v206
	v_mov_b32_e32 v230, v214
	v_mov_b32_e32 v223, v207
	v_mov_b32_e32 v231, v215
	v_mov_b32_e32 v224, v208
	v_mov_b32_e32 v232, v216
	v_mov_b32_e32 v225, v209
	v_mov_b32_e32 v233, v217
	v_mov_b32_e32 v226, v210
	v_mov_b32_e32 v234, v218
	v_mov_b32_e32 v227, v211
	v_mov_b32_e32 v235, v219
	v_mov_b32_e32 v228, v212
	v_mov_b32_e32 v236, v220
	v_mov_b32_e32 v229, v213
	v_mov_b32_e32 v237, v221
	v_fmac_f32_e32 v222, v214, v34
	v_fmac_f32_e32 v223, v215, v34
	v_fmac_f32_e32 v224, v216, v34
	v_fmac_f32_e32 v225, v217, v34
	v_fmac_f32_e32 v226, v218, v34
	v_fmac_f32_e32 v227, v219, v34
	v_fmac_f32_e32 v228, v220, v34
	v_fmac_f32_e32 v229, v221, v34
	v_lshlrev_b32_e32 v238, 16, v104
	v_and_b32_e32 v239, 0xffff0000, v104
	v_lshlrev_b32_e32 v240, 16, v105
	v_and_b32_e32 v241, 0xffff0000, v105
	v_lshlrev_b32_e32 v242, 16, v106
	v_and_b32_e32 v243, 0xffff0000, v106
	v_lshlrev_b32_e32 v244, 16, v107
	v_and_b32_e32 v245, 0xffff0000, v107
	v_fmac_f32_e32 v222, v238, v35
	v_fmac_f32_e32 v230, v238, v35
	v_fmac_f32_e32 v223, v239, v35
	v_fmac_f32_e32 v231, v239, v35
	v_fmac_f32_e32 v224, v240, v35
	v_fmac_f32_e32 v232, v240, v35
	v_fmac_f32_e32 v225, v241, v35
	v_fmac_f32_e32 v233, v241, v35
	v_fmac_f32_e32 v226, v242, v35
	v_fmac_f32_e32 v234, v242, v35
	v_fmac_f32_e32 v227, v243, v35
	v_fmac_f32_e32 v235, v243, v35
	v_fmac_f32_e32 v228, v244, v35
	v_fmac_f32_e32 v236, v244, v35
	v_fmac_f32_e32 v229, v245, v35
	v_fmac_f32_e32 v237, v245, v35
	v_lshlrev_b32_e32 v238, 16, v108
	v_and_b32_e32 v239, 0xffff0000, v108
	v_lshlrev_b32_e32 v240, 16, v109
	v_and_b32_e32 v241, 0xffff0000, v109
	v_lshlrev_b32_e32 v242, 16, v110
	v_and_b32_e32 v243, 0xffff0000, v110
	v_lshlrev_b32_e32 v244, 16, v111
	v_and_b32_e32 v245, 0xffff0000, v111
	v_fmac_f32_e32 v222, v238, v36
	v_fmac_f32_e32 v230, v238, v36
	v_fmac_f32_e32 v223, v239, v36
	v_fmac_f32_e32 v231, v239, v36
	v_fmac_f32_e32 v224, v240, v36
	v_fmac_f32_e32 v232, v240, v36
	v_fmac_f32_e32 v225, v241, v36
	v_fmac_f32_e32 v233, v241, v36
	v_fmac_f32_e32 v226, v242, v36
	v_fmac_f32_e32 v234, v242, v36
	v_fmac_f32_e32 v227, v243, v36
	v_fmac_f32_e32 v235, v243, v36
	v_fmac_f32_e32 v228, v244, v36
	v_fmac_f32_e32 v236, v244, v36
	v_fmac_f32_e32 v229, v245, v36
	v_fmac_f32_e32 v237, v245, v36
	v_lshlrev_b32_e32 v238, 16, v112
	v_and_b32_e32 v239, 0xffff0000, v112
	v_lshlrev_b32_e32 v240, 16, v113
	v_and_b32_e32 v241, 0xffff0000, v113
	v_lshlrev_b32_e32 v242, 16, v114
	v_and_b32_e32 v243, 0xffff0000, v114
	v_lshlrev_b32_e32 v244, 16, v115
	v_and_b32_e32 v245, 0xffff0000, v115
	v_fmac_f32_e32 v222, v238, v37
	v_fmac_f32_e32 v230, v238, v37
	v_fmac_f32_e32 v223, v239, v37
	v_fmac_f32_e32 v231, v239, v37
	v_fmac_f32_e32 v224, v240, v37
	v_fmac_f32_e32 v232, v240, v37
	v_fmac_f32_e32 v225, v241, v37
	v_fmac_f32_e32 v233, v241, v37
	v_fmac_f32_e32 v226, v242, v37
	v_fmac_f32_e32 v234, v242, v37
	v_fmac_f32_e32 v227, v243, v37
	v_fmac_f32_e32 v235, v243, v37
	v_fmac_f32_e32 v228, v244, v37
	v_fmac_f32_e32 v236, v244, v37
	v_fmac_f32_e32 v229, v245, v37
	v_fmac_f32_e32 v237, v245, v37
	v_lshlrev_b32_e32 v238, 16, v116
	v_and_b32_e32 v239, 0xffff0000, v116
	v_lshlrev_b32_e32 v240, 16, v117
	v_and_b32_e32 v241, 0xffff0000, v117
	v_lshlrev_b32_e32 v242, 16, v118
	v_and_b32_e32 v243, 0xffff0000, v118
	v_lshlrev_b32_e32 v244, 16, v119
	v_and_b32_e32 v245, 0xffff0000, v119
	v_fmac_f32_e32 v222, v238, v38
	v_fmac_f32_e32 v230, v238, v38
	v_fmac_f32_e32 v223, v239, v38
	v_fmac_f32_e32 v231, v239, v38
	v_fmac_f32_e32 v224, v240, v38
	v_fmac_f32_e32 v232, v240, v38
	v_fmac_f32_e32 v225, v241, v38
	v_fmac_f32_e32 v233, v241, v38
	v_fmac_f32_e32 v226, v242, v38
	v_fmac_f32_e32 v234, v242, v38
	v_fmac_f32_e32 v227, v243, v38
	v_fmac_f32_e32 v235, v243, v38
	v_fmac_f32_e32 v228, v244, v38
	v_fmac_f32_e32 v236, v244, v38
	v_fmac_f32_e32 v229, v245, v38
	v_fmac_f32_e32 v237, v245, v38
	v_lshlrev_b32_e32 v238, 16, v120
	v_and_b32_e32 v239, 0xffff0000, v120
	v_lshlrev_b32_e32 v240, 16, v121
	v_and_b32_e32 v241, 0xffff0000, v121
	v_lshlrev_b32_e32 v242, 16, v122
	v_and_b32_e32 v243, 0xffff0000, v122
	v_lshlrev_b32_e32 v244, 16, v123
	v_and_b32_e32 v245, 0xffff0000, v123
	v_fmac_f32_e32 v222, v238, v39
	v_fmac_f32_e32 v230, v238, v39
	v_fmac_f32_e32 v223, v239, v39
	v_fmac_f32_e32 v231, v239, v39
	v_fmac_f32_e32 v224, v240, v39
	v_fmac_f32_e32 v232, v240, v39
	v_fmac_f32_e32 v225, v241, v39
	v_fmac_f32_e32 v233, v241, v39
	v_fmac_f32_e32 v226, v242, v39
	v_fmac_f32_e32 v234, v242, v39
	v_fmac_f32_e32 v227, v243, v39
	v_fmac_f32_e32 v235, v243, v39
	v_fmac_f32_e32 v228, v244, v39
	v_fmac_f32_e32 v236, v244, v39
	v_fmac_f32_e32 v229, v245, v39
	v_fmac_f32_e32 v237, v245, v39
	v_lshlrev_b32_e32 v238, 16, v124
	v_and_b32_e32 v239, 0xffff0000, v124
	v_lshlrev_b32_e32 v240, 16, v125
	v_and_b32_e32 v241, 0xffff0000, v125
	v_lshlrev_b32_e32 v242, 16, v126
	v_and_b32_e32 v243, 0xffff0000, v126
	v_lshlrev_b32_e32 v244, 16, v127
	v_and_b32_e32 v245, 0xffff0000, v127
	v_fmac_f32_e32 v222, v238, v40
	v_fmac_f32_e32 v230, v238, v40
	v_fmac_f32_e32 v223, v239, v40
	v_fmac_f32_e32 v231, v239, v40
	v_fmac_f32_e32 v224, v240, v40
	v_fmac_f32_e32 v232, v240, v40
	v_fmac_f32_e32 v225, v241, v40
	v_fmac_f32_e32 v233, v241, v40
	v_fmac_f32_e32 v226, v242, v40
	v_fmac_f32_e32 v234, v242, v40
	v_fmac_f32_e32 v227, v243, v40
	v_fmac_f32_e32 v235, v243, v40
	v_fmac_f32_e32 v228, v244, v40
	v_fmac_f32_e32 v236, v244, v40
	v_fmac_f32_e32 v229, v245, v40
	v_fmac_f32_e32 v237, v245, v40
	v_lshlrev_b32_e32 v238, 16, v128
	v_and_b32_e32 v239, 0xffff0000, v128
	v_lshlrev_b32_e32 v240, 16, v129
	v_and_b32_e32 v241, 0xffff0000, v129
	v_lshlrev_b32_e32 v242, 16, v130
	v_and_b32_e32 v243, 0xffff0000, v130
	v_lshlrev_b32_e32 v244, 16, v131
	v_and_b32_e32 v245, 0xffff0000, v131
	v_fmac_f32_e32 v230, v238, v41
	v_fmac_f32_e32 v231, v239, v41
	v_fmac_f32_e32 v232, v240, v41
	v_fmac_f32_e32 v233, v241, v41
	v_fmac_f32_e32 v234, v242, v41
	v_fmac_f32_e32 v235, v243, v41
	v_fmac_f32_e32 v236, v244, v41
	v_fmac_f32_e32 v237, v245, v41
	v_fma_f32 v222, v222, v52, -v206
	v_fma_f32 v230, v230, v56, -v214
	v_fma_f32 v223, v223, v52, -v207
	v_fma_f32 v231, v231, v56, -v215
	v_fma_f32 v224, v224, v52, -v208
	v_fma_f32 v232, v232, v56, -v216
	v_fma_f32 v225, v225, v52, -v209
	v_fma_f32 v233, v233, v56, -v217
	v_fma_f32 v226, v226, v52, -v210
	v_fma_f32 v234, v234, v56, -v218
	v_fma_f32 v227, v227, v52, -v211
	v_fma_f32 v235, v235, v56, -v219
	v_fma_f32 v228, v228, v52, -v212
	v_fma_f32 v236, v236, v56, -v220
	v_fma_f32 v229, v229, v52, -v213
	v_fma_f32 v237, v237, v56, -v221
	v_cvt_pk_bf16_f32 v246, v222, v223
	v_cvt_pk_bf16_f32 v247, v224, v225
	v_cvt_pk_bf16_f32 v248, v226, v227
	v_cvt_pk_bf16_f32 v249, v228, v229
	global_store_dwordx4 v7, v[246:249], s[84:85] offset:1024
	s_nop 1
	v_cvt_pk_bf16_f32 v250, v230, v231
	v_cvt_pk_bf16_f32 v251, v232, v233
	v_cvt_pk_bf16_f32 v252, v234, v235
	v_cvt_pk_bf16_f32 v253, v236, v237
	global_store_dwordx4 v7, v[250:253], s[84:85] offset:-1024
	s_nop 1
	s_waitcnt vmcnt(6)
	v_lshlrev_b32_e32 v206, 16, v132
	v_and_b32_e32 v207, 0xffff0000, v132
	v_lshlrev_b32_e32 v208, 16, v133
	v_and_b32_e32 v209, 0xffff0000, v133
	v_lshlrev_b32_e32 v210, 16, v134
	v_and_b32_e32 v211, 0xffff0000, v134
	v_lshlrev_b32_e32 v212, 16, v135
	v_and_b32_e32 v213, 0xffff0000, v135
	v_lshlrev_b32_e32 v214, 16, v136
	v_and_b32_e32 v215, 0xffff0000, v136
	v_lshlrev_b32_e32 v216, 16, v137
	v_and_b32_e32 v217, 0xffff0000, v137
	v_lshlrev_b32_e32 v218, 16, v138
	v_and_b32_e32 v219, 0xffff0000, v138
	v_lshlrev_b32_e32 v220, 16, v139
	v_and_b32_e32 v221, 0xffff0000, v139
	v_mov_b32_e32 v222, v206
	v_mov_b32_e32 v230, v214
	v_mov_b32_e32 v223, v207
	v_mov_b32_e32 v231, v215
	v_mov_b32_e32 v224, v208
	v_mov_b32_e32 v232, v216
	v_mov_b32_e32 v225, v209
	v_mov_b32_e32 v233, v217
	v_mov_b32_e32 v226, v210
	v_mov_b32_e32 v234, v218
	v_mov_b32_e32 v227, v211
	v_mov_b32_e32 v235, v219
	v_mov_b32_e32 v228, v212
	v_mov_b32_e32 v236, v220
	v_mov_b32_e32 v229, v213
	v_mov_b32_e32 v237, v221
	v_fmac_f32_e32 v222, v214, v34
	v_fmac_f32_e32 v223, v215, v34
	v_fmac_f32_e32 v224, v216, v34
	v_fmac_f32_e32 v225, v217, v34
	v_fmac_f32_e32 v226, v218, v34
	v_fmac_f32_e32 v227, v219, v34
	v_fmac_f32_e32 v228, v220, v34
	v_fmac_f32_e32 v229, v221, v34
	v_lshlrev_b32_e32 v238, 16, v140
	v_and_b32_e32 v239, 0xffff0000, v140
	v_lshlrev_b32_e32 v240, 16, v141
	v_and_b32_e32 v241, 0xffff0000, v141
	v_lshlrev_b32_e32 v242, 16, v142
	v_and_b32_e32 v243, 0xffff0000, v142
	v_lshlrev_b32_e32 v244, 16, v143
	v_and_b32_e32 v245, 0xffff0000, v143
	v_fmac_f32_e32 v222, v238, v35
	v_fmac_f32_e32 v230, v238, v35
	v_fmac_f32_e32 v223, v239, v35
	v_fmac_f32_e32 v231, v239, v35
	v_fmac_f32_e32 v224, v240, v35
	v_fmac_f32_e32 v232, v240, v35
	v_fmac_f32_e32 v225, v241, v35
	v_fmac_f32_e32 v233, v241, v35
	v_fmac_f32_e32 v226, v242, v35
	v_fmac_f32_e32 v234, v242, v35
	v_fmac_f32_e32 v227, v243, v35
	v_fmac_f32_e32 v235, v243, v35
	v_fmac_f32_e32 v228, v244, v35
	v_fmac_f32_e32 v236, v244, v35
	v_fmac_f32_e32 v229, v245, v35
	v_fmac_f32_e32 v237, v245, v35
	v_lshlrev_b32_e32 v238, 16, v144
	v_and_b32_e32 v239, 0xffff0000, v144
	v_lshlrev_b32_e32 v240, 16, v145
	v_and_b32_e32 v241, 0xffff0000, v145
	v_lshlrev_b32_e32 v242, 16, v146
	v_and_b32_e32 v243, 0xffff0000, v146
	v_lshlrev_b32_e32 v244, 16, v147
	v_and_b32_e32 v245, 0xffff0000, v147
	v_fmac_f32_e32 v222, v238, v36
	v_fmac_f32_e32 v230, v238, v36
	v_fmac_f32_e32 v223, v239, v36
	v_fmac_f32_e32 v231, v239, v36
	v_fmac_f32_e32 v224, v240, v36
	v_fmac_f32_e32 v232, v240, v36
	v_fmac_f32_e32 v225, v241, v36
	v_fmac_f32_e32 v233, v241, v36
	v_fmac_f32_e32 v226, v242, v36
	v_fmac_f32_e32 v234, v242, v36
	v_fmac_f32_e32 v227, v243, v36
	v_fmac_f32_e32 v235, v243, v36
	v_fmac_f32_e32 v228, v244, v36
	v_fmac_f32_e32 v236, v244, v36
	v_fmac_f32_e32 v229, v245, v36
	v_fmac_f32_e32 v237, v245, v36
	v_lshlrev_b32_e32 v238, 16, v148
	v_and_b32_e32 v239, 0xffff0000, v148
	v_lshlrev_b32_e32 v240, 16, v149
	v_and_b32_e32 v241, 0xffff0000, v149
	v_lshlrev_b32_e32 v242, 16, v150
	v_and_b32_e32 v243, 0xffff0000, v150
	v_lshlrev_b32_e32 v244, 16, v151
	v_and_b32_e32 v245, 0xffff0000, v151
	v_fmac_f32_e32 v222, v238, v37
	v_fmac_f32_e32 v230, v238, v37
	v_fmac_f32_e32 v223, v239, v37
	v_fmac_f32_e32 v231, v239, v37
	v_fmac_f32_e32 v224, v240, v37
	v_fmac_f32_e32 v232, v240, v37
	v_fmac_f32_e32 v225, v241, v37
	v_fmac_f32_e32 v233, v241, v37
	v_fmac_f32_e32 v226, v242, v37
	v_fmac_f32_e32 v234, v242, v37
	v_fmac_f32_e32 v227, v243, v37
	v_fmac_f32_e32 v235, v243, v37
	v_fmac_f32_e32 v228, v244, v37
	v_fmac_f32_e32 v236, v244, v37
	v_fmac_f32_e32 v229, v245, v37
	v_fmac_f32_e32 v237, v245, v37
	v_lshlrev_b32_e32 v238, 16, v152
	v_and_b32_e32 v239, 0xffff0000, v152
	v_lshlrev_b32_e32 v240, 16, v153
	v_and_b32_e32 v241, 0xffff0000, v153
	v_lshlrev_b32_e32 v242, 16, v154
	v_and_b32_e32 v243, 0xffff0000, v154
	v_lshlrev_b32_e32 v244, 16, v155
	v_and_b32_e32 v245, 0xffff0000, v155
	v_fmac_f32_e32 v222, v238, v38
	v_fmac_f32_e32 v230, v238, v38
	v_fmac_f32_e32 v223, v239, v38
	v_fmac_f32_e32 v231, v239, v38
	v_fmac_f32_e32 v224, v240, v38
	v_fmac_f32_e32 v232, v240, v38
	v_fmac_f32_e32 v225, v241, v38
	v_fmac_f32_e32 v233, v241, v38
	v_fmac_f32_e32 v226, v242, v38
	v_fmac_f32_e32 v234, v242, v38
	v_fmac_f32_e32 v227, v243, v38
	v_fmac_f32_e32 v235, v243, v38
	v_fmac_f32_e32 v228, v244, v38
	v_fmac_f32_e32 v236, v244, v38
	v_fmac_f32_e32 v229, v245, v38
	v_fmac_f32_e32 v237, v245, v38
	v_lshlrev_b32_e32 v238, 16, v156
	v_and_b32_e32 v239, 0xffff0000, v156
	v_lshlrev_b32_e32 v240, 16, v157
	v_and_b32_e32 v241, 0xffff0000, v157
	v_lshlrev_b32_e32 v242, 16, v158
	v_and_b32_e32 v243, 0xffff0000, v158
	v_lshlrev_b32_e32 v244, 16, v159
	v_and_b32_e32 v245, 0xffff0000, v159
	v_fmac_f32_e32 v222, v238, v39
	v_fmac_f32_e32 v230, v238, v39
	v_fmac_f32_e32 v223, v239, v39
	v_fmac_f32_e32 v231, v239, v39
	v_fmac_f32_e32 v224, v240, v39
	v_fmac_f32_e32 v232, v240, v39
	v_fmac_f32_e32 v225, v241, v39
	v_fmac_f32_e32 v233, v241, v39
	v_fmac_f32_e32 v226, v242, v39
	v_fmac_f32_e32 v234, v242, v39
	v_fmac_f32_e32 v227, v243, v39
	v_fmac_f32_e32 v235, v243, v39
	v_fmac_f32_e32 v228, v244, v39
	v_fmac_f32_e32 v236, v244, v39
	v_fmac_f32_e32 v229, v245, v39
	v_fmac_f32_e32 v237, v245, v39
	v_lshlrev_b32_e32 v238, 16, v160
	v_and_b32_e32 v239, 0xffff0000, v160
	v_lshlrev_b32_e32 v240, 16, v161
	v_and_b32_e32 v241, 0xffff0000, v161
	v_lshlrev_b32_e32 v242, 16, v162
	v_and_b32_e32 v243, 0xffff0000, v162
	v_lshlrev_b32_e32 v244, 16, v163
	v_and_b32_e32 v245, 0xffff0000, v163
	v_fmac_f32_e32 v222, v238, v40
	v_fmac_f32_e32 v230, v238, v40
	v_fmac_f32_e32 v223, v239, v40
	v_fmac_f32_e32 v231, v239, v40
	v_fmac_f32_e32 v224, v240, v40
	v_fmac_f32_e32 v232, v240, v40
	v_fmac_f32_e32 v225, v241, v40
	v_fmac_f32_e32 v233, v241, v40
	v_fmac_f32_e32 v226, v242, v40
	v_fmac_f32_e32 v234, v242, v40
	v_fmac_f32_e32 v227, v243, v40
	v_fmac_f32_e32 v235, v243, v40
	v_fmac_f32_e32 v228, v244, v40
	v_fmac_f32_e32 v236, v244, v40
	v_fmac_f32_e32 v229, v245, v40
	v_fmac_f32_e32 v237, v245, v40
	v_lshlrev_b32_e32 v238, 16, v164
	v_and_b32_e32 v239, 0xffff0000, v164
	v_lshlrev_b32_e32 v240, 16, v165
	v_and_b32_e32 v241, 0xffff0000, v165
	v_lshlrev_b32_e32 v242, 16, v166
	v_and_b32_e32 v243, 0xffff0000, v166
	v_lshlrev_b32_e32 v244, 16, v167
	v_and_b32_e32 v245, 0xffff0000, v167
	v_fmac_f32_e32 v222, v238, v41
	v_fmac_f32_e32 v230, v238, v41
	v_fmac_f32_e32 v223, v239, v41
	v_fmac_f32_e32 v231, v239, v41
	v_fmac_f32_e32 v224, v240, v41
	v_fmac_f32_e32 v232, v240, v41
	v_fmac_f32_e32 v225, v241, v41
	v_fmac_f32_e32 v233, v241, v41
	v_fmac_f32_e32 v226, v242, v41
	v_fmac_f32_e32 v234, v242, v41
	v_fmac_f32_e32 v227, v243, v41
	v_fmac_f32_e32 v235, v243, v41
	v_fmac_f32_e32 v228, v244, v41
	v_fmac_f32_e32 v236, v244, v41
	v_fmac_f32_e32 v229, v245, v41
	v_fmac_f32_e32 v237, v245, v41
	v_lshlrev_b32_e32 v238, 16, v168
	v_and_b32_e32 v239, 0xffff0000, v168
	v_lshlrev_b32_e32 v240, 16, v169
	v_and_b32_e32 v241, 0xffff0000, v169
	v_lshlrev_b32_e32 v242, 16, v170
	v_and_b32_e32 v243, 0xffff0000, v170
	v_lshlrev_b32_e32 v244, 16, v171
	v_and_b32_e32 v245, 0xffff0000, v171
	v_fmac_f32_e32 v222, v238, v42
	v_fmac_f32_e32 v230, v238, v42
	v_fmac_f32_e32 v223, v239, v42
	v_fmac_f32_e32 v231, v239, v42
	v_fmac_f32_e32 v224, v240, v42
	v_fmac_f32_e32 v232, v240, v42
	v_fmac_f32_e32 v225, v241, v42
	v_fmac_f32_e32 v233, v241, v42
	v_fmac_f32_e32 v226, v242, v42
	v_fmac_f32_e32 v234, v242, v42
	v_fmac_f32_e32 v227, v243, v42
	v_fmac_f32_e32 v235, v243, v42
	v_fmac_f32_e32 v228, v244, v42
	v_fmac_f32_e32 v236, v244, v42
	v_fmac_f32_e32 v229, v245, v42
	v_fmac_f32_e32 v237, v245, v42
	v_lshlrev_b32_e32 v238, 16, v172
	v_and_b32_e32 v239, 0xffff0000, v172
	v_lshlrev_b32_e32 v240, 16, v173
	v_and_b32_e32 v241, 0xffff0000, v173
	v_lshlrev_b32_e32 v242, 16, v174
	v_and_b32_e32 v243, 0xffff0000, v174
	v_lshlrev_b32_e32 v244, 16, v175
	v_and_b32_e32 v245, 0xffff0000, v175
	v_fmac_f32_e32 v222, v238, v43
	v_fmac_f32_e32 v230, v238, v43
	v_fmac_f32_e32 v223, v239, v43
	v_fmac_f32_e32 v231, v239, v43
	v_fmac_f32_e32 v224, v240, v43
	v_fmac_f32_e32 v232, v240, v43
	v_fmac_f32_e32 v225, v241, v43
	v_fmac_f32_e32 v233, v241, v43
	v_fmac_f32_e32 v226, v242, v43
	v_fmac_f32_e32 v234, v242, v43
	v_fmac_f32_e32 v227, v243, v43
	v_fmac_f32_e32 v235, v243, v43
	v_fmac_f32_e32 v228, v244, v43
	v_fmac_f32_e32 v236, v244, v43
	v_fmac_f32_e32 v229, v245, v43
	v_fmac_f32_e32 v237, v245, v43
	v_lshlrev_b32_e32 v238, 16, v176
	v_and_b32_e32 v239, 0xffff0000, v176
	v_lshlrev_b32_e32 v240, 16, v177
	v_and_b32_e32 v241, 0xffff0000, v177
	v_lshlrev_b32_e32 v242, 16, v178
	v_and_b32_e32 v243, 0xffff0000, v178
	v_lshlrev_b32_e32 v244, 16, v179
	v_and_b32_e32 v245, 0xffff0000, v179
	v_fmac_f32_e32 v222, v238, v44
	v_fmac_f32_e32 v230, v238, v44
	v_fmac_f32_e32 v223, v239, v44
	v_fmac_f32_e32 v231, v239, v44
	v_fmac_f32_e32 v224, v240, v44
	v_fmac_f32_e32 v232, v240, v44
	v_fmac_f32_e32 v225, v241, v44
	v_fmac_f32_e32 v233, v241, v44
	v_fmac_f32_e32 v226, v242, v44
	v_fmac_f32_e32 v234, v242, v44
	v_fmac_f32_e32 v227, v243, v44
	v_fmac_f32_e32 v235, v243, v44
	v_fmac_f32_e32 v228, v244, v44
	v_fmac_f32_e32 v236, v244, v44
	v_fmac_f32_e32 v229, v245, v44
	v_fmac_f32_e32 v237, v245, v44
	v_lshlrev_b32_e32 v238, 16, v180
	v_and_b32_e32 v239, 0xffff0000, v180
	v_lshlrev_b32_e32 v240, 16, v181
	v_and_b32_e32 v241, 0xffff0000, v181
	v_lshlrev_b32_e32 v242, 16, v182
	v_and_b32_e32 v243, 0xffff0000, v182
	v_lshlrev_b32_e32 v244, 16, v183
	v_and_b32_e32 v245, 0xffff0000, v183
	v_fmac_f32_e32 v222, v238, v45
	v_fmac_f32_e32 v230, v238, v45
	v_fmac_f32_e32 v223, v239, v45
	v_fmac_f32_e32 v231, v239, v45
	v_fmac_f32_e32 v224, v240, v45
	v_fmac_f32_e32 v232, v240, v45
	v_fmac_f32_e32 v225, v241, v45
	v_fmac_f32_e32 v233, v241, v45
	v_fmac_f32_e32 v226, v242, v45
	v_fmac_f32_e32 v234, v242, v45
	v_fmac_f32_e32 v227, v243, v45
	v_fmac_f32_e32 v235, v243, v45
	v_fmac_f32_e32 v228, v244, v45
	v_fmac_f32_e32 v236, v244, v45
	v_fmac_f32_e32 v229, v245, v45
	v_fmac_f32_e32 v237, v245, v45
	v_lshlrev_b32_e32 v238, 16, v184
	v_and_b32_e32 v239, 0xffff0000, v184
	v_lshlrev_b32_e32 v240, 16, v185
	v_and_b32_e32 v241, 0xffff0000, v185
	v_lshlrev_b32_e32 v242, 16, v186
	v_and_b32_e32 v243, 0xffff0000, v186
	v_lshlrev_b32_e32 v244, 16, v187
	v_and_b32_e32 v245, 0xffff0000, v187
	v_fmac_f32_e32 v222, v238, v46
	v_fmac_f32_e32 v230, v238, v46
	v_fmac_f32_e32 v223, v239, v46
	v_fmac_f32_e32 v231, v239, v46
	v_fmac_f32_e32 v224, v240, v46
	v_fmac_f32_e32 v232, v240, v46
	v_fmac_f32_e32 v225, v241, v46
	v_fmac_f32_e32 v233, v241, v46
	v_fmac_f32_e32 v226, v242, v46
	v_fmac_f32_e32 v234, v242, v46
	v_fmac_f32_e32 v227, v243, v46
	v_fmac_f32_e32 v235, v243, v46
	v_fmac_f32_e32 v228, v244, v46
	v_fmac_f32_e32 v236, v244, v46
	v_fmac_f32_e32 v229, v245, v46
	v_fmac_f32_e32 v237, v245, v46
	v_lshlrev_b32_e32 v238, 16, v188
	v_and_b32_e32 v239, 0xffff0000, v188
	v_lshlrev_b32_e32 v240, 16, v189
	v_and_b32_e32 v241, 0xffff0000, v189
	v_lshlrev_b32_e32 v242, 16, v190
	v_and_b32_e32 v243, 0xffff0000, v190
	v_lshlrev_b32_e32 v244, 16, v191
	v_and_b32_e32 v245, 0xffff0000, v191
	v_fmac_f32_e32 v222, v238, v47
	v_fmac_f32_e32 v230, v238, v47
	v_fmac_f32_e32 v223, v239, v47
	v_fmac_f32_e32 v231, v239, v47
	v_fmac_f32_e32 v224, v240, v47
	v_fmac_f32_e32 v232, v240, v47
	v_fmac_f32_e32 v225, v241, v47
	v_fmac_f32_e32 v233, v241, v47
	v_fmac_f32_e32 v226, v242, v47
	v_fmac_f32_e32 v234, v242, v47
	v_fmac_f32_e32 v227, v243, v47
	v_fmac_f32_e32 v235, v243, v47
	v_fmac_f32_e32 v228, v244, v47
	v_fmac_f32_e32 v236, v244, v47
	v_fmac_f32_e32 v229, v245, v47
	v_fmac_f32_e32 v237, v245, v47
	v_lshlrev_b32_e32 v238, 16, v192
	v_and_b32_e32 v239, 0xffff0000, v192
	v_lshlrev_b32_e32 v240, 16, v193
	v_and_b32_e32 v241, 0xffff0000, v193
	v_lshlrev_b32_e32 v242, 16, v194
	v_and_b32_e32 v243, 0xffff0000, v194
	v_lshlrev_b32_e32 v244, 16, v195
	v_and_b32_e32 v245, 0xffff0000, v195
	v_fmac_f32_e32 v222, v238, v48
	v_fmac_f32_e32 v230, v238, v48
	v_fmac_f32_e32 v223, v239, v48
	v_fmac_f32_e32 v231, v239, v48
	v_fmac_f32_e32 v224, v240, v48
	v_fmac_f32_e32 v232, v240, v48
	v_fmac_f32_e32 v225, v241, v48
	v_fmac_f32_e32 v233, v241, v48
	v_fmac_f32_e32 v226, v242, v48
	v_fmac_f32_e32 v234, v242, v48
	v_fmac_f32_e32 v227, v243, v48
	v_fmac_f32_e32 v235, v243, v48
	v_fmac_f32_e32 v228, v244, v48
	v_fmac_f32_e32 v236, v244, v48
	v_fmac_f32_e32 v229, v245, v48
	v_fmac_f32_e32 v237, v245, v48
	v_lshlrev_b32_e32 v238, 16, v196
	v_and_b32_e32 v239, 0xffff0000, v196
	v_lshlrev_b32_e32 v240, 16, v197
	v_and_b32_e32 v241, 0xffff0000, v197
	v_lshlrev_b32_e32 v242, 16, v198
	v_and_b32_e32 v243, 0xffff0000, v198
	v_lshlrev_b32_e32 v244, 16, v199
	v_and_b32_e32 v245, 0xffff0000, v199
	v_fmac_f32_e32 v230, v238, v49
	v_fmac_f32_e32 v231, v239, v49
	v_fmac_f32_e32 v232, v240, v49
	v_fmac_f32_e32 v233, v241, v49
	v_fmac_f32_e32 v234, v242, v49
	v_fmac_f32_e32 v235, v243, v49
	v_fmac_f32_e32 v236, v244, v49
	v_fmac_f32_e32 v237, v245, v49
	v_fma_f32 v222, v222, v53, -v206
	v_fma_f32 v230, v230, v57, -v214
	v_fma_f32 v223, v223, v53, -v207
	v_fma_f32 v231, v231, v57, -v215
	v_fma_f32 v224, v224, v53, -v208
	v_fma_f32 v232, v232, v57, -v216
	v_fma_f32 v225, v225, v53, -v209
	v_fma_f32 v233, v233, v57, -v217
	v_fma_f32 v226, v226, v53, -v210
	v_fma_f32 v234, v234, v57, -v218
	v_fma_f32 v227, v227, v53, -v211
	v_fma_f32 v235, v235, v57, -v219
	v_fma_f32 v228, v228, v53, -v212
	v_fma_f32 v236, v236, v57, -v220
	v_fma_f32 v229, v229, v53, -v213
	v_fma_f32 v237, v237, v57, -v221
	v_cvt_pk_bf16_f32 v246, v222, v223
	v_cvt_pk_bf16_f32 v247, v224, v225
	v_cvt_pk_bf16_f32 v248, v226, v227
	v_cvt_pk_bf16_f32 v249, v228, v229
	global_store_dwordx4 v7, v[246:249], s[84:85] offset:1536
	s_nop 1
	v_cvt_pk_bf16_f32 v250, v230, v231
	v_cvt_pk_bf16_f32 v251, v232, v233
	v_cvt_pk_bf16_f32 v252, v234, v235
	v_cvt_pk_bf16_f32 v253, v236, v237
	global_store_dwordx4 v7, v[250:253], s[84:85] offset:-512
	s_nop 1
	v_add_u32_e32 v2, 0x40000, v2
	s_cmp_gt_u32 s2, 31
	s_cbranch_scc1 .Lpoold_done
	s_lshr_b32 s90, s2, 3
	s_lshl_b32 s91, s90, 12
	v_subrev_u32_e32 v2, s91, v2
	v_lshrrev_b32_e32 v3, 5, v2
	v_and_b32_e32 v5, 31, v2
	v_lshlrev_b32_e32 v5, 4, v5
	v_mul_u32_u24_e32 v6, 0x4800, v3
	v_add_u32_e32 v6, v6, v5
	v_lshl_add_u32 v7, v3, 11, v5
	v_add_u32_e32 v8, 0xffffe000, v3
	v_mul_u32_u24_e32 v8, 0xf000, v8
	v_lshl_add_u32 v8, v5, 1, v8
	s_cmp_lg_u32 s90, 0
	s_cbranch_scc1 .Lpoold_sg0_end
	global_load_dwordx4 v[64:67], v6, s[28:29]
	s_add_u32 s88, s60, 0xe000
	s_addc_u32 s89, s61, 0
	global_load_dwordx4 v[68:71], v8, s[88:89]
	global_load_dwordx4 v[72:75], v8, s[88:89] offset:16
	s_waitcnt vmcnt(0)
	v_lshlrev_b32_e32 v220, 16, v64
	v_and_b32_e32 v221, 0xffff0000, v64
	v_lshlrev_b32_e32 v222, 16, v65
	v_and_b32_e32 v223, 0xffff0000, v65
	v_lshlrev_b32_e32 v224, 16, v66
	v_and_b32_e32 v225, 0xffff0000, v66
	v_lshlrev_b32_e32 v226, 16, v67
	v_and_b32_e32 v227, 0xffff0000, v67
	v_mov_b32_e32 v228, v220
	v_mov_b32_e32 v229, v221
	v_mov_b32_e32 v230, v222
	v_mov_b32_e32 v231, v223
	v_mov_b32_e32 v232, v224
	v_mov_b32_e32 v233, v225
	v_mov_b32_e32 v234, v226
	v_mov_b32_e32 v235, v227
	v_add_f32_e32 v228, v228, v68
	v_add_f32_e32 v229, v229, v69
	v_add_f32_e32 v230, v230, v70
	v_add_f32_e32 v231, v231, v71
	v_add_f32_e32 v232, v232, v72
	v_add_f32_e32 v233, v233, v73
	v_add_f32_e32 v234, v234, v74
	v_add_f32_e32 v235, v235, v75
	v_mov_b32_e32 v48, 0x3f000000
	v_fma_f32 v228, v228, v48, -v220
	v_fma_f32 v229, v229, v48, -v221
	v_fma_f32 v230, v230, v48, -v222
	v_fma_f32 v231, v231, v48, -v223
	v_fma_f32 v232, v232, v48, -v224
	v_fma_f32 v233, v233, v48, -v225
	v_fma_f32 v234, v234, v48, -v226
	v_fma_f32 v235, v235, v48, -v227
	v_cvt_pk_bf16_f32 v244, v228, v229
	v_cvt_pk_bf16_f32 v245, v230, v231
	v_cvt_pk_bf16_f32 v246, v232, v233
	v_cvt_pk_bf16_f32 v247, v234, v235
	global_store_dwordx4 v7, v[244:247], s[84:85]
	s_nop 1

.LBB0_818:
	s_setprio 0
	s_cmp_lt_i32 s18, 4
	s_cselect_b64 s[4:5], -1, 0
	s_and_b64 s[10:11], s[4:5], s[0:1]
	s_andn2_b64 vcc, exec, s[10:11]
	s_cbranch_vccnz .LBB0_967
	s_cmp_gt_i32 s2, 63
	s_mov_b64 s[0:1], -1
	s_cbranch_scc0 .LBB0_897
	s_cmp_gt_u32 s2, 0xbf
	s_cbranch_scc1 .Lcpd_back
	s_mov_b32 s32, 1
	v_writelane_b32 v254, s10, 40
	v_writelane_b32 v254, s11, 41
	s_add_i32 s79, s2, 0x400
	s_add_u32 s28, s22, 0xa6aa000
	s_addc_u32 s29, s23, 0
	s_mov_b64 s[30:31], 0
	s_mov_b64 exec, -1
	s_branch .LBB0_661

.LBB0_851:
	s_ashr_i32 s39, s38, 31
	s_lshl_b64 s[40:41], s[38:39], 19
	ds_read_b128 v[0:3], v149
	ds_read_b128 v[4:7], v149 offset:1024
	ds_read_b128 v[8:11], v149 offset:2048
	ds_read_b128 v[12:15], v149 offset:3072
	ds_read_b128 v[16:19], v150
	ds_read_b128 v[20:23], v150 offset:1024
	ds_read_b128 v[24:27], v150 offset:2048
	ds_read_b128 v[28:31], v150 offset:3072
	s_add_u32 s39, s4, s40
	s_addc_u32 s42, s5, s41
	s_ashr_i32 s37, s36, 31
	s_lshl_b64 s[40:41], s[36:37], 9
	s_add_u32 s40, s39, s40
	s_addc_u32 s41, s42, s41
	s_and_b64 s[42:43], s[0:1], exec
	s_cselect_b32 s57, s41, s47
	s_cselect_b32 s56, s40, s46
	s_lshl_b64 s[42:43], s[36:37], 17
	s_add_u32 s42, s22, s42
	s_addc_u32 s43, s23, s43
	s_and_b64 s[50:51], s[0:1], exec
	s_cselect_b32 s51, s43, s49
	s_cselect_b32 s50, s42, s48
	s_add_u32 s64, s46, 0x40080
	s_addc_u32 s65, s47, 0
	s_add_i32 s74, s13, 0xc000
	v_lshl_add_u64 v[64:65], s[64:65], 0, v[128:129]
	s_mov_b32 m0, s74
	s_add_i32 s37, s13, 0xe000
	ds_read_b128 v[32:35], v151
	ds_read_b128 v[36:39], v151 offset:1024
	ds_read_b128 v[40:43], v151 offset:2048
	ds_read_b128 v[44:47], v151 offset:3072
	ds_read_b128 v[48:51], v151 offset:4096
	ds_read_b128 v[52:55], v151 offset:5120
	ds_read_b128 v[56:59], v151 offset:6144
	ds_read_b128 v[60:63], v151 offset:7168
	global_load_lds_dwordx4 v[64:65], off
	v_lshl_add_u64 v[64:65], s[64:65], 0, v[132:133]
	s_mov_b32 m0, s37
	s_nop 0
	global_load_lds_dwordx4 v[64:65], off
	s_waitcnt vmcnt(8)
	s_waitcnt lgkmcnt(0)
	s_barrier
	s_waitcnt lgkmcnt(0)
	v_mfma_f32_16x16x32_bf16 v[64:67], v[0:3], v[32:35], 0
	v_mfma_f32_16x16x32_bf16 v[68:71], v[8:11], v[32:35], 0
	v_mfma_f32_16x16x32_bf16 v[72:75], v[0:3], v[40:43], 0
	v_mfma_f32_16x16x32_bf16 v[76:79], v[8:11], v[40:43], 0
	v_mfma_f32_16x16x32_bf16 v[80:83], v[0:3], v[48:51], 0
	v_mfma_f32_16x16x32_bf16 v[84:87], v[8:11], v[48:51], 0
	v_mfma_f32_16x16x32_bf16 v[88:91], v[0:3], v[56:59], 0
	v_mfma_f32_16x16x32_bf16 v[92:95], v[8:11], v[56:59], 0
	v_mfma_f32_16x16x32_bf16 v[64:67], v[4:7], v[36:39], v[64:67]
	v_mfma_f32_16x16x32_bf16 v[68:71], v[12:15], v[36:39], v[68:71]
	v_mfma_f32_16x16x32_bf16 v[72:75], v[4:7], v[44:47], v[72:75]
	v_mfma_f32_16x16x32_bf16 v[76:79], v[12:15], v[44:47], v[76:79]
	v_mfma_f32_16x16x32_bf16 v[80:83], v[4:7], v[52:55], v[80:83]
	v_mfma_f32_16x16x32_bf16 v[84:87], v[12:15], v[52:55], v[84:87]
	v_mfma_f32_16x16x32_bf16 v[88:91], v[4:7], v[60:63], v[88:91]
	v_mfma_f32_16x16x32_bf16 v[92:95], v[12:15], v[60:63], v[92:95]
	v_mfma_f32_16x16x32_bf16 v[96:99], v[16:19], v[32:35], 0
	v_mfma_f32_16x16x32_bf16 v[32:35], v[24:27], v[32:35], 0
	v_mfma_f32_16x16x32_bf16 v[96:99], v[20:23], v[36:39], v[96:99]
	v_mfma_f32_16x16x32_bf16 v[32:35], v[28:31], v[36:39], v[32:35]
	v_mfma_f32_16x16x32_bf16 v[36:39], v[16:19], v[40:43], 0
	v_mfma_f32_16x16x32_bf16 v[40:43], v[24:27], v[40:43], 0
	v_mfma_f32_16x16x32_bf16 v[36:39], v[20:23], v[44:47], v[36:39]
	v_mfma_f32_16x16x32_bf16 v[40:43], v[28:31], v[44:47], v[40:43]
	v_mfma_f32_16x16x32_bf16 v[44:47], v[16:19], v[48:51], 0
	v_mfma_f32_16x16x32_bf16 v[48:51], v[24:27], v[48:51], 0
	v_mfma_f32_16x16x32_bf16 v[44:47], v[20:23], v[52:55], v[44:47]
	v_mfma_f32_16x16x32_bf16 v[48:51], v[28:31], v[52:55], v[48:51]
	v_mfma_f32_16x16x32_bf16 v[52:55], v[16:19], v[56:59], 0
	v_mfma_f32_16x16x32_bf16 v[56:59], v[24:27], v[56:59], 0
	v_mfma_f32_16x16x32_bf16 v[52:55], v[20:23], v[60:63], v[52:55]
	v_mfma_f32_16x16x32_bf16 v[56:59], v[28:31], v[60:63], v[56:59]
	s_barrier
	s_add_i32 s66, s61, s3
	v_lshl_add_u64 v[144:145], s[48:49], 0, v[130:131]
	s_add_i32 s39, s66, 0x2000
	v_lshl_add_u64 v[140:141], v[144:145], 0, s[30:31]
	s_mov_b32 m0, s66
	v_lshl_add_u64 v[212:213], s[48:49], 0, v[134:135]
	s_add_u32 s76, s48, 0x10100
	ds_read_b128 v[60:63], v151 offset:16384
	ds_read_b128 v[100:103], v151 offset:17408
	ds_read_b128 v[104:107], v151 offset:18432
	ds_read_b128 v[108:111], v151 offset:19456
	ds_read_b128 v[112:115], v151 offset:20480
	ds_read_b128 v[116:119], v151 offset:21504
	ds_read_b128 v[120:123], v151 offset:22528
	ds_read_b128 v[124:127], v151 offset:23552
	global_load_lds_dwordx4 v[140:141], off
	v_lshl_add_u64 v[140:141], v[212:213], 0, s[30:31]
	s_mov_b32 m0, s39
	s_addc_u32 s77, s49, 0
	s_add_i32 s64, s62, s3
	global_load_lds_dwordx4 v[140:141], off
	v_lshl_add_u64 v[140:141], s[76:77], 0, v[130:131]
	s_mov_b32 m0, s64
	s_add_i32 s65, s64, 0x2000
	global_load_lds_dwordx4 v[140:141], off
	v_lshl_add_u64 v[140:141], s[76:77], 0, v[134:135]
	s_mov_b32 m0, s65
	v_lshl_add_u64 v[214:215], s[46:47], 0, v[128:129]
	global_load_lds_dwordx4 v[140:141], off
	v_lshl_add_u64 v[140:141], v[214:215], 0, s[30:31]
	s_mov_b32 m0, s13
	v_lshl_add_u64 v[216:217], s[46:47], 0, v[132:133]
	global_load_lds_dwordx4 v[140:141], off
	v_lshl_add_u64 v[140:141], v[216:217], 0, s[30:31]
	s_mov_b32 m0, s15
	s_nop 0
	global_load_lds_dwordx4 v[140:141], off
	s_waitcnt vmcnt(8)
	s_waitcnt lgkmcnt(0)
	s_barrier
	s_waitcnt lgkmcnt(0)
	v_mfma_f32_16x16x32_bf16 v[140:143], v[0:3], v[60:63], 0
	v_mfma_f32_16x16x32_bf16 v[156:159], v[0:3], v[104:107], 0
	v_mfma_f32_16x16x32_bf16 v[164:167], v[0:3], v[112:115], 0
	v_mfma_f32_16x16x32_bf16 v[0:3], v[0:3], v[120:123], 0
	v_mfma_f32_16x16x32_bf16 v[140:143], v[4:7], v[100:103], v[140:143]
	v_mfma_f32_16x16x32_bf16 v[156:159], v[4:7], v[108:111], v[156:159]
	v_mfma_f32_16x16x32_bf16 v[164:167], v[4:7], v[116:119], v[164:167]
	v_mfma_f32_16x16x32_bf16 v[0:3], v[4:7], v[124:127], v[0:3]
	v_mfma_f32_16x16x32_bf16 v[4:7], v[8:11], v[120:123], 0
	v_mfma_f32_16x16x32_bf16 v[152:155], v[8:11], v[60:63], 0
	v_mfma_f32_16x16x32_bf16 v[160:163], v[8:11], v[104:107], 0
	v_mfma_f32_16x16x32_bf16 v[168:171], v[8:11], v[112:115], 0
	v_mfma_f32_16x16x32_bf16 v[4:7], v[12:15], v[124:127], v[4:7]
	v_mfma_f32_16x16x32_bf16 v[152:155], v[12:15], v[100:103], v[152:155]
	v_mfma_f32_16x16x32_bf16 v[160:163], v[12:15], v[108:111], v[160:163]
	v_mfma_f32_16x16x32_bf16 v[168:171], v[12:15], v[116:119], v[168:171]
	v_mfma_f32_16x16x32_bf16 v[8:11], v[16:19], v[60:63], 0
	v_mfma_f32_16x16x32_bf16 v[12:15], v[24:27], v[60:63], 0
	v_mfma_f32_16x16x32_bf16 v[8:11], v[20:23], v[100:103], v[8:11]
	v_mfma_f32_16x16x32_bf16 v[12:15], v[28:31], v[100:103], v[12:15]
	v_mfma_f32_16x16x32_bf16 v[60:63], v[16:19], v[104:107], 0
	v_mfma_f32_16x16x32_bf16 v[100:103], v[24:27], v[104:107], 0
	v_mfma_f32_16x16x32_bf16 v[104:107], v[16:19], v[112:115], 0
	v_mfma_f32_16x16x32_bf16 v[16:19], v[16:19], v[120:123], 0
	v_mfma_f32_16x16x32_bf16 v[60:63], v[20:23], v[108:111], v[60:63]
	v_mfma_f32_16x16x32_bf16 v[100:103], v[28:31], v[108:111], v[100:103]
	v_mfma_f32_16x16x32_bf16 v[104:107], v[20:23], v[116:119], v[104:107]
	v_mfma_f32_16x16x32_bf16 v[108:111], v[24:27], v[112:115], 0
	v_mfma_f32_16x16x32_bf16 v[16:19], v[20:23], v[124:127], v[16:19]
	v_mfma_f32_16x16x32_bf16 v[20:23], v[24:27], v[120:123], 0
	v_mfma_f32_16x16x32_bf16 v[108:111], v[28:31], v[116:119], v[108:111]
	v_mfma_f32_16x16x32_bf16 v[20:23], v[28:31], v[124:127], v[20:23]
	s_barrier
	s_add_i32 s75, 0, 0x18000
	s_add_i32 s78, 0, 0x1c000
	v_add_u32_e32 v224, s75, v147
	v_add_u32_e32 v225, s78, v147
	ds_read_b128 v[24:27], v224
	ds_read_b128 v[28:31], v224 offset:1024
	ds_read_b128 v[112:115], v224 offset:2048
	ds_read_b128 v[116:119], v224 offset:3072
	ds_read_b128 v[120:123], v225
	ds_read_b128 v[124:127], v225 offset:1024
	ds_read_b128 v[172:175], v225 offset:2048
	ds_read_b128 v[176:179], v225 offset:3072
	s_add_u32 s76, s46, 0x40100
	s_addc_u32 s77, s47, 0
	s_mov_b32 m0, s25
	v_lshl_add_u64 v[218:219], s[76:77], 0, v[128:129]
	ds_read_b128 v[180:183], v151 offset:32768
	ds_read_b128 v[184:187], v151 offset:33792
	ds_read_b128 v[188:191], v151 offset:34816
	ds_read_b128 v[192:195], v151 offset:35840
	ds_read_b128 v[196:199], v151 offset:36864
	ds_read_b128 v[200:203], v151 offset:37888
	ds_read_b128 v[204:207], v151 offset:38912
	ds_read_b128 v[208:211], v151 offset:39936
	global_load_lds_dwordx4 v[218:219], off
	v_lshl_add_u64 v[218:219], s[76:77], 0, v[132:133]
	s_mov_b32 m0, s45
	s_nop 0
	global_load_lds_dwordx4 v[218:219], off
	s_waitcnt vmcnt(8)
	s_waitcnt lgkmcnt(0)
	s_barrier
	s_waitcnt lgkmcnt(0)
	v_mfma_f32_16x16x32_bf16 v[64:67], v[24:27], v[180:183], v[64:67]
	v_mfma_f32_16x16x32_bf16 v[68:71], v[112:115], v[180:183], v[68:71]
	v_mfma_f32_16x16x32_bf16 v[72:75], v[24:27], v[188:191], v[72:75]
	v_mfma_f32_16x16x32_bf16 v[76:79], v[112:115], v[188:191], v[76:79]
	v_mfma_f32_16x16x32_bf16 v[80:83], v[24:27], v[196:199], v[80:83]
	v_mfma_f32_16x16x32_bf16 v[84:87], v[112:115], v[196:199], v[84:87]
	v_mfma_f32_16x16x32_bf16 v[88:91], v[24:27], v[204:207], v[88:91]
	v_mfma_f32_16x16x32_bf16 v[92:95], v[112:115], v[204:207], v[92:95]
	v_mfma_f32_16x16x32_bf16 v[64:67], v[28:31], v[184:187], v[64:67]
	v_mfma_f32_16x16x32_bf16 v[68:71], v[116:119], v[184:187], v[68:71]
	v_mfma_f32_16x16x32_bf16 v[72:75], v[28:31], v[192:195], v[72:75]
	v_mfma_f32_16x16x32_bf16 v[76:79], v[116:119], v[192:195], v[76:79]
	v_mfma_f32_16x16x32_bf16 v[80:83], v[28:31], v[200:203], v[80:83]
	v_mfma_f32_16x16x32_bf16 v[84:87], v[116:119], v[200:203], v[84:87]
	v_mfma_f32_16x16x32_bf16 v[88:91], v[28:31], v[208:211], v[88:91]
	v_mfma_f32_16x16x32_bf16 v[92:95], v[116:119], v[208:211], v[92:95]
	v_mfma_f32_16x16x32_bf16 v[96:99], v[120:123], v[180:183], v[96:99]
	v_mfma_f32_16x16x32_bf16 v[32:35], v[172:175], v[180:183], v[32:35]
	v_mfma_f32_16x16x32_bf16 v[36:39], v[120:123], v[188:191], v[36:39]
	v_mfma_f32_16x16x32_bf16 v[40:43], v[172:175], v[188:191], v[40:43]
	v_mfma_f32_16x16x32_bf16 v[44:47], v[120:123], v[196:199], v[44:47]
	v_mfma_f32_16x16x32_bf16 v[48:51], v[172:175], v[196:199], v[48:51]
	v_mfma_f32_16x16x32_bf16 v[52:55], v[120:123], v[204:207], v[52:55]
	v_mfma_f32_16x16x32_bf16 v[56:59], v[172:175], v[204:207], v[56:59]
	v_mfma_f32_16x16x32_bf16 v[96:99], v[124:127], v[184:187], v[96:99]
	v_mfma_f32_16x16x32_bf16 v[32:35], v[176:179], v[184:187], v[32:35]
	v_mfma_f32_16x16x32_bf16 v[36:39], v[124:127], v[192:195], v[36:39]
	v_mfma_f32_16x16x32_bf16 v[40:43], v[176:179], v[192:195], v[40:43]
	v_mfma_f32_16x16x32_bf16 v[44:47], v[124:127], v[200:203], v[44:47]
	v_mfma_f32_16x16x32_bf16 v[48:51], v[176:179], v[200:203], v[48:51]
	v_mfma_f32_16x16x32_bf16 v[52:55], v[124:127], v[208:211], v[52:55]
	v_mfma_f32_16x16x32_bf16 v[56:59], v[176:179], v[208:211], v[56:59]
	s_barrier
	s_add_i32 s75, s75, s3
	s_add_i32 s67, s75, 0x2000
	v_lshl_add_u64 v[144:145], v[144:145], 0, s[34:35]
	s_mov_b32 m0, s75
	s_add_u32 s76, s48, 0x10180
	ds_read_b128 v[180:183], v151 offset:49152
	ds_read_b128 v[184:187], v151 offset:50176
	ds_read_b128 v[188:191], v151 offset:51200
	ds_read_b128 v[192:195], v151 offset:52224
	ds_read_b128 v[196:199], v151 offset:53248
	ds_read_b128 v[200:203], v151 offset:54272
	ds_read_b128 v[204:207], v151 offset:55296
	ds_read_b128 v[208:211], v151 offset:56320
	global_load_lds_dwordx4 v[144:145], off
	v_lshl_add_u64 v[144:145], v[212:213], 0, s[34:35]
	s_mov_b32 m0, s67
	s_addc_u32 s77, s49, 0
	s_add_i32 s48, s78, s3
	global_load_lds_dwordx4 v[144:145], off
	v_lshl_add_u64 v[144:145], s[76:77], 0, v[130:131]
	s_mov_b32 m0, s48
	s_add_i32 s49, s48, 0x2000
	global_load_lds_dwordx4 v[144:145], off
	v_lshl_add_u64 v[144:145], s[76:77], 0, v[134:135]
	s_mov_b32 m0, s49
	s_nop 0
	global_load_lds_dwordx4 v[144:145], off
	v_lshl_add_u64 v[144:145], v[214:215], 0, s[34:35]
	s_mov_b32 m0, s58
	s_nop 0
	global_load_lds_dwordx4 v[144:145], off
	v_lshl_add_u64 v[144:145], v[216:217], 0, s[34:35]
	s_mov_b32 m0, s59
	s_nop 0
	global_load_lds_dwordx4 v[144:145], off
	s_waitcnt vmcnt(8)
	s_waitcnt lgkmcnt(0)
	s_barrier
	s_waitcnt lgkmcnt(0)
	v_mfma_f32_16x16x32_bf16 v[0:3], v[24:27], v[204:207], v[0:3]
	v_mfma_f32_16x16x32_bf16 v[4:7], v[112:115], v[204:207], v[4:7]
	v_mfma_f32_16x16x32_bf16 v[140:143], v[24:27], v[180:183], v[140:143]
	v_mfma_f32_16x16x32_bf16 v[152:155], v[112:115], v[180:183], v[152:155]
	v_mfma_f32_16x16x32_bf16 v[156:159], v[24:27], v[188:191], v[156:159]
	v_mfma_f32_16x16x32_bf16 v[160:163], v[112:115], v[188:191], v[160:163]
	v_mfma_f32_16x16x32_bf16 v[164:167], v[24:27], v[196:199], v[164:167]
	v_mfma_f32_16x16x32_bf16 v[168:171], v[112:115], v[196:199], v[168:171]
	v_mfma_f32_16x16x32_bf16 v[0:3], v[28:31], v[208:211], v[0:3]
	v_mfma_f32_16x16x32_bf16 v[4:7], v[116:119], v[208:211], v[4:7]
	v_mfma_f32_16x16x32_bf16 v[140:143], v[28:31], v[184:187], v[140:143]
	v_mfma_f32_16x16x32_bf16 v[152:155], v[116:119], v[184:187], v[152:155]
	v_mfma_f32_16x16x32_bf16 v[156:159], v[28:31], v[192:195], v[156:159]
	v_mfma_f32_16x16x32_bf16 v[160:163], v[116:119], v[192:195], v[160:163]
	v_mfma_f32_16x16x32_bf16 v[164:167], v[28:31], v[200:203], v[164:167]
	v_mfma_f32_16x16x32_bf16 v[168:171], v[116:119], v[200:203], v[168:171]
	v_mfma_f32_16x16x32_bf16 v[8:11], v[120:123], v[180:183], v[8:11]
	v_mfma_f32_16x16x32_bf16 v[12:15], v[172:175], v[180:183], v[12:15]
	v_mfma_f32_16x16x32_bf16 v[24:27], v[120:123], v[188:191], v[60:63]
	v_mfma_f32_16x16x32_bf16 v[28:31], v[172:175], v[188:191], v[100:103]
	v_mfma_f32_16x16x32_bf16 v[60:63], v[120:123], v[196:199], v[104:107]
	v_mfma_f32_16x16x32_bf16 v[100:103], v[172:175], v[196:199], v[108:111]
	v_mfma_f32_16x16x32_bf16 v[16:19], v[120:123], v[204:207], v[16:19]
	v_mfma_f32_16x16x32_bf16 v[20:23], v[172:175], v[204:207], v[20:23]
	v_mfma_f32_16x16x32_bf16 v[8:11], v[124:127], v[184:187], v[8:11]
	v_mfma_f32_16x16x32_bf16 v[12:15], v[176:179], v[184:187], v[12:15]
	v_mfma_f32_16x16x32_bf16 v[24:27], v[124:127], v[192:195], v[24:27]
	v_mfma_f32_16x16x32_bf16 v[28:31], v[176:179], v[192:195], v[28:31]
	v_mfma_f32_16x16x32_bf16 v[60:63], v[124:127], v[200:203], v[60:63]
	v_mfma_f32_16x16x32_bf16 v[100:103], v[176:179], v[200:203], v[100:103]
	v_mfma_f32_16x16x32_bf16 v[16:19], v[124:127], v[208:211], v[16:19]
	v_mfma_f32_16x16x32_bf16 v[20:23], v[176:179], v[208:211], v[20:23]
	s_barrier
	ds_read_b128 v[104:107], v149
	ds_read_b128 v[108:111], v149 offset:1024
	ds_read_b128 v[112:115], v149 offset:2048
	ds_read_b128 v[116:119], v149 offset:3072
	ds_read_b128 v[120:123], v150
	ds_read_b128 v[124:127], v150 offset:1024
	ds_read_b128 v[172:175], v150 offset:2048
	ds_read_b128 v[176:179], v150 offset:3072
	s_add_u32 s46, s46, 0x40180
	s_addc_u32 s47, s47, 0
	s_mov_b32 m0, s74
	v_lshl_add_u64 v[144:145], s[46:47], 0, v[128:129]
	ds_read_b128 v[180:183], v151
	ds_read_b128 v[184:187], v151 offset:1024
	ds_read_b128 v[188:191], v151 offset:2048
	ds_read_b128 v[192:195], v151 offset:3072
	ds_read_b128 v[196:199], v151 offset:4096
	ds_read_b128 v[200:203], v151 offset:5120
	ds_read_b128 v[204:207], v151 offset:6144
	ds_read_b128 v[208:211], v151 offset:7168
	global_load_lds_dwordx4 v[144:145], off
	v_lshl_add_u64 v[144:145], s[46:47], 0, v[132:133]
	s_mov_b32 m0, s37
	s_nop 0
	global_load_lds_dwordx4 v[144:145], off
	s_waitcnt vmcnt(8)
	s_waitcnt lgkmcnt(0)
	s_barrier
	s_waitcnt lgkmcnt(0)
	v_mfma_f32_16x16x32_bf16 v[64:67], v[104:107], v[180:183], v[64:67]
	v_mfma_f32_16x16x32_bf16 v[68:71], v[112:115], v[180:183], v[68:71]
	v_mfma_f32_16x16x32_bf16 v[72:75], v[104:107], v[188:191], v[72:75]
	v_mfma_f32_16x16x32_bf16 v[76:79], v[112:115], v[188:191], v[76:79]
	v_mfma_f32_16x16x32_bf16 v[80:83], v[104:107], v[196:199], v[80:83]
	v_mfma_f32_16x16x32_bf16 v[84:87], v[112:115], v[196:199], v[84:87]
	v_mfma_f32_16x16x32_bf16 v[88:91], v[104:107], v[204:207], v[88:91]
	v_mfma_f32_16x16x32_bf16 v[64:67], v[108:111], v[184:187], v[64:67]
	v_mfma_f32_16x16x32_bf16 v[68:71], v[116:119], v[184:187], v[68:71]
	v_mfma_f32_16x16x32_bf16 v[72:75], v[108:111], v[192:195], v[72:75]
	v_mfma_f32_16x16x32_bf16 v[76:79], v[116:119], v[192:195], v[76:79]
	v_mfma_f32_16x16x32_bf16 v[80:83], v[108:111], v[200:203], v[80:83]
	v_mfma_f32_16x16x32_bf16 v[84:87], v[116:119], v[200:203], v[84:87]
	v_mfma_f32_16x16x32_bf16 v[212:215], v[108:111], v[208:211], v[88:91]
	v_mfma_f32_16x16x32_bf16 v[88:91], v[112:115], v[204:207], v[92:95]
	v_mfma_f32_16x16x32_bf16 v[216:219], v[116:119], v[208:211], v[88:91]
	v_mfma_f32_16x16x32_bf16 v[88:91], v[120:123], v[180:183], v[96:99]
	v_mfma_f32_16x16x32_bf16 v[32:35], v[172:175], v[180:183], v[32:35]
	v_mfma_f32_16x16x32_bf16 v[36:39], v[120:123], v[188:191], v[36:39]
	v_mfma_f32_16x16x32_bf16 v[40:43], v[172:175], v[188:191], v[40:43]
	v_mfma_f32_16x16x32_bf16 v[44:47], v[120:123], v[196:199], v[44:47]
	v_mfma_f32_16x16x32_bf16 v[48:51], v[172:175], v[196:199], v[48:51]
	v_mfma_f32_16x16x32_bf16 v[52:55], v[120:123], v[204:207], v[52:55]
	v_mfma_f32_16x16x32_bf16 v[56:59], v[172:175], v[204:207], v[56:59]
	v_mfma_f32_16x16x32_bf16 v[96:99], v[124:127], v[184:187], v[88:91]
	v_mfma_f32_16x16x32_bf16 v[32:35], v[176:179], v[184:187], v[32:35]
	v_mfma_f32_16x16x32_bf16 v[36:39], v[124:127], v[192:195], v[36:39]
	v_mfma_f32_16x16x32_bf16 v[40:43], v[176:179], v[192:195], v[40:43]
	v_mfma_f32_16x16x32_bf16 v[44:47], v[124:127], v[200:203], v[44:47]
	v_mfma_f32_16x16x32_bf16 v[48:51], v[176:179], v[200:203], v[48:51]
	v_mfma_f32_16x16x32_bf16 v[52:55], v[124:127], v[208:211], v[52:55]
	v_mfma_f32_16x16x32_bf16 v[56:59], v[176:179], v[208:211], v[56:59]
	s_barrier
	s_mov_b32 m0, s66
	v_lshl_add_u64 v[144:145], s[50:51], 0, v[130:131]
	s_add_u32 s46, s50, 0x10000
	ds_read_b128 v[88:91], v151 offset:16384
	ds_read_b128 v[92:95], v151 offset:17408
	ds_read_b128 v[180:183], v151 offset:18432
	ds_read_b128 v[184:187], v151 offset:19456
	ds_read_b128 v[188:191], v151 offset:20480
	ds_read_b128 v[192:195], v151 offset:21504
	ds_read_b128 v[196:199], v151 offset:22528
	ds_read_b128 v[200:203], v151 offset:23552
	global_load_lds_dwordx4 v[144:145], off
	v_lshl_add_u64 v[248:249], s[50:51], 0, v[134:135]
	s_mov_b32 m0, s39
	s_addc_u32 s47, s51, 0
	global_load_lds_dwordx4 v[248:249], off
	v_lshl_add_u64 v[204:205], s[46:47], 0, v[130:131]
	s_mov_b32 m0, s64
	v_lshl_add_u64 v[250:251], s[56:57], 0, v[128:129]
	global_load_lds_dwordx4 v[204:205], off
	v_lshl_add_u64 v[204:205], s[46:47], 0, v[134:135]
	s_mov_b32 m0, s65
	v_lshl_add_u64 v[252:253], s[56:57], 0, v[132:133]
	global_load_lds_dwordx4 v[204:205], off
	s_mov_b32 m0, s13
	s_nop 0
	global_load_lds_dwordx4 v[250:251], off
	s_mov_b32 m0, s15
	s_nop 0
	global_load_lds_dwordx4 v[252:253], off
	s_waitcnt vmcnt(8)
	s_waitcnt lgkmcnt(0)
	s_barrier
	s_waitcnt lgkmcnt(0)
	v_mfma_f32_16x16x32_bf16 v[0:3], v[104:107], v[196:199], v[0:3]
	v_mfma_f32_16x16x32_bf16 v[4:7], v[112:115], v[196:199], v[4:7]
	v_mfma_f32_16x16x32_bf16 v[140:143], v[104:107], v[88:91], v[140:143]
	v_mfma_f32_16x16x32_bf16 v[152:155], v[112:115], v[88:91], v[152:155]
	v_mfma_f32_16x16x32_bf16 v[156:159], v[104:107], v[180:183], v[156:159]
	v_mfma_f32_16x16x32_bf16 v[160:163], v[112:115], v[180:183], v[160:163]
	v_mfma_f32_16x16x32_bf16 v[164:167], v[104:107], v[188:191], v[164:167]
	v_mfma_f32_16x16x32_bf16 v[168:171], v[112:115], v[188:191], v[168:171]
	v_mfma_f32_16x16x32_bf16 v[0:3], v[108:111], v[200:203], v[0:3]
	v_mfma_f32_16x16x32_bf16 v[4:7], v[116:119], v[200:203], v[4:7]
	v_mfma_f32_16x16x32_bf16 v[140:143], v[108:111], v[92:95], v[140:143]
	v_mfma_f32_16x16x32_bf16 v[152:155], v[116:119], v[92:95], v[152:155]
	v_mfma_f32_16x16x32_bf16 v[156:159], v[108:111], v[184:187], v[156:159]
	v_mfma_f32_16x16x32_bf16 v[160:163], v[116:119], v[184:187], v[160:163]
	v_mfma_f32_16x16x32_bf16 v[164:167], v[108:111], v[192:195], v[164:167]
	v_mfma_f32_16x16x32_bf16 v[168:171], v[116:119], v[192:195], v[168:171]
	v_mfma_f32_16x16x32_bf16 v[8:11], v[120:123], v[88:91], v[8:11]
	v_mfma_f32_16x16x32_bf16 v[204:207], v[124:127], v[92:95], v[8:11]
	v_mfma_f32_16x16x32_bf16 v[8:11], v[172:175], v[88:91], v[12:15]
	v_mfma_f32_16x16x32_bf16 v[208:211], v[176:179], v[92:95], v[8:11]
	v_mfma_f32_16x16x32_bf16 v[8:11], v[120:123], v[180:183], v[24:27]
	v_mfma_f32_16x16x32_bf16 v[220:223], v[124:127], v[184:187], v[8:11]
	v_mfma_f32_16x16x32_bf16 v[8:11], v[172:175], v[180:183], v[28:31]
	v_mfma_f32_16x16x32_bf16 v[180:183], v[176:179], v[184:187], v[8:11]
	v_mfma_f32_16x16x32_bf16 v[8:11], v[120:123], v[188:191], v[60:63]
	v_mfma_f32_16x16x32_bf16 v[184:187], v[124:127], v[192:195], v[8:11]
	v_mfma_f32_16x16x32_bf16 v[8:11], v[172:175], v[188:191], v[100:103]
	v_mfma_f32_16x16x32_bf16 v[188:191], v[176:179], v[192:195], v[8:11]
	v_mfma_f32_16x16x32_bf16 v[8:11], v[120:123], v[196:199], v[16:19]
	v_mfma_f32_16x16x32_bf16 v[192:195], v[124:127], v[200:203], v[8:11]
	v_mfma_f32_16x16x32_bf16 v[8:11], v[172:175], v[196:199], v[20:23]
	v_mfma_f32_16x16x32_bf16 v[172:175], v[176:179], v[200:203], v[8:11]
	s_barrier
	s_nop 4
	ds_read_b128 v[8:11], v224
	ds_read_b128 v[12:15], v224 offset:1024
	ds_read_b128 v[16:19], v224 offset:2048
	ds_read_b128 v[20:23], v224 offset:3072
	ds_read_b128 v[176:179], v225
	ds_read_b128 v[196:199], v225 offset:1024
	ds_read_b128 v[200:203], v225 offset:2048
	ds_read_b128 v[224:227], v225 offset:3072
	s_add_u32 s46, s56, 0x40000
	s_addc_u32 s47, s57, 0
	s_mov_b32 m0, s25
	v_lshl_add_u64 v[88:89], s[46:47], 0, v[128:129]
	ds_read_b128 v[24:27], v151 offset:32768
	ds_read_b128 v[28:31], v151 offset:33792
	ds_read_b128 v[60:63], v151 offset:34816
	ds_read_b128 v[228:231], v151 offset:35840
	ds_read_b128 v[232:235], v151 offset:36864
	ds_read_b128 v[236:239], v151 offset:37888
	ds_read_b128 v[240:243], v151 offset:38912
	ds_read_b128 v[244:247], v151 offset:39936
	global_load_lds_dwordx4 v[88:89], off
	v_lshl_add_u64 v[88:89], s[46:47], 0, v[132:133]
	s_mov_b32 m0, s45
	s_nop 0
	global_load_lds_dwordx4 v[88:89], off
	s_waitcnt vmcnt(8)
	s_waitcnt lgkmcnt(0)
	s_barrier
	s_waitcnt lgkmcnt(0)
	v_mfma_f32_16x16x32_bf16 v[64:67], v[8:11], v[24:27], v[64:67]
	v_mfma_f32_16x16x32_bf16 v[124:127], v[12:15], v[28:31], v[64:67]
	v_mfma_f32_16x16x32_bf16 v[64:67], v[16:19], v[24:27], v[68:71]
	v_mfma_f32_16x16x32_bf16 v[120:123], v[20:23], v[28:31], v[64:67]
	v_mfma_f32_16x16x32_bf16 v[64:67], v[8:11], v[60:63], v[72:75]
	v_mfma_f32_16x16x32_bf16 v[108:111], v[12:15], v[228:231], v[64:67]
	v_mfma_f32_16x16x32_bf16 v[64:67], v[16:19], v[60:63], v[76:79]
	v_mfma_f32_16x16x32_bf16 v[104:107], v[20:23], v[228:231], v[64:67]
	v_mfma_f32_16x16x32_bf16 v[64:67], v[8:11], v[232:235], v[80:83]
	v_mfma_f32_16x16x32_bf16 v[92:95], v[12:15], v[236:239], v[64:67]
	v_mfma_f32_16x16x32_bf16 v[64:67], v[16:19], v[232:235], v[84:87]
	v_mfma_f32_16x16x32_bf16 v[88:91], v[20:23], v[236:239], v[64:67]
	v_mfma_f32_16x16x32_bf16 v[64:67], v[8:11], v[240:243], v[212:215]
	v_mfma_f32_16x16x32_bf16 v[76:79], v[12:15], v[244:247], v[64:67]
	v_mfma_f32_16x16x32_bf16 v[64:67], v[16:19], v[240:243], v[216:219]
	v_mfma_f32_16x16x32_bf16 v[68:71], v[20:23], v[244:247], v[64:67]
	v_mfma_f32_16x16x32_bf16 v[64:67], v[176:179], v[24:27], v[96:99]
	v_mfma_f32_16x16x32_bf16 v[24:27], v[200:203], v[24:27], v[32:35]
	v_mfma_f32_16x16x32_bf16 v[112:115], v[224:227], v[28:31], v[24:27]
	v_mfma_f32_16x16x32_bf16 v[24:27], v[176:179], v[60:63], v[36:39]
	v_mfma_f32_16x16x32_bf16 v[100:103], v[196:199], v[228:231], v[24:27]
	v_mfma_f32_16x16x32_bf16 v[24:27], v[200:203], v[60:63], v[40:43]
	v_mfma_f32_16x16x32_bf16 v[96:99], v[224:227], v[228:231], v[24:27]
	v_mfma_f32_16x16x32_bf16 v[24:27], v[176:179], v[232:235], v[44:47]
	v_mfma_f32_16x16x32_bf16 v[84:87], v[196:199], v[236:239], v[24:27]
	v_mfma_f32_16x16x32_bf16 v[24:27], v[200:203], v[232:235], v[48:51]
	v_mfma_f32_16x16x32_bf16 v[80:83], v[224:227], v[236:239], v[24:27]
	v_mfma_f32_16x16x32_bf16 v[24:27], v[176:179], v[240:243], v[52:55]
	v_mfma_f32_16x16x32_bf16 v[60:63], v[196:199], v[244:247], v[24:27]
	v_mfma_f32_16x16x32_bf16 v[24:27], v[200:203], v[240:243], v[56:59]
	v_mfma_f32_16x16x32_bf16 v[116:119], v[196:199], v[28:31], v[64:67]
	v_mfma_f32_16x16x32_bf16 v[52:55], v[224:227], v[244:247], v[24:27]
	s_barrier
	s_mov_b32 m0, s75
	s_nop 2
	v_lshl_add_u64 v[24:25], v[144:145], 0, s[16:17]
	s_add_u32 s46, s50, 0x10080
	ds_read_b128 v[32:35], v151 offset:49152
	ds_read_b128 v[36:39], v151 offset:50176
	ds_read_b128 v[212:215], v151 offset:51200
	ds_read_b128 v[216:219], v151 offset:52224
	ds_read_b128 v[228:231], v151 offset:53248
	ds_read_b128 v[232:235], v151 offset:54272
	ds_read_b128 v[236:239], v151 offset:55296
	ds_read_b128 v[240:243], v151 offset:56320
	global_load_lds_dwordx4 v[24:25], off
	v_lshl_add_u64 v[24:25], v[248:249], 0, s[16:17]
	s_mov_b32 m0, s67
	s_addc_u32 s47, s51, 0
	global_load_lds_dwordx4 v[24:25], off
	v_lshl_add_u64 v[24:25], s[46:47], 0, v[130:131]
	s_mov_b32 m0, s48
	s_nop 0
	global_load_lds_dwordx4 v[24:25], off
	v_lshl_add_u64 v[24:25], s[46:47], 0, v[134:135]
	s_mov_b32 m0, s49
	s_nop 0
	global_load_lds_dwordx4 v[24:25], off
	v_lshl_add_u64 v[24:25], v[250:251], 0, s[16:17]
	s_mov_b32 m0, s58
	s_nop 0
	global_load_lds_dwordx4 v[24:25], off
	v_lshl_add_u64 v[24:25], v[252:253], 0, s[16:17]
	s_mov_b32 m0, s59
	s_nop 0
	global_load_lds_dwordx4 v[24:25], off
	s_waitcnt vmcnt(8)
	s_waitcnt lgkmcnt(0)
	s_barrier
	s_waitcnt lgkmcnt(0)
	v_mfma_f32_16x16x32_bf16 v[24:27], v[8:11], v[32:35], v[140:143]
	v_mfma_f32_16x16x32_bf16 v[72:75], v[12:15], v[36:39], v[24:27]
	v_mfma_f32_16x16x32_bf16 v[24:27], v[16:19], v[32:35], v[152:155]
	v_mfma_f32_16x16x32_bf16 v[64:67], v[20:23], v[36:39], v[24:27]
	v_mfma_f32_16x16x32_bf16 v[24:27], v[8:11], v[212:215], v[156:159]
	v_mfma_f32_16x16x32_bf16 v[44:47], v[12:15], v[216:219], v[24:27]
	v_mfma_f32_16x16x32_bf16 v[24:27], v[16:19], v[212:215], v[160:163]
	v_mfma_f32_16x16x32_bf16 v[40:43], v[20:23], v[216:219], v[24:27]
	v_mfma_f32_16x16x32_bf16 v[24:27], v[8:11], v[228:231], v[164:167]
	v_mfma_f32_16x16x32_bf16 v[0:3], v[8:11], v[236:239], v[0:3]
	v_mfma_f32_16x16x32_bf16 v[28:31], v[12:15], v[232:235], v[24:27]
	v_mfma_f32_16x16x32_bf16 v[24:27], v[16:19], v[228:231], v[168:171]
	v_mfma_f32_16x16x32_bf16 v[12:15], v[12:15], v[240:243], v[0:3]
	v_mfma_f32_16x16x32_bf16 v[0:3], v[16:19], v[236:239], v[4:7]
	v_mfma_f32_16x16x32_bf16 v[24:27], v[20:23], v[232:235], v[24:27]
	v_mfma_f32_16x16x32_bf16 v[8:11], v[20:23], v[240:243], v[0:3]
	v_mfma_f32_16x16x32_bf16 v[0:3], v[176:179], v[32:35], v[204:207]
	v_mfma_f32_16x16x32_bf16 v[56:59], v[196:199], v[36:39], v[0:3]
	v_mfma_f32_16x16x32_bf16 v[0:3], v[200:203], v[32:35], v[208:211]
	v_mfma_f32_16x16x32_bf16 v[48:51], v[224:227], v[36:39], v[0:3]
	v_mfma_f32_16x16x32_bf16 v[0:3], v[176:179], v[212:215], v[220:223]
	v_mfma_f32_16x16x32_bf16 v[36:39], v[196:199], v[216:219], v[0:3]
	v_mfma_f32_16x16x32_bf16 v[0:3], v[200:203], v[212:215], v[180:183]
	v_mfma_f32_16x16x32_bf16 v[32:35], v[224:227], v[216:219], v[0:3]
	v_mfma_f32_16x16x32_bf16 v[0:3], v[176:179], v[228:231], v[184:187]
	v_mfma_f32_16x16x32_bf16 v[20:23], v[196:199], v[232:235], v[0:3]
	v_mfma_f32_16x16x32_bf16 v[0:3], v[200:203], v[228:231], v[188:191]
	v_mfma_f32_16x16x32_bf16 v[16:19], v[224:227], v[232:235], v[0:3]
	v_mfma_f32_16x16x32_bf16 v[0:3], v[176:179], v[236:239], v[192:195]
	v_mfma_f32_16x16x32_bf16 v[4:7], v[196:199], v[240:243], v[0:3]
	v_mfma_f32_16x16x32_bf16 v[0:3], v[200:203], v[236:239], v[172:175]
	v_mfma_f32_16x16x32_bf16 v[0:3], v[224:227], v[240:243], v[0:3]
	s_barrier
	s_andn2_b64 vcc, exec, s[26:27]
	s_cbranch_vccnz .LBB0_853
	s_barrier

; #define PG8_STAGE(bufoff, gbase, voff) do { _Pragma("unroll") for (int _i = 0; _i < 2; ++_i) \
;         __builtin_amdgcn_global_load_lds((const unsigned*)((const char*)(gbase) + (voff)[_i]), (LAS unsigned*)(lds + (bufoff) + ldsw + _i * 8192), 16, 0, 0); } while (0)
; #define PG8_LDA(dst, b, h) do { _Pragma("unroll") for (int m = 0; m < 4; ++m) _Pragma("unroll") for (int k = 0; k < 2; ++k) dst[m][k] = *(const LAS bf16x8*)(lds + PG8_SA(b, h) + aoff + m * 2048 + k * 1024); } while (0)
; #define PG8_LDB(dst, b, h) do { _Pragma("unroll") for (int n = 0; n < 2; ++n) _Pragma("unroll") for (int k = 0; k < 2; ++k) dst[n][k] = *(const LAS bf16x8*)(lds + PG8_SB(b, h) + boff + n * 2048 + k * 1024); } while (0)
; #define PG8_MMA(ai, bj, At, Bt) do { __builtin_amdgcn_s_setprio(1); _Pragma("unroll") for (int m = 0; m < 4; ++m) _Pragma("unroll") for (int n = 0; n < 2; ++n) _Pragma("unroll") for (int k = 0; k < 2; ++k) \
;         acc[ai][bj][m][n] = __builtin_amdgcn_mfma_f32_16x16x32_bf16(Bt[n][k], At[m][k], acc[ai][bj][m][n], 0, 0, 0); __builtin_amdgcn_s_setprio(0); } while (0)
; #define PG8_WAIT_V(n) asm volatile("s_waitcnt vmcnt(" #n ")" ::: "memory")
; #define PG8_WAIT_L(n) asm volatile("s_waitcnt lgkmcnt(" #n ")" ::: "memory")
; #define PG8_BAR __builtin_amdgcn_s_barrier()
; #define PG8_SCHED __builtin_amdgcn_sched_barrier(0)
; template <class Epi>
; __device__ __forceinline__ void gemm_phase(LAS unsigned char* lds, const Gemm g, const StaticOrder& S, const Epi& E, int wave_s) {
;     ...
;             PG8_LDB(B0, 0, 0); PG8_LDB(B1, 0, 1); PG8_SCHED; PG8_LDA(At, 0, 0); PG8_STAGE(PG8_SA(1, 1), a1 + hstepA, voffA);
;             PG8_WAIT_V(8); PG8_WAIT_L(0); PG8_BAR; PG8_MMA(0, 0, At, B0); PG8_MMA(0, 1, At, B1); PG8_BAR; PG8_SCHED;
;             PG8_LDA(At, 0, 1); PG8_STAGE(PG8_SB(0, 0), b2, voffB); PG8_STAGE(PG8_SB(0, 1), b2 + hstepB, voffB); PG8_STAGE(PG8_SA(0, 0), a2, voffA);
.LBB0_1016:
	ds_read_b128 v[144:147], v151
	ds_read_b128 v[154:157], v151 offset:1024
	ds_read_b128 v[158:161], v151 offset:2048
	ds_read_b128 v[162:165], v151 offset:3072
	ds_read_b128 v[166:169], v152
	ds_read_b128 v[170:173], v152 offset:1024
	ds_read_b128 v[174:177], v152 offset:2048
	ds_read_b128 v[178:181], v152 offset:3072
	s_add_u32 s44, s42, 0xfffc0080
	s_addc_u32 s45, s43, -1
	s_cmp_eq_u32 s66, 12
	s_cselect_b32 s47, s35, s45
	s_cselect_b32 s46, s62, s44
	s_cselect_b32 s45, s31, s65
	s_cselect_b32 s44, s63, s64
	v_lshl_add_u64 v[214:215], s[42:43], 0, v[136:137]
	s_add_i32 m0, s41, 0xc000
	ds_read_b128 v[182:185], v153
	ds_read_b128 v[186:189], v153 offset:1024
	ds_read_b128 v[190:193], v153 offset:2048
	ds_read_b128 v[194:197], v153 offset:3072
	ds_read_b128 v[198:201], v153 offset:4096
	ds_read_b128 v[202:205], v153 offset:5120
	ds_read_b128 v[206:209], v153 offset:6144
	ds_read_b128 v[210:213], v153 offset:7168
	global_load_lds_dwordx4 v[214:215], off
	v_lshl_add_u64 v[214:215], s[42:43], 0, v[138:139]
	s_add_i32 m0, s41, 0xe000
	s_nop 0
	global_load_lds_dwordx4 v[214:215], off
	s_waitcnt vmcnt(8)
	s_waitcnt lgkmcnt(0)
	s_barrier
	s_waitcnt lgkmcnt(0)
	v_mfma_f32_16x16x32_bf16 v[124:127], v[144:147], v[182:185], v[124:127]
	v_mfma_f32_16x16x32_bf16 v[120:123], v[158:161], v[182:185], v[120:123]
	v_mfma_f32_16x16x32_bf16 v[108:111], v[144:147], v[190:193], v[108:111]
	v_mfma_f32_16x16x32_bf16 v[104:107], v[158:161], v[190:193], v[104:107]
	v_mfma_f32_16x16x32_bf16 v[92:95], v[144:147], v[198:201], v[92:95]
	v_mfma_f32_16x16x32_bf16 v[88:91], v[158:161], v[198:201], v[88:91]
	v_mfma_f32_16x16x32_bf16 v[76:79], v[144:147], v[206:209], v[76:79]
	v_mfma_f32_16x16x32_bf16 v[72:75], v[158:161], v[206:209], v[72:75]
	v_mfma_f32_16x16x32_bf16 v[124:127], v[154:157], v[186:189], v[124:127]
	v_mfma_f32_16x16x32_bf16 v[120:123], v[162:165], v[186:189], v[120:123]
	v_mfma_f32_16x16x32_bf16 v[108:111], v[154:157], v[194:197], v[108:111]
	v_mfma_f32_16x16x32_bf16 v[104:107], v[162:165], v[194:197], v[104:107]
	v_mfma_f32_16x16x32_bf16 v[92:95], v[154:157], v[202:205], v[92:95]
	v_mfma_f32_16x16x32_bf16 v[88:91], v[162:165], v[202:205], v[88:91]
	v_mfma_f32_16x16x32_bf16 v[76:79], v[154:157], v[210:213], v[76:79]
	v_mfma_f32_16x16x32_bf16 v[72:75], v[162:165], v[210:213], v[72:75]
	v_mfma_f32_16x16x32_bf16 v[116:119], v[166:169], v[182:185], v[116:119]
	v_mfma_f32_16x16x32_bf16 v[112:115], v[174:177], v[182:185], v[112:115]
	v_mfma_f32_16x16x32_bf16 v[100:103], v[166:169], v[190:193], v[100:103]
	v_mfma_f32_16x16x32_bf16 v[96:99], v[174:177], v[190:193], v[96:99]
	v_mfma_f32_16x16x32_bf16 v[84:87], v[166:169], v[198:201], v[84:87]
	v_mfma_f32_16x16x32_bf16 v[80:83], v[174:177], v[198:201], v[80:83]
	v_mfma_f32_16x16x32_bf16 v[68:71], v[166:169], v[206:209], v[68:71]
	v_mfma_f32_16x16x32_bf16 v[64:67], v[174:177], v[206:209], v[64:67]
	v_mfma_f32_16x16x32_bf16 v[116:119], v[170:173], v[186:189], v[116:119]
	v_mfma_f32_16x16x32_bf16 v[112:115], v[178:181], v[186:189], v[112:115]
	v_mfma_f32_16x16x32_bf16 v[100:103], v[170:173], v[194:197], v[100:103]
	v_mfma_f32_16x16x32_bf16 v[96:99], v[178:181], v[194:197], v[96:99]
	v_mfma_f32_16x16x32_bf16 v[84:87], v[170:173], v[202:205], v[84:87]
	v_mfma_f32_16x16x32_bf16 v[80:83], v[178:181], v[202:205], v[80:83]
	v_mfma_f32_16x16x32_bf16 v[68:71], v[170:173], v[210:213], v[68:71]
	v_mfma_f32_16x16x32_bf16 v[64:67], v[178:181], v[210:213], v[64:67]
	s_barrier
	s_add_i32 s67, s59, s25
	v_lshl_add_u64 v[214:215], s[44:45], 0, v[130:131]
	s_mov_b32 m0, s67
	ds_read_b128 v[182:185], v153 offset:16384
	ds_read_b128 v[186:189], v153 offset:17408
	ds_read_b128 v[190:193], v153 offset:18432
	ds_read_b128 v[194:197], v153 offset:19456
	ds_read_b128 v[198:201], v153 offset:20480
	ds_read_b128 v[202:205], v153 offset:21504
	ds_read_b128 v[206:209], v153 offset:22528
	ds_read_b128 v[210:213], v153 offset:23552
	global_load_lds_dwordx4 v[214:215], off
	s_add_i32 m0, s67, 0x2000
	s_add_u32 s68, s44, 0x40000
	v_lshl_add_u64 v[216:217], s[44:45], 0, v[134:135]
	s_addc_u32 s69, s45, 0
	s_add_i32 s67, s60, s25
	global_load_lds_dwordx4 v[216:217], off
	v_lshl_add_u64 v[218:219], s[68:69], 0, v[130:131]
	s_mov_b32 m0, s67
	v_lshl_add_u64 v[220:221], s[46:47], 0, v[132:133]
	global_load_lds_dwordx4 v[218:219], off
	v_lshl_add_u64 v[218:219], s[68:69], 0, v[134:135]
	s_add_i32 m0, s67, 0x2000
	s_nop 0
	global_load_lds_dwordx4 v[218:219], off
	v_lshl_add_u64 v[218:219], s[46:47], 0, v[128:129]
	s_mov_b32 m0, s41
	s_nop 0
	global_load_lds_dwordx4 v[218:219], off
	s_mov_b32 m0, s48
	s_nop 0
	global_load_lds_dwordx4 v[220:221], off
	s_waitcnt vmcnt(8)
	s_waitcnt lgkmcnt(0)
	s_barrier
; #define PG8_STAGE(bufoff, gbase, voff) do { _Pragma("unroll") for (int _i = 0; _i < 2; ++_i) \
;         __builtin_amdgcn_global_load_lds((const unsigned*)((const char*)(gbase) + (voff)[_i]), (LAS unsigned*)(lds + (bufoff) + ldsw + _i * 8192), 16, 0, 0); } while (0)
; #define PG8_LDA(dst, b, h) do { _Pragma("unroll") for (int m = 0; m < 4; ++m) _Pragma("unroll") for (int k = 0; k < 2; ++k) dst[m][k] = *(const LAS bf16x8*)(lds + PG8_SA(b, h) + aoff + m * 2048 + k * 1024); } while (0)
; #define PG8_LDB(dst, b, h) do { _Pragma("unroll") for (int n = 0; n < 2; ++n) _Pragma("unroll") for (int k = 0; k < 2; ++k) dst[n][k] = *(const LAS bf16x8*)(lds + PG8_SB(b, h) + boff + n * 2048 + k * 1024); } while (0)
; #define PG8_MMA(ai, bj, At, Bt) do { __builtin_amdgcn_s_setprio(1); _Pragma("unroll") for (int m = 0; m < 4; ++m) _Pragma("unroll") for (int n = 0; n < 2; ++n) _Pragma("unroll") for (int k = 0; k < 2; ++k) \
;         acc[ai][bj][m][n] = __builtin_amdgcn_mfma_f32_16x16x32_bf16(Bt[n][k], At[m][k], acc[ai][bj][m][n], 0, 0, 0); __builtin_amdgcn_s_setprio(0); } while (0)
; #define PG8_WAIT_V(n) asm volatile("s_waitcnt vmcnt(" #n ")" ::: "memory")
; #define PG8_WAIT_L(n) asm volatile("s_waitcnt lgkmcnt(" #n ")" ::: "memory")
; #define PG8_BAR __builtin_amdgcn_s_barrier()
; #define PG8_SCHED __builtin_amdgcn_sched_barrier(0)
; template <class Epi>
; __device__ __forceinline__ void gemm_phase(LAS unsigned char* lds, const Gemm g, const StaticOrder& S, const Epi& E, int wave_s) {
;     ...
;             PG8_WAIT_V(8); PG8_WAIT_L(0); PG8_BAR; PG8_MMA(1, 0, At, B0); PG8_MMA(1, 1, At, B1); PG8_BAR; PG8_SCHED;
;             PG8_LDB(B0, 1, 0); PG8_LDB(B1, 1, 1); PG8_SCHED; PG8_LDA(At, 1, 0); PG8_STAGE(PG8_SA(0, 1), a2 + hstepA, voffA);
;             PG8_WAIT_V(8); PG8_WAIT_L(0); PG8_BAR; PG8_MMA(0, 0, At, B0); PG8_MMA(0, 1, At, B1); PG8_BAR; PG8_SCHED;
	s_waitcnt lgkmcnt(0)
	v_mfma_f32_16x16x32_bf16 v[60:63], v[144:147], v[182:185], v[60:63]
	v_mfma_f32_16x16x32_bf16 v[56:59], v[158:161], v[182:185], v[56:59]
	v_mfma_f32_16x16x32_bf16 v[44:47], v[144:147], v[190:193], v[44:47]
	v_mfma_f32_16x16x32_bf16 v[40:43], v[158:161], v[190:193], v[40:43]
	v_mfma_f32_16x16x32_bf16 v[28:31], v[144:147], v[198:201], v[28:31]
	v_mfma_f32_16x16x32_bf16 v[24:27], v[158:161], v[198:201], v[24:27]
	v_mfma_f32_16x16x32_bf16 v[12:15], v[144:147], v[206:209], v[12:15]
	v_mfma_f32_16x16x32_bf16 v[8:11], v[158:161], v[206:209], v[8:11]
	v_mfma_f32_16x16x32_bf16 v[60:63], v[154:157], v[186:189], v[60:63]
	v_mfma_f32_16x16x32_bf16 v[56:59], v[162:165], v[186:189], v[56:59]
	v_mfma_f32_16x16x32_bf16 v[44:47], v[154:157], v[194:197], v[44:47]
	v_mfma_f32_16x16x32_bf16 v[40:43], v[162:165], v[194:197], v[40:43]
	v_mfma_f32_16x16x32_bf16 v[28:31], v[154:157], v[202:205], v[28:31]
	v_mfma_f32_16x16x32_bf16 v[24:27], v[162:165], v[202:205], v[24:27]
	v_mfma_f32_16x16x32_bf16 v[12:15], v[154:157], v[210:213], v[12:15]
	v_mfma_f32_16x16x32_bf16 v[8:11], v[162:165], v[210:213], v[8:11]
	v_mfma_f32_16x16x32_bf16 v[52:55], v[166:169], v[182:185], v[52:55]
	v_mfma_f32_16x16x32_bf16 v[48:51], v[174:177], v[182:185], v[48:51]
	v_mfma_f32_16x16x32_bf16 v[36:39], v[166:169], v[190:193], v[36:39]
	v_mfma_f32_16x16x32_bf16 v[32:35], v[174:177], v[190:193], v[32:35]
	v_mfma_f32_16x16x32_bf16 v[20:23], v[166:169], v[198:201], v[20:23]
	v_mfma_f32_16x16x32_bf16 v[16:19], v[174:177], v[198:201], v[16:19]
	v_mfma_f32_16x16x32_bf16 v[4:7], v[166:169], v[206:209], v[4:7]
	v_mfma_f32_16x16x32_bf16 v[0:3], v[174:177], v[206:209], v[0:3]
	v_mfma_f32_16x16x32_bf16 v[52:55], v[170:173], v[186:189], v[52:55]
	v_mfma_f32_16x16x32_bf16 v[48:51], v[178:181], v[186:189], v[48:51]
	v_mfma_f32_16x16x32_bf16 v[36:39], v[170:173], v[194:197], v[36:39]
	v_mfma_f32_16x16x32_bf16 v[32:35], v[178:181], v[194:197], v[32:35]
	v_mfma_f32_16x16x32_bf16 v[20:23], v[170:173], v[202:205], v[20:23]
	v_mfma_f32_16x16x32_bf16 v[16:19], v[178:181], v[202:205], v[16:19]
	v_mfma_f32_16x16x32_bf16 v[4:7], v[170:173], v[210:213], v[4:7]
	v_mfma_f32_16x16x32_bf16 v[0:3], v[178:181], v[210:213], v[0:3]
	s_barrier
	s_add_i32 s67, 0, 0x18000
	s_add_i32 s68, 0, 0x1c000
	v_add_u32_e32 v162, s67, v149
	v_add_u32_e32 v178, s68, v149
	ds_read_b128 v[144:147], v162
	ds_read_b128 v[154:157], v162 offset:1024
	ds_read_b128 v[158:161], v162 offset:2048
	ds_read_b128 v[162:165], v162 offset:3072
	ds_read_b128 v[166:169], v178
	ds_read_b128 v[170:173], v178 offset:1024
	ds_read_b128 v[174:177], v178 offset:2048
	ds_read_b128 v[178:181], v178 offset:3072
	s_add_u32 s46, s46, 0x40000
	s_addc_u32 s47, s47, 0
	s_mov_b32 m0, s49
	v_lshl_add_u64 v[222:223], s[46:47], 0, v[128:129]
	ds_read_b128 v[182:185], v153 offset:32768
	ds_read_b128 v[186:189], v153 offset:33792
	ds_read_b128 v[190:193], v153 offset:34816
	ds_read_b128 v[194:197], v153 offset:35840
	ds_read_b128 v[198:201], v153 offset:36864
	ds_read_b128 v[202:205], v153 offset:37888
	ds_read_b128 v[206:209], v153 offset:38912
	ds_read_b128 v[210:213], v153 offset:39936
	global_load_lds_dwordx4 v[222:223], off
	v_lshl_add_u64 v[222:223], s[46:47], 0, v[132:133]
	s_mov_b32 m0, s50
	s_nop 0
	global_load_lds_dwordx4 v[222:223], off
	s_waitcnt vmcnt(8)
	s_waitcnt lgkmcnt(0)
	s_barrier
	s_waitcnt lgkmcnt(0)
	v_mfma_f32_16x16x32_bf16 v[124:127], v[144:147], v[182:185], v[124:127]
	v_mfma_f32_16x16x32_bf16 v[120:123], v[158:161], v[182:185], v[120:123]
	v_mfma_f32_16x16x32_bf16 v[108:111], v[144:147], v[190:193], v[108:111]
	v_mfma_f32_16x16x32_bf16 v[104:107], v[158:161], v[190:193], v[104:107]
	v_mfma_f32_16x16x32_bf16 v[92:95], v[144:147], v[198:201], v[92:95]
	v_mfma_f32_16x16x32_bf16 v[88:91], v[158:161], v[198:201], v[88:91]
	v_mfma_f32_16x16x32_bf16 v[76:79], v[144:147], v[206:209], v[76:79]
	v_mfma_f32_16x16x32_bf16 v[72:75], v[158:161], v[206:209], v[72:75]
	v_mfma_f32_16x16x32_bf16 v[124:127], v[154:157], v[186:189], v[124:127]
	v_mfma_f32_16x16x32_bf16 v[120:123], v[162:165], v[186:189], v[120:123]
	v_mfma_f32_16x16x32_bf16 v[108:111], v[154:157], v[194:197], v[108:111]
	v_mfma_f32_16x16x32_bf16 v[104:107], v[162:165], v[194:197], v[104:107]
	v_mfma_f32_16x16x32_bf16 v[92:95], v[154:157], v[202:205], v[92:95]
	v_mfma_f32_16x16x32_bf16 v[88:91], v[162:165], v[202:205], v[88:91]
	v_mfma_f32_16x16x32_bf16 v[76:79], v[154:157], v[210:213], v[76:79]
	v_mfma_f32_16x16x32_bf16 v[72:75], v[162:165], v[210:213], v[72:75]
	v_mfma_f32_16x16x32_bf16 v[116:119], v[166:169], v[182:185], v[116:119]
	v_mfma_f32_16x16x32_bf16 v[112:115], v[174:177], v[182:185], v[112:115]
	v_mfma_f32_16x16x32_bf16 v[100:103], v[166:169], v[190:193], v[100:103]
	v_mfma_f32_16x16x32_bf16 v[96:99], v[174:177], v[190:193], v[96:99]
	v_mfma_f32_16x16x32_bf16 v[84:87], v[166:169], v[198:201], v[84:87]
	v_mfma_f32_16x16x32_bf16 v[80:83], v[174:177], v[198:201], v[80:83]
	v_mfma_f32_16x16x32_bf16 v[68:71], v[166:169], v[206:209], v[68:71]
	v_mfma_f32_16x16x32_bf16 v[64:67], v[174:177], v[206:209], v[64:67]
	v_mfma_f32_16x16x32_bf16 v[116:119], v[170:173], v[186:189], v[116:119]
	v_mfma_f32_16x16x32_bf16 v[112:115], v[178:181], v[186:189], v[112:115]
	v_mfma_f32_16x16x32_bf16 v[100:103], v[170:173], v[194:197], v[100:103]
	v_mfma_f32_16x16x32_bf16 v[96:99], v[178:181], v[194:197], v[96:99]
	v_mfma_f32_16x16x32_bf16 v[84:87], v[170:173], v[202:205], v[84:87]
	v_mfma_f32_16x16x32_bf16 v[80:83], v[178:181], v[202:205], v[80:83]
	v_mfma_f32_16x16x32_bf16 v[68:71], v[170:173], v[210:213], v[68:71]
	v_mfma_f32_16x16x32_bf16 v[64:67], v[178:181], v[210:213], v[64:67]
	s_barrier
; #define PG8_STAGE(bufoff, gbase, voff) do { _Pragma("unroll") for (int _i = 0; _i < 2; ++_i) \
;         __builtin_amdgcn_global_load_lds((const unsigned*)((const char*)(gbase) + (voff)[_i]), (LAS unsigned*)(lds + (bufoff) + ldsw + _i * 8192), 16, 0, 0); } while (0)
; #define PG8_LDA(dst, b, h) do { _Pragma("unroll") for (int m = 0; m < 4; ++m) _Pragma("unroll") for (int k = 0; k < 2; ++k) dst[m][k] = *(const LAS bf16x8*)(lds + PG8_SA(b, h) + aoff + m * 2048 + k * 1024); } while (0)
; #define PG8_MMA(ai, bj, At, Bt) do { __builtin_amdgcn_s_setprio(1); _Pragma("unroll") for (int m = 0; m < 4; ++m) _Pragma("unroll") for (int n = 0; n < 2; ++n) _Pragma("unroll") for (int k = 0; k < 2; ++k) \
;         acc[ai][bj][m][n] = __builtin_amdgcn_mfma_f32_16x16x32_bf16(Bt[n][k], At[m][k], acc[ai][bj][m][n], 0, 0, 0); __builtin_amdgcn_s_setprio(0); } while (0)
; #define PG8_WAIT_V(n) asm volatile("s_waitcnt vmcnt(" #n ")" ::: "memory")
; #define PG8_WAIT_L(n) asm volatile("s_waitcnt lgkmcnt(" #n ")" ::: "memory")
; #define PG8_BAR __builtin_amdgcn_s_barrier()
; #define PG8_SCHED __builtin_amdgcn_sched_barrier(0)
; template <class Epi>
; __device__ __forceinline__ void gemm_phase(LAS unsigned char* lds, const Gemm g, const StaticOrder& S, const Epi& E, int wave_s) {
;     ...
;             PG8_LDA(At, 1, 1); PG8_STAGE(PG8_SB(1, 0), b3, voffB); PG8_STAGE(PG8_SB(1, 1), b3 + hstepB, voffB); PG8_STAGE(PG8_SA(1, 0), a3, voffA);
;             PG8_WAIT_V(8); PG8_WAIT_L(0); PG8_BAR; PG8_MMA(1, 0, At, B0); PG8_MMA(1, 1, At, B1); PG8_BAR; PG8_SCHED;
;         }
	s_add_i32 s46, s67, s25
	v_lshl_add_u64 v[214:215], v[214:215], 0, s[16:17]
	s_mov_b32 m0, s46
	ds_read_b128 v[182:185], v153 offset:49152
	ds_read_b128 v[186:189], v153 offset:50176
	ds_read_b128 v[190:193], v153 offset:51200
	ds_read_b128 v[194:197], v153 offset:52224
	ds_read_b128 v[198:201], v153 offset:53248
	ds_read_b128 v[202:205], v153 offset:54272
	ds_read_b128 v[206:209], v153 offset:55296
	ds_read_b128 v[210:213], v153 offset:56320
	global_load_lds_dwordx4 v[214:215], off
	s_add_i32 m0, s46, 0x2000
	s_add_u32 s44, s44, 0x40080
	v_lshl_add_u64 v[214:215], v[216:217], 0, s[16:17]
	s_addc_u32 s45, s45, 0
	s_add_i32 s46, s68, s25
	global_load_lds_dwordx4 v[214:215], off
	v_lshl_add_u64 v[214:215], s[44:45], 0, v[130:131]
	s_mov_b32 m0, s46
	s_nop 0
	global_load_lds_dwordx4 v[214:215], off
	v_lshl_add_u64 v[214:215], s[44:45], 0, v[134:135]
	s_add_i32 m0, s46, 0x2000
	s_nop 0
	global_load_lds_dwordx4 v[214:215], off
	v_lshl_add_u64 v[214:215], v[218:219], 0, s[16:17]
	s_mov_b32 m0, s56
	s_nop 0
	global_load_lds_dwordx4 v[214:215], off
	v_lshl_add_u64 v[214:215], v[220:221], 0, s[16:17]
	s_mov_b32 m0, s57
	s_nop 0
	global_load_lds_dwordx4 v[214:215], off
	s_waitcnt vmcnt(8)
	s_waitcnt lgkmcnt(0)
	s_barrier
	s_waitcnt lgkmcnt(0)
	v_mfma_f32_16x16x32_bf16 v[60:63], v[144:147], v[182:185], v[60:63]
	v_mfma_f32_16x16x32_bf16 v[56:59], v[158:161], v[182:185], v[56:59]
	v_mfma_f32_16x16x32_bf16 v[44:47], v[144:147], v[190:193], v[44:47]
	v_mfma_f32_16x16x32_bf16 v[40:43], v[158:161], v[190:193], v[40:43]
	v_mfma_f32_16x16x32_bf16 v[28:31], v[144:147], v[198:201], v[28:31]
	v_mfma_f32_16x16x32_bf16 v[24:27], v[158:161], v[198:201], v[24:27]
	v_mfma_f32_16x16x32_bf16 v[12:15], v[144:147], v[206:209], v[12:15]
	v_mfma_f32_16x16x32_bf16 v[8:11], v[158:161], v[206:209], v[8:11]
	v_mfma_f32_16x16x32_bf16 v[60:63], v[154:157], v[186:189], v[60:63]
	v_mfma_f32_16x16x32_bf16 v[56:59], v[162:165], v[186:189], v[56:59]
	v_mfma_f32_16x16x32_bf16 v[44:47], v[154:157], v[194:197], v[44:47]
	v_mfma_f32_16x16x32_bf16 v[40:43], v[162:165], v[194:197], v[40:43]
	v_mfma_f32_16x16x32_bf16 v[28:31], v[154:157], v[202:205], v[28:31]
	v_mfma_f32_16x16x32_bf16 v[24:27], v[162:165], v[202:205], v[24:27]
	v_mfma_f32_16x16x32_bf16 v[12:15], v[154:157], v[210:213], v[12:15]
	v_mfma_f32_16x16x32_bf16 v[8:11], v[162:165], v[210:213], v[8:11]
	v_mfma_f32_16x16x32_bf16 v[52:55], v[166:169], v[182:185], v[52:55]
	v_mfma_f32_16x16x32_bf16 v[48:51], v[174:177], v[182:185], v[48:51]
	v_mfma_f32_16x16x32_bf16 v[36:39], v[166:169], v[190:193], v[36:39]
	v_mfma_f32_16x16x32_bf16 v[32:35], v[174:177], v[190:193], v[32:35]
	v_mfma_f32_16x16x32_bf16 v[20:23], v[166:169], v[198:201], v[20:23]
	v_mfma_f32_16x16x32_bf16 v[16:19], v[174:177], v[198:201], v[16:19]
	v_mfma_f32_16x16x32_bf16 v[4:7], v[166:169], v[206:209], v[4:7]
	v_mfma_f32_16x16x32_bf16 v[0:3], v[174:177], v[206:209], v[0:3]
	v_mfma_f32_16x16x32_bf16 v[52:55], v[170:173], v[186:189], v[52:55]
	v_mfma_f32_16x16x32_bf16 v[48:51], v[178:181], v[186:189], v[48:51]
	v_mfma_f32_16x16x32_bf16 v[36:39], v[170:173], v[194:197], v[36:39]
	v_mfma_f32_16x16x32_bf16 v[32:35], v[178:181], v[194:197], v[32:35]
	v_mfma_f32_16x16x32_bf16 v[20:23], v[170:173], v[202:205], v[20:23]
	v_mfma_f32_16x16x32_bf16 v[16:19], v[178:181], v[202:205], v[16:19]
	v_mfma_f32_16x16x32_bf16 v[4:7], v[170:173], v[210:213], v[4:7]
	v_mfma_f32_16x16x32_bf16 v[0:3], v[178:181], v[210:213], v[0:3]
	s_barrier
	s_add_i32 s66, s66, 2
	s_add_u32 s42, s42, 0x100
	s_addc_u32 s43, s43, 0
	s_add_u32 s64, s64, 0x100
	s_addc_u32 s65, s65, 0
	s_cmp_gt_u32 s66, 13
	s_cbranch_scc0 .LBB0_1016
	s_and_b64 vcc, exec, s[26:27]
	s_cbranch_vccz .LBB0_1019
	s_barrier

; #define PG8_STAGE(bufoff, gbase, voff) do { _Pragma("unroll") for (int _i = 0; _i < 2; ++_i) \
;         __builtin_amdgcn_global_load_lds((const unsigned*)((const char*)(gbase) + (voff)[_i]), (LAS unsigned*)(lds + (bufoff) + ldsw + _i * 8192), 16, 0, 0); } while (0)
; #define PG8_LDA(dst, b, h) do { _Pragma("unroll") for (int m = 0; m < 4; ++m) _Pragma("unroll") for (int k = 0; k < 2; ++k) dst[m][k] = *(const LAS bf16x8*)(lds + PG8_SA(b, h) + aoff + m * 2048 + k * 1024); } while (0)
; #define PG8_LDB(dst, b, h) do { _Pragma("unroll") for (int n = 0; n < 2; ++n) _Pragma("unroll") for (int k = 0; k < 2; ++k) dst[n][k] = *(const LAS bf16x8*)(lds + PG8_SB(b, h) + boff + n * 2048 + k * 1024); } while (0)
; #define PG8_MMA(ai, bj, At, Bt) do { __builtin_amdgcn_s_setprio(1); _Pragma("unroll") for (int m = 0; m < 4; ++m) _Pragma("unroll") for (int n = 0; n < 2; ++n) _Pragma("unroll") for (int k = 0; k < 2; ++k) \
;         acc[ai][bj][m][n] = __builtin_amdgcn_mfma_f32_16x16x32_bf16(Bt[n][k], At[m][k], acc[ai][bj][m][n], 0, 0, 0); __builtin_amdgcn_s_setprio(0); } while (0)
; #define PG8_WAIT_V(n) asm volatile("s_waitcnt vmcnt(" #n ")" ::: "memory")
; #define PG8_WAIT_L(n) asm volatile("s_waitcnt lgkmcnt(" #n ")" ::: "memory")
; #define PG8_BAR __builtin_amdgcn_s_barrier()
; #define PG8_SCHED __builtin_amdgcn_sched_barrier(0)
; template <class Epi>
; __device__ __forceinline__ void gemm_phase(LAS unsigned char* lds, const Gemm g, const StaticOrder& S, const Epi& E, int wave_s) {
;     ...
;             PG8_LDB(B0, 0, 0); PG8_LDB(B1, 0, 1); PG8_SCHED; PG8_LDA(At, 0, 0); PG8_STAGE(PG8_SA(1, 1), a1 + hstepA, voffA);
;             PG8_WAIT_V(8); PG8_WAIT_L(0); PG8_BAR; PG8_MMA(0, 0, At, B0); PG8_MMA(0, 1, At, B1); PG8_BAR; PG8_SCHED;
;             PG8_LDA(At, 0, 1); PG8_STAGE(PG8_SB(0, 0), b2, voffB); PG8_STAGE(PG8_SB(0, 1), b2 + hstepB, voffB); PG8_STAGE(PG8_SA(0, 0), a2, voffA);
.LBB0_1040:
	ds_read_b128 v[144:147], v151
	ds_read_b128 v[154:157], v151 offset:1024
	ds_read_b128 v[158:161], v151 offset:2048
	ds_read_b128 v[162:165], v151 offset:3072
	ds_read_b128 v[166:169], v152
	ds_read_b128 v[170:173], v152 offset:1024
	ds_read_b128 v[174:177], v152 offset:2048
	ds_read_b128 v[178:181], v152 offset:3072
	s_add_u32 s50, s48, 0xfff80080
	s_addc_u32 s51, s49, -1
	s_cmp_eq_u32 s73, 28
	s_cselect_b32 s57, s41, s51
	s_cselect_b32 s56, s69, s50
	s_cselect_b32 s51, s39, s72
	s_cselect_b32 s50, s70, s71
	v_lshl_add_u64 v[214:215], s[48:49], 0, v[136:137]
	s_add_i32 m0, s47, 0xc000
	ds_read_b128 v[182:185], v153
	ds_read_b128 v[186:189], v153 offset:1024
	ds_read_b128 v[190:193], v153 offset:2048
	ds_read_b128 v[194:197], v153 offset:3072
	ds_read_b128 v[198:201], v153 offset:4096
	ds_read_b128 v[202:205], v153 offset:5120
	ds_read_b128 v[206:209], v153 offset:6144
	ds_read_b128 v[210:213], v153 offset:7168
	global_load_lds_dwordx4 v[214:215], off
	v_lshl_add_u64 v[214:215], s[48:49], 0, v[138:139]
	s_add_i32 m0, s47, 0xe000
	s_nop 0
	global_load_lds_dwordx4 v[214:215], off
	s_waitcnt vmcnt(8)
	s_waitcnt lgkmcnt(0)
	s_barrier
	s_waitcnt lgkmcnt(0)
	v_mfma_f32_16x16x32_bf16 v[124:127], v[144:147], v[182:185], v[124:127]
	v_mfma_f32_16x16x32_bf16 v[120:123], v[158:161], v[182:185], v[120:123]
	v_mfma_f32_16x16x32_bf16 v[108:111], v[144:147], v[190:193], v[108:111]
	v_mfma_f32_16x16x32_bf16 v[104:107], v[158:161], v[190:193], v[104:107]
	v_mfma_f32_16x16x32_bf16 v[92:95], v[144:147], v[198:201], v[92:95]
	v_mfma_f32_16x16x32_bf16 v[88:91], v[158:161], v[198:201], v[88:91]
	v_mfma_f32_16x16x32_bf16 v[76:79], v[144:147], v[206:209], v[76:79]
	v_mfma_f32_16x16x32_bf16 v[72:75], v[158:161], v[206:209], v[72:75]
	v_mfma_f32_16x16x32_bf16 v[124:127], v[154:157], v[186:189], v[124:127]
	v_mfma_f32_16x16x32_bf16 v[120:123], v[162:165], v[186:189], v[120:123]
	v_mfma_f32_16x16x32_bf16 v[108:111], v[154:157], v[194:197], v[108:111]
	v_mfma_f32_16x16x32_bf16 v[104:107], v[162:165], v[194:197], v[104:107]
	v_mfma_f32_16x16x32_bf16 v[92:95], v[154:157], v[202:205], v[92:95]
	v_mfma_f32_16x16x32_bf16 v[88:91], v[162:165], v[202:205], v[88:91]
	v_mfma_f32_16x16x32_bf16 v[76:79], v[154:157], v[210:213], v[76:79]
	v_mfma_f32_16x16x32_bf16 v[72:75], v[162:165], v[210:213], v[72:75]
	v_mfma_f32_16x16x32_bf16 v[116:119], v[166:169], v[182:185], v[116:119]
	v_mfma_f32_16x16x32_bf16 v[112:115], v[174:177], v[182:185], v[112:115]
	v_mfma_f32_16x16x32_bf16 v[100:103], v[166:169], v[190:193], v[100:103]
	v_mfma_f32_16x16x32_bf16 v[96:99], v[174:177], v[190:193], v[96:99]
	v_mfma_f32_16x16x32_bf16 v[84:87], v[166:169], v[198:201], v[84:87]
	v_mfma_f32_16x16x32_bf16 v[80:83], v[174:177], v[198:201], v[80:83]
	v_mfma_f32_16x16x32_bf16 v[68:71], v[166:169], v[206:209], v[68:71]
	v_mfma_f32_16x16x32_bf16 v[64:67], v[174:177], v[206:209], v[64:67]
	v_mfma_f32_16x16x32_bf16 v[116:119], v[170:173], v[186:189], v[116:119]
	v_mfma_f32_16x16x32_bf16 v[112:115], v[178:181], v[186:189], v[112:115]
	v_mfma_f32_16x16x32_bf16 v[100:103], v[170:173], v[194:197], v[100:103]
	v_mfma_f32_16x16x32_bf16 v[96:99], v[178:181], v[194:197], v[96:99]
	v_mfma_f32_16x16x32_bf16 v[84:87], v[170:173], v[202:205], v[84:87]
	v_mfma_f32_16x16x32_bf16 v[80:83], v[178:181], v[202:205], v[80:83]
	v_mfma_f32_16x16x32_bf16 v[68:71], v[170:173], v[210:213], v[68:71]
	v_mfma_f32_16x16x32_bf16 v[64:67], v[178:181], v[210:213], v[64:67]
	s_barrier
	s_add_i32 s74, s65, s25
	v_lshl_add_u64 v[214:215], s[50:51], 0, v[130:131]
	s_mov_b32 m0, s74
	ds_read_b128 v[182:185], v153 offset:16384
	ds_read_b128 v[186:189], v153 offset:17408
	ds_read_b128 v[190:193], v153 offset:18432
	ds_read_b128 v[194:197], v153 offset:19456
	ds_read_b128 v[198:201], v153 offset:20480
	ds_read_b128 v[202:205], v153 offset:21504
	ds_read_b128 v[206:209], v153 offset:22528
	ds_read_b128 v[210:213], v153 offset:23552
	global_load_lds_dwordx4 v[214:215], off
	s_add_i32 m0, s74, 0x2000
	s_add_u32 s74, s50, 0x80000
	v_lshl_add_u64 v[216:217], s[50:51], 0, v[134:135]
	s_addc_u32 s75, s51, 0
	s_add_i32 s76, s66, s25
	global_load_lds_dwordx4 v[216:217], off
	v_lshl_add_u64 v[218:219], s[74:75], 0, v[130:131]
	s_mov_b32 m0, s76
	v_lshl_add_u64 v[220:221], s[56:57], 0, v[132:133]
	global_load_lds_dwordx4 v[218:219], off
	v_lshl_add_u64 v[218:219], s[74:75], 0, v[134:135]
	s_add_i32 m0, s76, 0x2000
	s_nop 0
	global_load_lds_dwordx4 v[218:219], off
	v_lshl_add_u64 v[218:219], s[56:57], 0, v[128:129]
	s_mov_b32 m0, s47
	s_nop 0
	global_load_lds_dwordx4 v[218:219], off
	s_mov_b32 m0, s58
	s_nop 0
	global_load_lds_dwordx4 v[220:221], off
	s_waitcnt vmcnt(8)
	s_waitcnt lgkmcnt(0)
	s_barrier
; #define PG8_STAGE(bufoff, gbase, voff) do { _Pragma("unroll") for (int _i = 0; _i < 2; ++_i) \
;         __builtin_amdgcn_global_load_lds((const unsigned*)((const char*)(gbase) + (voff)[_i]), (LAS unsigned*)(lds + (bufoff) + ldsw + _i * 8192), 16, 0, 0); } while (0)
; #define PG8_LDA(dst, b, h) do { _Pragma("unroll") for (int m = 0; m < 4; ++m) _Pragma("unroll") for (int k = 0; k < 2; ++k) dst[m][k] = *(const LAS bf16x8*)(lds + PG8_SA(b, h) + aoff + m * 2048 + k * 1024); } while (0)
; #define PG8_LDB(dst, b, h) do { _Pragma("unroll") for (int n = 0; n < 2; ++n) _Pragma("unroll") for (int k = 0; k < 2; ++k) dst[n][k] = *(const LAS bf16x8*)(lds + PG8_SB(b, h) + boff + n * 2048 + k * 1024); } while (0)
; #define PG8_MMA(ai, bj, At, Bt) do { __builtin_amdgcn_s_setprio(1); _Pragma("unroll") for (int m = 0; m < 4; ++m) _Pragma("unroll") for (int n = 0; n < 2; ++n) _Pragma("unroll") for (int k = 0; k < 2; ++k) \
;         acc[ai][bj][m][n] = __builtin_amdgcn_mfma_f32_16x16x32_bf16(Bt[n][k], At[m][k], acc[ai][bj][m][n], 0, 0, 0); __builtin_amdgcn_s_setprio(0); } while (0)
; #define PG8_WAIT_V(n) asm volatile("s_waitcnt vmcnt(" #n ")" ::: "memory")
; #define PG8_WAIT_L(n) asm volatile("s_waitcnt lgkmcnt(" #n ")" ::: "memory")
; #define PG8_BAR __builtin_amdgcn_s_barrier()
; #define PG8_SCHED __builtin_amdgcn_sched_barrier(0)
; template <class Epi>
; __device__ __forceinline__ void gemm_phase(LAS unsigned char* lds, const Gemm g, const StaticOrder& S, const Epi& E, int wave_s) {
;     ...
;             PG8_WAIT_V(8); PG8_WAIT_L(0); PG8_BAR; PG8_MMA(1, 0, At, B0); PG8_MMA(1, 1, At, B1); PG8_BAR; PG8_SCHED;
;             PG8_LDB(B0, 1, 0); PG8_LDB(B1, 1, 1); PG8_SCHED; PG8_LDA(At, 1, 0); PG8_STAGE(PG8_SA(0, 1), a2 + hstepA, voffA);
;             PG8_WAIT_V(8); PG8_WAIT_L(0); PG8_BAR; PG8_MMA(0, 0, At, B0); PG8_MMA(0, 1, At, B1); PG8_BAR; PG8_SCHED;
	s_waitcnt lgkmcnt(0)
	v_mfma_f32_16x16x32_bf16 v[60:63], v[144:147], v[182:185], v[60:63]
	v_mfma_f32_16x16x32_bf16 v[56:59], v[158:161], v[182:185], v[56:59]
	v_mfma_f32_16x16x32_bf16 v[44:47], v[144:147], v[190:193], v[44:47]
	v_mfma_f32_16x16x32_bf16 v[40:43], v[158:161], v[190:193], v[40:43]
	v_mfma_f32_16x16x32_bf16 v[28:31], v[144:147], v[198:201], v[28:31]
	v_mfma_f32_16x16x32_bf16 v[24:27], v[158:161], v[198:201], v[24:27]
	v_mfma_f32_16x16x32_bf16 v[12:15], v[144:147], v[206:209], v[12:15]
	v_mfma_f32_16x16x32_bf16 v[8:11], v[158:161], v[206:209], v[8:11]
	v_mfma_f32_16x16x32_bf16 v[60:63], v[154:157], v[186:189], v[60:63]
	v_mfma_f32_16x16x32_bf16 v[56:59], v[162:165], v[186:189], v[56:59]
	v_mfma_f32_16x16x32_bf16 v[44:47], v[154:157], v[194:197], v[44:47]
	v_mfma_f32_16x16x32_bf16 v[40:43], v[162:165], v[194:197], v[40:43]
	v_mfma_f32_16x16x32_bf16 v[28:31], v[154:157], v[202:205], v[28:31]
	v_mfma_f32_16x16x32_bf16 v[24:27], v[162:165], v[202:205], v[24:27]
	v_mfma_f32_16x16x32_bf16 v[12:15], v[154:157], v[210:213], v[12:15]
	v_mfma_f32_16x16x32_bf16 v[8:11], v[162:165], v[210:213], v[8:11]
	v_mfma_f32_16x16x32_bf16 v[52:55], v[166:169], v[182:185], v[52:55]
	v_mfma_f32_16x16x32_bf16 v[48:51], v[174:177], v[182:185], v[48:51]
	v_mfma_f32_16x16x32_bf16 v[36:39], v[166:169], v[190:193], v[36:39]
	v_mfma_f32_16x16x32_bf16 v[32:35], v[174:177], v[190:193], v[32:35]
	v_mfma_f32_16x16x32_bf16 v[20:23], v[166:169], v[198:201], v[20:23]
	v_mfma_f32_16x16x32_bf16 v[16:19], v[174:177], v[198:201], v[16:19]
	v_mfma_f32_16x16x32_bf16 v[4:7], v[166:169], v[206:209], v[4:7]
	v_mfma_f32_16x16x32_bf16 v[0:3], v[174:177], v[206:209], v[0:3]
	v_mfma_f32_16x16x32_bf16 v[52:55], v[170:173], v[186:189], v[52:55]
	v_mfma_f32_16x16x32_bf16 v[48:51], v[178:181], v[186:189], v[48:51]
	v_mfma_f32_16x16x32_bf16 v[36:39], v[170:173], v[194:197], v[36:39]
	v_mfma_f32_16x16x32_bf16 v[32:35], v[178:181], v[194:197], v[32:35]
	v_mfma_f32_16x16x32_bf16 v[20:23], v[170:173], v[202:205], v[20:23]
	v_mfma_f32_16x16x32_bf16 v[16:19], v[178:181], v[202:205], v[16:19]
	v_mfma_f32_16x16x32_bf16 v[4:7], v[170:173], v[210:213], v[4:7]
	v_mfma_f32_16x16x32_bf16 v[0:3], v[178:181], v[210:213], v[0:3]
	s_barrier
	s_add_i32 s74, 0, 0x18000
	s_add_i32 s75, 0, 0x1c000
	v_add_u32_e32 v162, s74, v149
	v_add_u32_e32 v178, s75, v149
	ds_read_b128 v[144:147], v162
	ds_read_b128 v[154:157], v162 offset:1024
	ds_read_b128 v[158:161], v162 offset:2048
	ds_read_b128 v[162:165], v162 offset:3072
	ds_read_b128 v[166:169], v178
	ds_read_b128 v[170:173], v178 offset:1024
	ds_read_b128 v[174:177], v178 offset:2048
	ds_read_b128 v[178:181], v178 offset:3072
	s_add_u32 s56, s56, 0x80000
	s_addc_u32 s57, s57, 0
	s_mov_b32 m0, s59
	v_lshl_add_u64 v[222:223], s[56:57], 0, v[128:129]
	ds_read_b128 v[182:185], v153 offset:32768
	ds_read_b128 v[186:189], v153 offset:33792
	ds_read_b128 v[190:193], v153 offset:34816
	ds_read_b128 v[194:197], v153 offset:35840
	ds_read_b128 v[198:201], v153 offset:36864
	ds_read_b128 v[202:205], v153 offset:37888
	ds_read_b128 v[206:209], v153 offset:38912
	ds_read_b128 v[210:213], v153 offset:39936
	global_load_lds_dwordx4 v[222:223], off
	v_lshl_add_u64 v[222:223], s[56:57], 0, v[132:133]
	s_mov_b32 m0, s60
	s_nop 0
	global_load_lds_dwordx4 v[222:223], off
	s_waitcnt vmcnt(8)
	s_waitcnt lgkmcnt(0)
	s_barrier
	s_waitcnt lgkmcnt(0)
	v_mfma_f32_16x16x32_bf16 v[124:127], v[144:147], v[182:185], v[124:127]
	v_mfma_f32_16x16x32_bf16 v[120:123], v[158:161], v[182:185], v[120:123]
	v_mfma_f32_16x16x32_bf16 v[108:111], v[144:147], v[190:193], v[108:111]
	v_mfma_f32_16x16x32_bf16 v[104:107], v[158:161], v[190:193], v[104:107]
	v_mfma_f32_16x16x32_bf16 v[92:95], v[144:147], v[198:201], v[92:95]
	v_mfma_f32_16x16x32_bf16 v[88:91], v[158:161], v[198:201], v[88:91]
	v_mfma_f32_16x16x32_bf16 v[76:79], v[144:147], v[206:209], v[76:79]
	v_mfma_f32_16x16x32_bf16 v[72:75], v[158:161], v[206:209], v[72:75]
	v_mfma_f32_16x16x32_bf16 v[124:127], v[154:157], v[186:189], v[124:127]
	v_mfma_f32_16x16x32_bf16 v[120:123], v[162:165], v[186:189], v[120:123]
	v_mfma_f32_16x16x32_bf16 v[108:111], v[154:157], v[194:197], v[108:111]
	v_mfma_f32_16x16x32_bf16 v[104:107], v[162:165], v[194:197], v[104:107]
	v_mfma_f32_16x16x32_bf16 v[92:95], v[154:157], v[202:205], v[92:95]
	v_mfma_f32_16x16x32_bf16 v[88:91], v[162:165], v[202:205], v[88:91]
	v_mfma_f32_16x16x32_bf16 v[76:79], v[154:157], v[210:213], v[76:79]
	v_mfma_f32_16x16x32_bf16 v[72:75], v[162:165], v[210:213], v[72:75]
	v_mfma_f32_16x16x32_bf16 v[116:119], v[166:169], v[182:185], v[116:119]
	v_mfma_f32_16x16x32_bf16 v[112:115], v[174:177], v[182:185], v[112:115]
	v_mfma_f32_16x16x32_bf16 v[100:103], v[166:169], v[190:193], v[100:103]
	v_mfma_f32_16x16x32_bf16 v[96:99], v[174:177], v[190:193], v[96:99]
	v_mfma_f32_16x16x32_bf16 v[84:87], v[166:169], v[198:201], v[84:87]
	v_mfma_f32_16x16x32_bf16 v[80:83], v[174:177], v[198:201], v[80:83]
	v_mfma_f32_16x16x32_bf16 v[68:71], v[166:169], v[206:209], v[68:71]
	v_mfma_f32_16x16x32_bf16 v[64:67], v[174:177], v[206:209], v[64:67]
	v_mfma_f32_16x16x32_bf16 v[116:119], v[170:173], v[186:189], v[116:119]
	v_mfma_f32_16x16x32_bf16 v[112:115], v[178:181], v[186:189], v[112:115]
	v_mfma_f32_16x16x32_bf16 v[100:103], v[170:173], v[194:197], v[100:103]
	v_mfma_f32_16x16x32_bf16 v[96:99], v[178:181], v[194:197], v[96:99]
	v_mfma_f32_16x16x32_bf16 v[84:87], v[170:173], v[202:205], v[84:87]
	v_mfma_f32_16x16x32_bf16 v[80:83], v[178:181], v[202:205], v[80:83]
	v_mfma_f32_16x16x32_bf16 v[68:71], v[170:173], v[210:213], v[68:71]
	v_mfma_f32_16x16x32_bf16 v[64:67], v[178:181], v[210:213], v[64:67]
	s_barrier
; #define PG8_STAGE(bufoff, gbase, voff) do { _Pragma("unroll") for (int _i = 0; _i < 2; ++_i) \
;         __builtin_amdgcn_global_load_lds((const unsigned*)((const char*)(gbase) + (voff)[_i]), (LAS unsigned*)(lds + (bufoff) + ldsw + _i * 8192), 16, 0, 0); } while (0)
; #define PG8_LDA(dst, b, h) do { _Pragma("unroll") for (int m = 0; m < 4; ++m) _Pragma("unroll") for (int k = 0; k < 2; ++k) dst[m][k] = *(const LAS bf16x8*)(lds + PG8_SA(b, h) + aoff + m * 2048 + k * 1024); } while (0)
; #define PG8_MMA(ai, bj, At, Bt) do { __builtin_amdgcn_s_setprio(1); _Pragma("unroll") for (int m = 0; m < 4; ++m) _Pragma("unroll") for (int n = 0; n < 2; ++n) _Pragma("unroll") for (int k = 0; k < 2; ++k) \
;         acc[ai][bj][m][n] = __builtin_amdgcn_mfma_f32_16x16x32_bf16(Bt[n][k], At[m][k], acc[ai][bj][m][n], 0, 0, 0); __builtin_amdgcn_s_setprio(0); } while (0)
; #define PG8_WAIT_V(n) asm volatile("s_waitcnt vmcnt(" #n ")" ::: "memory")
; #define PG8_WAIT_L(n) asm volatile("s_waitcnt lgkmcnt(" #n ")" ::: "memory")
; #define PG8_BAR __builtin_amdgcn_s_barrier()
; #define PG8_SCHED __builtin_amdgcn_sched_barrier(0)
; template <class Epi>
; __device__ __forceinline__ void gemm_phase(LAS unsigned char* lds, const Gemm g, const StaticOrder& S, const Epi& E, int wave_s) {
;     ...
;             PG8_LDA(At, 1, 1); PG8_STAGE(PG8_SB(1, 0), b3, voffB); PG8_STAGE(PG8_SB(1, 1), b3 + hstepB, voffB); PG8_STAGE(PG8_SA(1, 0), a3, voffA);
;             PG8_WAIT_V(8); PG8_WAIT_L(0); PG8_BAR; PG8_MMA(1, 0, At, B0); PG8_MMA(1, 1, At, B1); PG8_BAR; PG8_SCHED;
;         }
	s_add_i32 s56, s74, s25
	v_lshl_add_u64 v[214:215], v[214:215], 0, s[30:31]
	s_mov_b32 m0, s56
	ds_read_b128 v[182:185], v153 offset:49152
	ds_read_b128 v[186:189], v153 offset:50176
	ds_read_b128 v[190:193], v153 offset:51200
	ds_read_b128 v[194:197], v153 offset:52224
	ds_read_b128 v[198:201], v153 offset:53248
	ds_read_b128 v[202:205], v153 offset:54272
	ds_read_b128 v[206:209], v153 offset:55296
	ds_read_b128 v[210:213], v153 offset:56320
	global_load_lds_dwordx4 v[214:215], off
	s_add_i32 m0, s56, 0x2000
	s_add_u32 s50, s50, 0x80080
	v_lshl_add_u64 v[214:215], v[216:217], 0, s[30:31]
	s_addc_u32 s51, s51, 0
	s_add_i32 s56, s75, s25
	global_load_lds_dwordx4 v[214:215], off
	v_lshl_add_u64 v[214:215], s[50:51], 0, v[130:131]
	s_mov_b32 m0, s56
	s_nop 0
	global_load_lds_dwordx4 v[214:215], off
	v_lshl_add_u64 v[214:215], s[50:51], 0, v[134:135]
	s_add_i32 m0, s56, 0x2000
	s_nop 0
	global_load_lds_dwordx4 v[214:215], off
	v_lshl_add_u64 v[214:215], v[218:219], 0, s[30:31]
	s_mov_b32 m0, s62
	s_nop 0
	global_load_lds_dwordx4 v[214:215], off
	v_lshl_add_u64 v[214:215], v[220:221], 0, s[30:31]
	s_mov_b32 m0, s63
	s_nop 0
	global_load_lds_dwordx4 v[214:215], off
	s_waitcnt vmcnt(8)
	s_waitcnt lgkmcnt(0)
	s_barrier
	s_waitcnt lgkmcnt(0)
	v_mfma_f32_16x16x32_bf16 v[60:63], v[144:147], v[182:185], v[60:63]
	v_mfma_f32_16x16x32_bf16 v[56:59], v[158:161], v[182:185], v[56:59]
	v_mfma_f32_16x16x32_bf16 v[44:47], v[144:147], v[190:193], v[44:47]
	v_mfma_f32_16x16x32_bf16 v[40:43], v[158:161], v[190:193], v[40:43]
	v_mfma_f32_16x16x32_bf16 v[28:31], v[144:147], v[198:201], v[28:31]
	v_mfma_f32_16x16x32_bf16 v[24:27], v[158:161], v[198:201], v[24:27]
	v_mfma_f32_16x16x32_bf16 v[12:15], v[144:147], v[206:209], v[12:15]
	v_mfma_f32_16x16x32_bf16 v[8:11], v[158:161], v[206:209], v[8:11]
	v_mfma_f32_16x16x32_bf16 v[60:63], v[154:157], v[186:189], v[60:63]
	v_mfma_f32_16x16x32_bf16 v[56:59], v[162:165], v[186:189], v[56:59]
	v_mfma_f32_16x16x32_bf16 v[44:47], v[154:157], v[194:197], v[44:47]
	v_mfma_f32_16x16x32_bf16 v[40:43], v[162:165], v[194:197], v[40:43]
	v_mfma_f32_16x16x32_bf16 v[28:31], v[154:157], v[202:205], v[28:31]
	v_mfma_f32_16x16x32_bf16 v[24:27], v[162:165], v[202:205], v[24:27]
	v_mfma_f32_16x16x32_bf16 v[12:15], v[154:157], v[210:213], v[12:15]
	v_mfma_f32_16x16x32_bf16 v[8:11], v[162:165], v[210:213], v[8:11]
	v_mfma_f32_16x16x32_bf16 v[52:55], v[166:169], v[182:185], v[52:55]
	v_mfma_f32_16x16x32_bf16 v[48:51], v[174:177], v[182:185], v[48:51]
	v_mfma_f32_16x16x32_bf16 v[36:39], v[166:169], v[190:193], v[36:39]
	v_mfma_f32_16x16x32_bf16 v[32:35], v[174:177], v[190:193], v[32:35]
	v_mfma_f32_16x16x32_bf16 v[20:23], v[166:169], v[198:201], v[20:23]
	v_mfma_f32_16x16x32_bf16 v[16:19], v[174:177], v[198:201], v[16:19]
	v_mfma_f32_16x16x32_bf16 v[4:7], v[166:169], v[206:209], v[4:7]
	v_mfma_f32_16x16x32_bf16 v[0:3], v[174:177], v[206:209], v[0:3]
	v_mfma_f32_16x16x32_bf16 v[52:55], v[170:173], v[186:189], v[52:55]
	v_mfma_f32_16x16x32_bf16 v[48:51], v[178:181], v[186:189], v[48:51]
	v_mfma_f32_16x16x32_bf16 v[36:39], v[170:173], v[194:197], v[36:39]
	v_mfma_f32_16x16x32_bf16 v[32:35], v[178:181], v[194:197], v[32:35]
	v_mfma_f32_16x16x32_bf16 v[20:23], v[170:173], v[202:205], v[20:23]
	v_mfma_f32_16x16x32_bf16 v[16:19], v[178:181], v[202:205], v[16:19]
	v_mfma_f32_16x16x32_bf16 v[4:7], v[170:173], v[210:213], v[4:7]
	v_mfma_f32_16x16x32_bf16 v[0:3], v[178:181], v[210:213], v[0:3]
	s_barrier
	s_add_i32 s73, s73, 2
	s_add_u32 s48, s48, 0x100
	s_addc_u32 s49, s49, 0
	s_add_u32 s71, s71, 0x100
	s_addc_u32 s72, s72, 0
	s_cmp_gt_u32 s73, 29
	s_cbranch_scc0 .LBB0_1040
	s_and_b64 vcc, exec, s[34:35]
	s_cbranch_vccz .LBB0_1043
	s_barrier

; #define PG8_STAGE(bufoff, gbase, voff) do { _Pragma("unroll") for (int _i = 0; _i < 2; ++_i) \
;         __builtin_amdgcn_global_load_lds((const unsigned*)((const char*)(gbase) + (voff)[_i]), (LAS unsigned*)(lds + (bufoff) + ldsw + _i * 8192), 16, 0, 0); } while (0)
; #define PG8_LDA(dst, b, h) do { _Pragma("unroll") for (int m = 0; m < 4; ++m) _Pragma("unroll") for (int k = 0; k < 2; ++k) dst[m][k] = *(const LAS bf16x8*)(lds + PG8_SA(b, h) + aoff + m * 2048 + k * 1024); } while (0)
; #define PG8_LDB(dst, b, h) do { _Pragma("unroll") for (int n = 0; n < 2; ++n) _Pragma("unroll") for (int k = 0; k < 2; ++k) dst[n][k] = *(const LAS bf16x8*)(lds + PG8_SB(b, h) + boff + n * 2048 + k * 1024); } while (0)
; #define PG8_MMA(ai, bj, At, Bt) do { __builtin_amdgcn_s_setprio(1); _Pragma("unroll") for (int m = 0; m < 4; ++m) _Pragma("unroll") for (int n = 0; n < 2; ++n) _Pragma("unroll") for (int k = 0; k < 2; ++k) \
;         acc[ai][bj][m][n] = __builtin_amdgcn_mfma_f32_16x16x32_bf16(Bt[n][k], At[m][k], acc[ai][bj][m][n], 0, 0, 0); __builtin_amdgcn_s_setprio(0); } while (0)
; #define PG8_WAIT_V(n) asm volatile("s_waitcnt vmcnt(" #n ")" ::: "memory")
; #define PG8_WAIT_L(n) asm volatile("s_waitcnt lgkmcnt(" #n ")" ::: "memory")
; #define PG8_BAR __builtin_amdgcn_s_barrier()
; #define PG8_SCHED __builtin_amdgcn_sched_barrier(0)
; template <class Epi>
; __device__ __forceinline__ void gemm_phase(LAS unsigned char* lds, const Gemm g, const StaticOrder& S, const Epi& E, int wave_s) {
;     ...
;             PG8_LDB(B0, 0, 0); PG8_LDB(B1, 0, 1); PG8_SCHED; PG8_LDA(At, 0, 0); PG8_STAGE(PG8_SA(1, 1), a1 + hstepA, voffA);
;             PG8_WAIT_V(8); PG8_WAIT_L(0); PG8_BAR; PG8_MMA(0, 0, At, B0); PG8_MMA(0, 1, At, B1); PG8_BAR; PG8_SCHED;
;             PG8_LDA(At, 0, 1); PG8_STAGE(PG8_SB(0, 0), b2, voffB); PG8_STAGE(PG8_SB(0, 1), b2 + hstepB, voffB); PG8_STAGE(PG8_SA(0, 0), a2, voffA);
.LBB0_1101:
	ds_read_b128 v[146:149], v157
	ds_read_b128 v[150:153], v157 offset:1024
	ds_read_b128 v[160:163], v157 offset:2048
	ds_read_b128 v[164:167], v157 offset:3072
	ds_read_b128 v[168:171], v158
	ds_read_b128 v[172:175], v158 offset:1024
	ds_read_b128 v[176:179], v158 offset:2048
	ds_read_b128 v[180:183], v158 offset:3072
	s_add_u32 s42, s40, 0xfff80080
	s_addc_u32 s43, s41, -1
	s_cmp_eq_u32 s64, 28
	s_cselect_b32 s45, s29, s43
	s_cselect_b32 s44, s37, s42
	s_cselect_b32 s43, s27, s63
	s_cselect_b32 s42, s39, s62
	v_lshl_add_u64 v[216:217], s[40:41], 0, v[138:139]
	s_add_i32 m0, s25, 0xc000
	ds_read_b128 v[184:187], v159
	ds_read_b128 v[188:191], v159 offset:1024
	ds_read_b128 v[192:195], v159 offset:2048
	ds_read_b128 v[196:199], v159 offset:3072
	ds_read_b128 v[200:203], v159 offset:4096
	ds_read_b128 v[204:207], v159 offset:5120
	ds_read_b128 v[208:211], v159 offset:6144
	ds_read_b128 v[212:215], v159 offset:7168
	global_load_lds_dwordx4 v[216:217], off
	v_lshl_add_u64 v[216:217], s[40:41], 0, v[140:141]
	s_add_i32 m0, s25, 0xe000
	s_nop 0
	global_load_lds_dwordx4 v[216:217], off
	s_waitcnt vmcnt(8)
	s_waitcnt lgkmcnt(0)
	s_barrier
	s_waitcnt lgkmcnt(0)
	v_mfma_f32_16x16x32_bf16 v[124:127], v[146:149], v[184:187], v[124:127]
	v_mfma_f32_16x16x32_bf16 v[120:123], v[160:163], v[184:187], v[120:123]
	v_mfma_f32_16x16x32_bf16 v[108:111], v[146:149], v[192:195], v[108:111]
	v_mfma_f32_16x16x32_bf16 v[104:107], v[160:163], v[192:195], v[104:107]
	v_mfma_f32_16x16x32_bf16 v[92:95], v[146:149], v[200:203], v[92:95]
	v_mfma_f32_16x16x32_bf16 v[88:91], v[160:163], v[200:203], v[88:91]
	v_mfma_f32_16x16x32_bf16 v[76:79], v[146:149], v[208:211], v[76:79]
	v_mfma_f32_16x16x32_bf16 v[72:75], v[160:163], v[208:211], v[72:75]
	v_mfma_f32_16x16x32_bf16 v[124:127], v[150:153], v[188:191], v[124:127]
	v_mfma_f32_16x16x32_bf16 v[120:123], v[164:167], v[188:191], v[120:123]
	v_mfma_f32_16x16x32_bf16 v[108:111], v[150:153], v[196:199], v[108:111]
	v_mfma_f32_16x16x32_bf16 v[104:107], v[164:167], v[196:199], v[104:107]
	v_mfma_f32_16x16x32_bf16 v[92:95], v[150:153], v[204:207], v[92:95]
	v_mfma_f32_16x16x32_bf16 v[88:91], v[164:167], v[204:207], v[88:91]
	v_mfma_f32_16x16x32_bf16 v[76:79], v[150:153], v[212:215], v[76:79]
	v_mfma_f32_16x16x32_bf16 v[72:75], v[164:167], v[212:215], v[72:75]
	v_mfma_f32_16x16x32_bf16 v[116:119], v[168:171], v[184:187], v[116:119]
	v_mfma_f32_16x16x32_bf16 v[112:115], v[176:179], v[184:187], v[112:115]
	v_mfma_f32_16x16x32_bf16 v[100:103], v[168:171], v[192:195], v[100:103]
	v_mfma_f32_16x16x32_bf16 v[96:99], v[176:179], v[192:195], v[96:99]
	v_mfma_f32_16x16x32_bf16 v[84:87], v[168:171], v[200:203], v[84:87]
	v_mfma_f32_16x16x32_bf16 v[80:83], v[176:179], v[200:203], v[80:83]
	v_mfma_f32_16x16x32_bf16 v[68:71], v[168:171], v[208:211], v[68:71]
	v_mfma_f32_16x16x32_bf16 v[64:67], v[176:179], v[208:211], v[64:67]
	v_mfma_f32_16x16x32_bf16 v[116:119], v[172:175], v[188:191], v[116:119]
	v_mfma_f32_16x16x32_bf16 v[112:115], v[180:183], v[188:191], v[112:115]
	v_mfma_f32_16x16x32_bf16 v[100:103], v[172:175], v[196:199], v[100:103]
	v_mfma_f32_16x16x32_bf16 v[96:99], v[180:183], v[196:199], v[96:99]
	v_mfma_f32_16x16x32_bf16 v[84:87], v[172:175], v[204:207], v[84:87]
	v_mfma_f32_16x16x32_bf16 v[80:83], v[180:183], v[204:207], v[80:83]
	v_mfma_f32_16x16x32_bf16 v[68:71], v[172:175], v[212:215], v[68:71]
	v_mfma_f32_16x16x32_bf16 v[64:67], v[180:183], v[212:215], v[64:67]
	s_barrier
	s_add_i32 s65, s59, s3
	v_lshl_add_u64 v[216:217], s[42:43], 0, v[130:131]
	s_mov_b32 m0, s65
	ds_read_b128 v[184:187], v159 offset:16384
	ds_read_b128 v[188:191], v159 offset:17408
	ds_read_b128 v[192:195], v159 offset:18432
	ds_read_b128 v[196:199], v159 offset:19456
	ds_read_b128 v[200:203], v159 offset:20480
	ds_read_b128 v[204:207], v159 offset:21504
	ds_read_b128 v[208:211], v159 offset:22528
	ds_read_b128 v[212:215], v159 offset:23552
	global_load_lds_dwordx4 v[216:217], off
	s_add_i32 m0, s65, 0x2000
	s_add_u32 s66, s42, 0x80000
	v_lshl_add_u64 v[218:219], s[42:43], 0, v[134:135]
	s_addc_u32 s67, s43, 0
	s_add_i32 s65, s60, s3
	global_load_lds_dwordx4 v[218:219], off
	v_lshl_add_u64 v[220:221], s[66:67], 0, v[130:131]
	s_mov_b32 m0, s65
	v_lshl_add_u64 v[222:223], s[44:45], 0, v[132:133]
	global_load_lds_dwordx4 v[220:221], off
	v_lshl_add_u64 v[220:221], s[66:67], 0, v[134:135]
	s_add_i32 m0, s65, 0x2000
	s_nop 0
	global_load_lds_dwordx4 v[220:221], off
	v_lshl_add_u64 v[220:221], s[44:45], 0, v[128:129]
	s_mov_b32 m0, s25
	s_nop 0
	global_load_lds_dwordx4 v[220:221], off
	s_mov_b32 m0, s46
	s_nop 0
	global_load_lds_dwordx4 v[222:223], off
	s_waitcnt vmcnt(8)
	s_waitcnt lgkmcnt(0)
	s_barrier
; #define PG8_STAGE(bufoff, gbase, voff) do { _Pragma("unroll") for (int _i = 0; _i < 2; ++_i) \
;         __builtin_amdgcn_global_load_lds((const unsigned*)((const char*)(gbase) + (voff)[_i]), (LAS unsigned*)(lds + (bufoff) + ldsw + _i * 8192), 16, 0, 0); } while (0)
; #define PG8_LDA(dst, b, h) do { _Pragma("unroll") for (int m = 0; m < 4; ++m) _Pragma("unroll") for (int k = 0; k < 2; ++k) dst[m][k] = *(const LAS bf16x8*)(lds + PG8_SA(b, h) + aoff + m * 2048 + k * 1024); } while (0)
; #define PG8_LDB(dst, b, h) do { _Pragma("unroll") for (int n = 0; n < 2; ++n) _Pragma("unroll") for (int k = 0; k < 2; ++k) dst[n][k] = *(const LAS bf16x8*)(lds + PG8_SB(b, h) + boff + n * 2048 + k * 1024); } while (0)
; #define PG8_MMA(ai, bj, At, Bt) do { __builtin_amdgcn_s_setprio(1); _Pragma("unroll") for (int m = 0; m < 4; ++m) _Pragma("unroll") for (int n = 0; n < 2; ++n) _Pragma("unroll") for (int k = 0; k < 2; ++k) \
;         acc[ai][bj][m][n] = __builtin_amdgcn_mfma_f32_16x16x32_bf16(Bt[n][k], At[m][k], acc[ai][bj][m][n], 0, 0, 0); __builtin_amdgcn_s_setprio(0); } while (0)
; #define PG8_WAIT_V(n) asm volatile("s_waitcnt vmcnt(" #n ")" ::: "memory")
; #define PG8_WAIT_L(n) asm volatile("s_waitcnt lgkmcnt(" #n ")" ::: "memory")
; #define PG8_BAR __builtin_amdgcn_s_barrier()
; #define PG8_SCHED __builtin_amdgcn_sched_barrier(0)
; template <class Epi>
; __device__ __forceinline__ void gemm_phase(LAS unsigned char* lds, const Gemm g, const StaticOrder& S, const Epi& E, int wave_s) {
;     ...
;             PG8_WAIT_V(8); PG8_WAIT_L(0); PG8_BAR; PG8_MMA(1, 0, At, B0); PG8_MMA(1, 1, At, B1); PG8_BAR; PG8_SCHED;
;             PG8_LDB(B0, 1, 0); PG8_LDB(B1, 1, 1); PG8_SCHED; PG8_LDA(At, 1, 0); PG8_STAGE(PG8_SA(0, 1), a2 + hstepA, voffA);
;             PG8_WAIT_V(8); PG8_WAIT_L(0); PG8_BAR; PG8_MMA(0, 0, At, B0); PG8_MMA(0, 1, At, B1); PG8_BAR; PG8_SCHED;
	s_waitcnt lgkmcnt(0)
	v_mfma_f32_16x16x32_bf16 v[60:63], v[146:149], v[184:187], v[60:63]
	v_mfma_f32_16x16x32_bf16 v[56:59], v[160:163], v[184:187], v[56:59]
	v_mfma_f32_16x16x32_bf16 v[44:47], v[146:149], v[192:195], v[44:47]
	v_mfma_f32_16x16x32_bf16 v[40:43], v[160:163], v[192:195], v[40:43]
	v_mfma_f32_16x16x32_bf16 v[28:31], v[146:149], v[200:203], v[28:31]
	v_mfma_f32_16x16x32_bf16 v[24:27], v[160:163], v[200:203], v[24:27]
	v_mfma_f32_16x16x32_bf16 v[12:15], v[146:149], v[208:211], v[12:15]
	v_mfma_f32_16x16x32_bf16 v[8:11], v[160:163], v[208:211], v[8:11]
	v_mfma_f32_16x16x32_bf16 v[60:63], v[150:153], v[188:191], v[60:63]
	v_mfma_f32_16x16x32_bf16 v[56:59], v[164:167], v[188:191], v[56:59]
	v_mfma_f32_16x16x32_bf16 v[44:47], v[150:153], v[196:199], v[44:47]
	v_mfma_f32_16x16x32_bf16 v[40:43], v[164:167], v[196:199], v[40:43]
	v_mfma_f32_16x16x32_bf16 v[28:31], v[150:153], v[204:207], v[28:31]
	v_mfma_f32_16x16x32_bf16 v[24:27], v[164:167], v[204:207], v[24:27]
	v_mfma_f32_16x16x32_bf16 v[12:15], v[150:153], v[212:215], v[12:15]
	v_mfma_f32_16x16x32_bf16 v[8:11], v[164:167], v[212:215], v[8:11]
	v_mfma_f32_16x16x32_bf16 v[52:55], v[168:171], v[184:187], v[52:55]
	v_mfma_f32_16x16x32_bf16 v[48:51], v[176:179], v[184:187], v[48:51]
	v_mfma_f32_16x16x32_bf16 v[36:39], v[168:171], v[192:195], v[36:39]
	v_mfma_f32_16x16x32_bf16 v[32:35], v[176:179], v[192:195], v[32:35]
	v_mfma_f32_16x16x32_bf16 v[20:23], v[168:171], v[200:203], v[20:23]
	v_mfma_f32_16x16x32_bf16 v[16:19], v[176:179], v[200:203], v[16:19]
	v_mfma_f32_16x16x32_bf16 v[4:7], v[168:171], v[208:211], v[4:7]
	v_mfma_f32_16x16x32_bf16 v[0:3], v[176:179], v[208:211], v[0:3]
	v_mfma_f32_16x16x32_bf16 v[52:55], v[172:175], v[188:191], v[52:55]
	v_mfma_f32_16x16x32_bf16 v[48:51], v[180:183], v[188:191], v[48:51]
	v_mfma_f32_16x16x32_bf16 v[36:39], v[172:175], v[196:199], v[36:39]
	v_mfma_f32_16x16x32_bf16 v[32:35], v[180:183], v[196:199], v[32:35]
	v_mfma_f32_16x16x32_bf16 v[20:23], v[172:175], v[204:207], v[20:23]
	v_mfma_f32_16x16x32_bf16 v[16:19], v[180:183], v[204:207], v[16:19]
	v_mfma_f32_16x16x32_bf16 v[4:7], v[172:175], v[212:215], v[4:7]
	v_mfma_f32_16x16x32_bf16 v[0:3], v[180:183], v[212:215], v[0:3]
	s_barrier
	s_add_i32 s65, 0, 0x18000
	v_add_u32_e32 v136, s65, v155
	s_add_i32 s66, 0, 0x1c000
	ds_read_b128 v[146:149], v136
	ds_read_b128 v[150:153], v136 offset:1024
	ds_read_b128 v[160:163], v136 offset:2048
	ds_read_b128 v[164:167], v136 offset:3072
	v_add_u32_e32 v136, s66, v155
	ds_read_b128 v[168:171], v136
	ds_read_b128 v[172:175], v136 offset:1024
	ds_read_b128 v[176:179], v136 offset:2048
	ds_read_b128 v[180:183], v136 offset:3072
	s_add_u32 s44, s44, 0x80000
	s_addc_u32 s45, s45, 0
	s_mov_b32 m0, s47
	v_lshl_add_u64 v[224:225], s[44:45], 0, v[128:129]
	ds_read_b128 v[184:187], v159 offset:32768
	ds_read_b128 v[188:191], v159 offset:33792
	ds_read_b128 v[192:195], v159 offset:34816
	ds_read_b128 v[196:199], v159 offset:35840
	ds_read_b128 v[200:203], v159 offset:36864
	ds_read_b128 v[204:207], v159 offset:37888
	ds_read_b128 v[208:211], v159 offset:38912
	ds_read_b128 v[212:215], v159 offset:39936
	global_load_lds_dwordx4 v[224:225], off
	v_lshl_add_u64 v[224:225], s[44:45], 0, v[132:133]
	s_mov_b32 m0, s48
	s_nop 0
	global_load_lds_dwordx4 v[224:225], off
	s_waitcnt vmcnt(8)
	s_waitcnt lgkmcnt(0)
	s_barrier
	s_waitcnt lgkmcnt(0)
	v_mfma_f32_16x16x32_bf16 v[124:127], v[146:149], v[184:187], v[124:127]
	v_mfma_f32_16x16x32_bf16 v[120:123], v[160:163], v[184:187], v[120:123]
	v_mfma_f32_16x16x32_bf16 v[108:111], v[146:149], v[192:195], v[108:111]
	v_mfma_f32_16x16x32_bf16 v[104:107], v[160:163], v[192:195], v[104:107]
	v_mfma_f32_16x16x32_bf16 v[92:95], v[146:149], v[200:203], v[92:95]
	v_mfma_f32_16x16x32_bf16 v[88:91], v[160:163], v[200:203], v[88:91]
	v_mfma_f32_16x16x32_bf16 v[76:79], v[146:149], v[208:211], v[76:79]
	v_mfma_f32_16x16x32_bf16 v[72:75], v[160:163], v[208:211], v[72:75]
	v_mfma_f32_16x16x32_bf16 v[124:127], v[150:153], v[188:191], v[124:127]
	v_mfma_f32_16x16x32_bf16 v[120:123], v[164:167], v[188:191], v[120:123]
	v_mfma_f32_16x16x32_bf16 v[108:111], v[150:153], v[196:199], v[108:111]
	v_mfma_f32_16x16x32_bf16 v[104:107], v[164:167], v[196:199], v[104:107]
	v_mfma_f32_16x16x32_bf16 v[92:95], v[150:153], v[204:207], v[92:95]
	v_mfma_f32_16x16x32_bf16 v[88:91], v[164:167], v[204:207], v[88:91]
	v_mfma_f32_16x16x32_bf16 v[76:79], v[150:153], v[212:215], v[76:79]
	v_mfma_f32_16x16x32_bf16 v[72:75], v[164:167], v[212:215], v[72:75]
	v_mfma_f32_16x16x32_bf16 v[116:119], v[168:171], v[184:187], v[116:119]
	v_mfma_f32_16x16x32_bf16 v[112:115], v[176:179], v[184:187], v[112:115]
	v_mfma_f32_16x16x32_bf16 v[100:103], v[168:171], v[192:195], v[100:103]
	v_mfma_f32_16x16x32_bf16 v[96:99], v[176:179], v[192:195], v[96:99]
	v_mfma_f32_16x16x32_bf16 v[84:87], v[168:171], v[200:203], v[84:87]
	v_mfma_f32_16x16x32_bf16 v[80:83], v[176:179], v[200:203], v[80:83]
	v_mfma_f32_16x16x32_bf16 v[68:71], v[168:171], v[208:211], v[68:71]
	v_mfma_f32_16x16x32_bf16 v[64:67], v[176:179], v[208:211], v[64:67]
	v_mfma_f32_16x16x32_bf16 v[116:119], v[172:175], v[188:191], v[116:119]
	v_mfma_f32_16x16x32_bf16 v[112:115], v[180:183], v[188:191], v[112:115]
	v_mfma_f32_16x16x32_bf16 v[100:103], v[172:175], v[196:199], v[100:103]
	v_mfma_f32_16x16x32_bf16 v[96:99], v[180:183], v[196:199], v[96:99]
	v_mfma_f32_16x16x32_bf16 v[84:87], v[172:175], v[204:207], v[84:87]
	v_mfma_f32_16x16x32_bf16 v[80:83], v[180:183], v[204:207], v[80:83]
	v_mfma_f32_16x16x32_bf16 v[68:71], v[172:175], v[212:215], v[68:71]
	v_mfma_f32_16x16x32_bf16 v[64:67], v[180:183], v[212:215], v[64:67]
	s_barrier
; #define PG8_STAGE(bufoff, gbase, voff) do { _Pragma("unroll") for (int _i = 0; _i < 2; ++_i) \
;         __builtin_amdgcn_global_load_lds((const unsigned*)((const char*)(gbase) + (voff)[_i]), (LAS unsigned*)(lds + (bufoff) + ldsw + _i * 8192), 16, 0, 0); } while (0)
; #define PG8_LDA(dst, b, h) do { _Pragma("unroll") for (int m = 0; m < 4; ++m) _Pragma("unroll") for (int k = 0; k < 2; ++k) dst[m][k] = *(const LAS bf16x8*)(lds + PG8_SA(b, h) + aoff + m * 2048 + k * 1024); } while (0)
; #define PG8_MMA(ai, bj, At, Bt) do { __builtin_amdgcn_s_setprio(1); _Pragma("unroll") for (int m = 0; m < 4; ++m) _Pragma("unroll") for (int n = 0; n < 2; ++n) _Pragma("unroll") for (int k = 0; k < 2; ++k) \
;         acc[ai][bj][m][n] = __builtin_amdgcn_mfma_f32_16x16x32_bf16(Bt[n][k], At[m][k], acc[ai][bj][m][n], 0, 0, 0); __builtin_amdgcn_s_setprio(0); } while (0)
; #define PG8_WAIT_V(n) asm volatile("s_waitcnt vmcnt(" #n ")" ::: "memory")
; #define PG8_WAIT_L(n) asm volatile("s_waitcnt lgkmcnt(" #n ")" ::: "memory")
; #define PG8_BAR __builtin_amdgcn_s_barrier()
; #define PG8_SCHED __builtin_amdgcn_sched_barrier(0)
; template <class Epi>
; __device__ __forceinline__ void gemm_phase(LAS unsigned char* lds, const Gemm g, const StaticOrder& S, const Epi& E, int wave_s) {
;     ...
;             PG8_LDA(At, 1, 1); PG8_STAGE(PG8_SB(1, 0), b3, voffB); PG8_STAGE(PG8_SB(1, 1), b3 + hstepB, voffB); PG8_STAGE(PG8_SA(1, 0), a3, voffA);
;             PG8_WAIT_V(8); PG8_WAIT_L(0); PG8_BAR; PG8_MMA(1, 0, At, B0); PG8_MMA(1, 1, At, B1); PG8_BAR; PG8_SCHED;
;         }
	s_add_i32 s44, s65, s3
	v_lshl_add_u64 v[216:217], v[216:217], 0, s[14:15]
	s_mov_b32 m0, s44
	ds_read_b128 v[184:187], v159 offset:49152
	ds_read_b128 v[188:191], v159 offset:50176
	ds_read_b128 v[192:195], v159 offset:51200
	ds_read_b128 v[196:199], v159 offset:52224
	ds_read_b128 v[200:203], v159 offset:53248
	ds_read_b128 v[204:207], v159 offset:54272
	ds_read_b128 v[208:211], v159 offset:55296
	ds_read_b128 v[212:215], v159 offset:56320
	global_load_lds_dwordx4 v[216:217], off
	s_add_i32 m0, s44, 0x2000
	s_add_u32 s42, s42, 0x80080
	v_lshl_add_u64 v[216:217], v[218:219], 0, s[14:15]
	s_addc_u32 s43, s43, 0
	s_add_i32 s44, s66, s3
	global_load_lds_dwordx4 v[216:217], off
	v_lshl_add_u64 v[216:217], s[42:43], 0, v[130:131]
	s_mov_b32 m0, s44
	s_nop 0
	global_load_lds_dwordx4 v[216:217], off
	v_lshl_add_u64 v[216:217], s[42:43], 0, v[134:135]
	s_add_i32 m0, s44, 0x2000
	s_nop 0
	global_load_lds_dwordx4 v[216:217], off
	v_lshl_add_u64 v[216:217], v[220:221], 0, s[14:15]
	s_mov_b32 m0, s51
	s_nop 0
	global_load_lds_dwordx4 v[216:217], off
	v_lshl_add_u64 v[216:217], v[222:223], 0, s[14:15]
	s_mov_b32 m0, s56
	s_nop 0
	global_load_lds_dwordx4 v[216:217], off
	s_waitcnt vmcnt(8)
	s_waitcnt lgkmcnt(0)
	s_barrier
	s_waitcnt lgkmcnt(0)
	v_mfma_f32_16x16x32_bf16 v[60:63], v[146:149], v[184:187], v[60:63]
	v_mfma_f32_16x16x32_bf16 v[56:59], v[160:163], v[184:187], v[56:59]
	v_mfma_f32_16x16x32_bf16 v[44:47], v[146:149], v[192:195], v[44:47]
	v_mfma_f32_16x16x32_bf16 v[40:43], v[160:163], v[192:195], v[40:43]
	v_mfma_f32_16x16x32_bf16 v[28:31], v[146:149], v[200:203], v[28:31]
	v_mfma_f32_16x16x32_bf16 v[24:27], v[160:163], v[200:203], v[24:27]
	v_mfma_f32_16x16x32_bf16 v[12:15], v[146:149], v[208:211], v[12:15]
	v_mfma_f32_16x16x32_bf16 v[8:11], v[160:163], v[208:211], v[8:11]
	v_mfma_f32_16x16x32_bf16 v[60:63], v[150:153], v[188:191], v[60:63]
	v_mfma_f32_16x16x32_bf16 v[56:59], v[164:167], v[188:191], v[56:59]
	v_mfma_f32_16x16x32_bf16 v[44:47], v[150:153], v[196:199], v[44:47]
	v_mfma_f32_16x16x32_bf16 v[40:43], v[164:167], v[196:199], v[40:43]
	v_mfma_f32_16x16x32_bf16 v[28:31], v[150:153], v[204:207], v[28:31]
	v_mfma_f32_16x16x32_bf16 v[24:27], v[164:167], v[204:207], v[24:27]
	v_mfma_f32_16x16x32_bf16 v[12:15], v[150:153], v[212:215], v[12:15]
	v_mfma_f32_16x16x32_bf16 v[8:11], v[164:167], v[212:215], v[8:11]
	v_mfma_f32_16x16x32_bf16 v[52:55], v[168:171], v[184:187], v[52:55]
	v_mfma_f32_16x16x32_bf16 v[48:51], v[176:179], v[184:187], v[48:51]
	v_mfma_f32_16x16x32_bf16 v[36:39], v[168:171], v[192:195], v[36:39]
	v_mfma_f32_16x16x32_bf16 v[32:35], v[176:179], v[192:195], v[32:35]
	v_mfma_f32_16x16x32_bf16 v[20:23], v[168:171], v[200:203], v[20:23]
	v_mfma_f32_16x16x32_bf16 v[16:19], v[176:179], v[200:203], v[16:19]
	v_mfma_f32_16x16x32_bf16 v[4:7], v[168:171], v[208:211], v[4:7]
	v_mfma_f32_16x16x32_bf16 v[0:3], v[176:179], v[208:211], v[0:3]
	v_mfma_f32_16x16x32_bf16 v[52:55], v[172:175], v[188:191], v[52:55]
	v_mfma_f32_16x16x32_bf16 v[48:51], v[180:183], v[188:191], v[48:51]
	v_mfma_f32_16x16x32_bf16 v[36:39], v[172:175], v[196:199], v[36:39]
	v_mfma_f32_16x16x32_bf16 v[32:35], v[180:183], v[196:199], v[32:35]
	v_mfma_f32_16x16x32_bf16 v[20:23], v[172:175], v[204:207], v[20:23]
	v_mfma_f32_16x16x32_bf16 v[16:19], v[180:183], v[204:207], v[16:19]
	v_mfma_f32_16x16x32_bf16 v[4:7], v[172:175], v[212:215], v[4:7]
	v_mfma_f32_16x16x32_bf16 v[0:3], v[180:183], v[212:215], v[0:3]
	s_barrier
	s_add_i32 s64, s64, 2
	s_add_u32 s40, s40, 0x100
	s_addc_u32 s41, s41, 0
	s_add_u32 s62, s62, 0x100
	s_addc_u32 s63, s63, 0
	s_cmp_gt_u32 s64, 29
	s_cbranch_scc0 .LBB0_1101
	s_and_b64 vcc, exec, s[16:17]
	s_cbranch_vccz .LBB0_1104
	s_barrier

; __device__ __forceinline__ unsigned pk2(float lo, float hi) { const f32x2_t v = {lo, hi}; const bf16x2_t b = __builtin_convertvector(v, bf16x2_t); return __builtin_bit_cast(unsigned, b); }
; __device__ __forceinline__ float bflo(unsigned w) { return __uint_as_float(w << 16); }
; __device__ __forceinline__ float bfhi(unsigned w) { return __uint_as_float(w & 0xffff0000u); }
; __device__ __forceinline__ void rms_row_b2b(const bf16_t* xrow, const float* g, bf16_t* orow, int lane) {
;     const u32x4* xr = (const u32x4*)xrow + lane; u32x4 w[4]; float s = 0.f;
; #pragma unroll
;     for (int j = 0; j < 4; ++j) { w[j] = xr[64 * j];
;         const float a0 = bflo(w[j].x), a1 = bfhi(w[j].x), a2 = bflo(w[j].y), a3 = bfhi(w[j].y), a4 = bflo(w[j].z), a5 = bfhi(w[j].z), a6 = bflo(w[j].w), a7 = bfhi(w[j].w);
;         s += ((a0 * a0 + a1 * a1) + (a2 * a2 + a3 * a3)) + ((a4 * a4 + a5 * a5) + (a6 * a6 + a7 * a7)); }
;     const float rstd = rsqrtf(wave_sum(s) * (1.f / DM) + EPS);
;     u32x4* o = (u32x4*)orow + lane;
; #pragma unroll
;     for (int j = 0; j < 4; ++j) { const f32x4 g0 = ((const f32x4*)g)[(64 * j + lane) * 2], g1 = ((const f32x4*)g)[(64 * j + lane) * 2 + 1]; u32x4 r;
;         r.x = pk2(bflo(w[j].x) * rstd * g0.x, bfhi(w[j].x) * rstd * g0.y); r.y = pk2(bflo(w[j].y) * rstd * g0.z, bfhi(w[j].y) * rstd * g0.w);
;         r.z = pk2(bflo(w[j].z) * rstd * g1.x, bfhi(w[j].z) * rstd * g1.y); r.w = pk2(bflo(w[j].w) * rstd * g1.z, bfhi(w[j].w) * rstd * g1.w); o[64 * j] = r; }
; }
; __global__ void __launch_bounds__(512, 2) mega(Params p) {
;     ...
;         const int tid = opaque_tid(wave_s), lane = tid & 63, wave = tid >> 6;
;         const int gw = bx * 8 + wave, NGW = G * 8;
;         for (int m = gw; m < MT; m += NGW) rms_row_b2b((const bf16_t*)(ws + WS_X1) + (size_t)m * DM, p.in[18], (bf16_t*)(ws + WS_H2) + (size_t)m * DM, lane);
.LBB0_1174:
	s_setprio 0
	s_cmp_lt_i32 s18, 7
	s_cselect_b64 s[4:5], -1, 0
	s_and_b64 s[4:5], s[4:5], s[0:1]
	s_andn2_b64 vcc, exec, s[4:5]
	s_cbranch_vccnz .LBB0_1179
	s_mov_b64 exec, -1
	v_mbcnt_lo_u32_b32 v0, -1, 0
	v_mbcnt_hi_u32_b32 v0, -1, v0
	s_lshr_b32 s84, s24, 6
	s_lshl_b32 s85, s2, 3
	s_add_i32 s85, s85, s84
	v_readlane_b32 s86, v254, 4
	v_readlane_b32 s87, v254, 5
	v_lshlrev_b32_e32 v1, 5, v0
	v_add_u32_e32 v2, 0x1000, v1
	v_lshlrev_b32_e32 v3, 4, v0
	s_nop 2
	global_load_dwordx4 v[64:67], v1, s[86:87]
	global_load_dwordx4 v[68:71], v1, s[86:87] offset:16
	global_load_dwordx4 v[72:75], v1, s[86:87] offset:2048
	global_load_dwordx4 v[76:79], v1, s[86:87] offset:2064
	global_load_dwordx4 v[80:83], v2, s[86:87]
	global_load_dwordx4 v[84:87], v2, s[86:87] offset:16
	global_load_dwordx4 v[88:91], v2, s[86:87] offset:2048
	global_load_dwordx4 v[92:95], v2, s[86:87] offset:2064
	s_lshl_b32 s88, s85, 12
	s_add_u32 s90, s22, 0x17d2a000
	s_addc_u32 s91, s23, 0
	s_add_u32 s90, s90, s88
	s_addc_u32 s91, s91, 0
	s_add_u32 s92, s90, 0x4200000
	s_addc_u32 s93, s91, 0
	v_mov_b32_e32 v4, 0x358637bd
	v_xor_b32_e32 v5, 1, v0
	v_lshlrev_b32_e32 v5, 2, v5
	v_xor_b32_e32 v6, 2, v0
	v_lshlrev_b32_e32 v6, 2, v6
	v_xor_b32_e32 v7, 4, v0
	v_lshlrev_b32_e32 v7, 2, v7
	v_xor_b32_e32 v8, 8, v0
	v_lshlrev_b32_e32 v8, 2, v8
	v_xor_b32_e32 v9, 16, v0
	v_lshlrev_b32_e32 v9, 2, v9
	v_xor_b32_e32 v10, 32, v0
	v_lshlrev_b32_e32 v10, 2, v10
	global_load_dwordx4 v[24:27], v3, s[90:91]
	global_load_dwordx4 v[28:31], v3, s[90:91] offset:1024
	global_load_dwordx4 v[32:35], v3, s[90:91] offset:2048
	global_load_dwordx4 v[36:39], v3, s[90:91] offset:3072
	s_waitcnt vmcnt(0)

; #define PG8_STAGE(bufoff, gbase, voff) do { _Pragma("unroll") for (int _i = 0; _i < 2; ++_i) \
;         __builtin_amdgcn_global_load_lds((const unsigned*)((const char*)(gbase) + (voff)[_i]), (LAS unsigned*)(lds + (bufoff) + ldsw + _i * 8192), 16, 0, 0); } while (0)
; #define PG8_LDA(dst, b, h) do { _Pragma("unroll") for (int m = 0; m < 4; ++m) _Pragma("unroll") for (int k = 0; k < 2; ++k) dst[m][k] = *(const LAS bf16x8*)(lds + PG8_SA(b, h) + aoff + m * 2048 + k * 1024); } while (0)
; #define PG8_LDB(dst, b, h) do { _Pragma("unroll") for (int n = 0; n < 2; ++n) _Pragma("unroll") for (int k = 0; k < 2; ++k) dst[n][k] = *(const LAS bf16x8*)(lds + PG8_SB(b, h) + boff + n * 2048 + k * 1024); } while (0)
; #define PG8_MMA(ai, bj, At, Bt) do { __builtin_amdgcn_s_setprio(1); _Pragma("unroll") for (int m = 0; m < 4; ++m) _Pragma("unroll") for (int n = 0; n < 2; ++n) _Pragma("unroll") for (int k = 0; k < 2; ++k) \
;         acc[ai][bj][m][n] = __builtin_amdgcn_mfma_f32_16x16x32_bf16(Bt[n][k], At[m][k], acc[ai][bj][m][n], 0, 0, 0); __builtin_amdgcn_s_setprio(0); } while (0)
; #define PG8_WAIT_V(n) asm volatile("s_waitcnt vmcnt(" #n ")" ::: "memory")
; #define PG8_WAIT_L(n) asm volatile("s_waitcnt lgkmcnt(" #n ")" ::: "memory")
; #define PG8_BAR __builtin_amdgcn_s_barrier()
; #define PG8_SCHED __builtin_amdgcn_sched_barrier(0)
; template <class Epi>
; __device__ __forceinline__ void gemm_phase(LAS unsigned char* lds, const Gemm g, const StaticOrder& S, const Epi& E, int wave_s) {
;     ...
;             PG8_LDB(B0, 0, 0); PG8_LDB(B1, 0, 1); PG8_SCHED; PG8_LDA(At, 0, 0); PG8_STAGE(PG8_SA(1, 1), a1 + hstepA, voffA);
;             PG8_WAIT_V(8); PG8_WAIT_L(0); PG8_BAR; PG8_MMA(0, 0, At, B0); PG8_MMA(0, 1, At, B1); PG8_BAR; PG8_SCHED;
;             PG8_LDA(At, 0, 1); PG8_STAGE(PG8_SB(0, 0), b2, voffB); PG8_STAGE(PG8_SB(0, 1), b2 + hstepB, voffB); PG8_STAGE(PG8_SA(0, 0), a2, voffA);
.LBB0_1228:
	ds_read_b128 v[150:153], v147
	ds_read_b128 v[154:157], v147 offset:1024
	ds_read_b128 v[158:161], v147 offset:2048
	ds_read_b128 v[162:165], v147 offset:3072
	ds_read_b128 v[166:169], v148
	ds_read_b128 v[170:173], v148 offset:1024
	ds_read_b128 v[174:177], v148 offset:2048
	ds_read_b128 v[178:181], v148 offset:3072
	s_add_u32 s36, s34, 0xfff80080
	s_addc_u32 s37, s35, -1
	s_cmp_eq_u32 s59, 28
	s_cselect_b32 s39, s17, s37
	s_cselect_b32 s38, s55, s36
	s_cselect_b32 s37, s15, s58
	s_cselect_b32 s36, s56, s57
	v_lshl_add_u64 v[214:215], s[34:35], 0, v[136:137]
	s_add_i32 m0, s31, 0xc000
	ds_read_b128 v[182:185], v149
	ds_read_b128 v[186:189], v149 offset:1024
	ds_read_b128 v[190:193], v149 offset:2048
	ds_read_b128 v[194:197], v149 offset:3072
	ds_read_b128 v[198:201], v149 offset:4096
	ds_read_b128 v[202:205], v149 offset:5120
	ds_read_b128 v[206:209], v149 offset:6144
	ds_read_b128 v[210:213], v149 offset:7168
	global_load_lds_dwordx4 v[214:215], off
	v_lshl_add_u64 v[214:215], s[34:35], 0, v[138:139]
	s_add_i32 m0, s31, 0xe000
	s_nop 0
	global_load_lds_dwordx4 v[214:215], off
	s_waitcnt vmcnt(8)
	s_waitcnt lgkmcnt(0)
	s_barrier
	s_waitcnt lgkmcnt(0)
	v_mfma_f32_16x16x32_bf16 v[124:127], v[150:153], v[182:185], v[124:127]
	v_mfma_f32_16x16x32_bf16 v[120:123], v[158:161], v[182:185], v[120:123]
	v_mfma_f32_16x16x32_bf16 v[108:111], v[150:153], v[190:193], v[108:111]
	v_mfma_f32_16x16x32_bf16 v[104:107], v[158:161], v[190:193], v[104:107]
	v_mfma_f32_16x16x32_bf16 v[92:95], v[150:153], v[198:201], v[92:95]
	v_mfma_f32_16x16x32_bf16 v[88:91], v[158:161], v[198:201], v[88:91]
	v_mfma_f32_16x16x32_bf16 v[76:79], v[150:153], v[206:209], v[76:79]
	v_mfma_f32_16x16x32_bf16 v[72:75], v[158:161], v[206:209], v[72:75]
	v_mfma_f32_16x16x32_bf16 v[124:127], v[154:157], v[186:189], v[124:127]
	v_mfma_f32_16x16x32_bf16 v[120:123], v[162:165], v[186:189], v[120:123]
	v_mfma_f32_16x16x32_bf16 v[108:111], v[154:157], v[194:197], v[108:111]
	v_mfma_f32_16x16x32_bf16 v[104:107], v[162:165], v[194:197], v[104:107]
	v_mfma_f32_16x16x32_bf16 v[92:95], v[154:157], v[202:205], v[92:95]
	v_mfma_f32_16x16x32_bf16 v[88:91], v[162:165], v[202:205], v[88:91]
	v_mfma_f32_16x16x32_bf16 v[76:79], v[154:157], v[210:213], v[76:79]
	v_mfma_f32_16x16x32_bf16 v[72:75], v[162:165], v[210:213], v[72:75]
	v_mfma_f32_16x16x32_bf16 v[116:119], v[166:169], v[182:185], v[116:119]
	v_mfma_f32_16x16x32_bf16 v[112:115], v[174:177], v[182:185], v[112:115]
	v_mfma_f32_16x16x32_bf16 v[100:103], v[166:169], v[190:193], v[100:103]
	v_mfma_f32_16x16x32_bf16 v[96:99], v[174:177], v[190:193], v[96:99]
	v_mfma_f32_16x16x32_bf16 v[84:87], v[166:169], v[198:201], v[84:87]
	v_mfma_f32_16x16x32_bf16 v[80:83], v[174:177], v[198:201], v[80:83]
	v_mfma_f32_16x16x32_bf16 v[68:71], v[166:169], v[206:209], v[68:71]
	v_mfma_f32_16x16x32_bf16 v[64:67], v[174:177], v[206:209], v[64:67]
	v_mfma_f32_16x16x32_bf16 v[116:119], v[170:173], v[186:189], v[116:119]
	v_mfma_f32_16x16x32_bf16 v[112:115], v[178:181], v[186:189], v[112:115]
	v_mfma_f32_16x16x32_bf16 v[100:103], v[170:173], v[194:197], v[100:103]
	v_mfma_f32_16x16x32_bf16 v[96:99], v[178:181], v[194:197], v[96:99]
	v_mfma_f32_16x16x32_bf16 v[84:87], v[170:173], v[202:205], v[84:87]
	v_mfma_f32_16x16x32_bf16 v[80:83], v[178:181], v[202:205], v[80:83]
	v_mfma_f32_16x16x32_bf16 v[68:71], v[170:173], v[210:213], v[68:71]
	v_mfma_f32_16x16x32_bf16 v[64:67], v[178:181], v[210:213], v[64:67]
	s_barrier
	s_add_i32 s60, s51, s43
	v_lshl_add_u64 v[214:215], s[36:37], 0, v[130:131]
	s_mov_b32 m0, s60
	ds_read_b128 v[182:185], v149 offset:16384
	ds_read_b128 v[186:189], v149 offset:17408
	ds_read_b128 v[190:193], v149 offset:18432
	ds_read_b128 v[194:197], v149 offset:19456
	ds_read_b128 v[198:201], v149 offset:20480
	ds_read_b128 v[202:205], v149 offset:21504
	ds_read_b128 v[206:209], v149 offset:22528
	ds_read_b128 v[210:213], v149 offset:23552
	global_load_lds_dwordx4 v[214:215], off
	s_add_i32 m0, s60, 0x2000
	s_add_u32 s60, s36, 0x80000
	v_lshl_add_u64 v[216:217], s[36:37], 0, v[134:135]
	s_addc_u32 s61, s37, 0
	s_add_i32 s62, s52, s43
	global_load_lds_dwordx4 v[216:217], off
	v_lshl_add_u64 v[218:219], s[60:61], 0, v[130:131]
	s_mov_b32 m0, s62
	v_lshl_add_u64 v[220:221], s[38:39], 0, v[132:133]
	global_load_lds_dwordx4 v[218:219], off
	v_lshl_add_u64 v[218:219], s[60:61], 0, v[134:135]
	s_add_i32 m0, s62, 0x2000
	s_nop 0
	global_load_lds_dwordx4 v[218:219], off
	v_lshl_add_u64 v[218:219], s[38:39], 0, v[128:129]
	s_mov_b32 m0, s31
	s_nop 0
	global_load_lds_dwordx4 v[218:219], off
	s_mov_b32 m0, s44
	s_nop 0
	global_load_lds_dwordx4 v[220:221], off
	s_waitcnt vmcnt(8)
	s_waitcnt lgkmcnt(0)
	s_barrier
; #define PG8_STAGE(bufoff, gbase, voff) do { _Pragma("unroll") for (int _i = 0; _i < 2; ++_i) \
;         __builtin_amdgcn_global_load_lds((const unsigned*)((const char*)(gbase) + (voff)[_i]), (LAS unsigned*)(lds + (bufoff) + ldsw + _i * 8192), 16, 0, 0); } while (0)
; #define PG8_LDA(dst, b, h) do { _Pragma("unroll") for (int m = 0; m < 4; ++m) _Pragma("unroll") for (int k = 0; k < 2; ++k) dst[m][k] = *(const LAS bf16x8*)(lds + PG8_SA(b, h) + aoff + m * 2048 + k * 1024); } while (0)
; #define PG8_LDB(dst, b, h) do { _Pragma("unroll") for (int n = 0; n < 2; ++n) _Pragma("unroll") for (int k = 0; k < 2; ++k) dst[n][k] = *(const LAS bf16x8*)(lds + PG8_SB(b, h) + boff + n * 2048 + k * 1024); } while (0)
; #define PG8_MMA(ai, bj, At, Bt) do { __builtin_amdgcn_s_setprio(1); _Pragma("unroll") for (int m = 0; m < 4; ++m) _Pragma("unroll") for (int n = 0; n < 2; ++n) _Pragma("unroll") for (int k = 0; k < 2; ++k) \
;         acc[ai][bj][m][n] = __builtin_amdgcn_mfma_f32_16x16x32_bf16(Bt[n][k], At[m][k], acc[ai][bj][m][n], 0, 0, 0); __builtin_amdgcn_s_setprio(0); } while (0)
; #define PG8_WAIT_V(n) asm volatile("s_waitcnt vmcnt(" #n ")" ::: "memory")
; #define PG8_WAIT_L(n) asm volatile("s_waitcnt lgkmcnt(" #n ")" ::: "memory")
; #define PG8_BAR __builtin_amdgcn_s_barrier()
; #define PG8_SCHED __builtin_amdgcn_sched_barrier(0)
; template <class Epi>
; __device__ __forceinline__ void gemm_phase(LAS unsigned char* lds, const Gemm g, const StaticOrder& S, const Epi& E, int wave_s) {
;     ...
;             PG8_WAIT_V(8); PG8_WAIT_L(0); PG8_BAR; PG8_MMA(1, 0, At, B0); PG8_MMA(1, 1, At, B1); PG8_BAR; PG8_SCHED;
;             PG8_LDB(B0, 1, 0); PG8_LDB(B1, 1, 1); PG8_SCHED; PG8_LDA(At, 1, 0); PG8_STAGE(PG8_SA(0, 1), a2 + hstepA, voffA);
;             PG8_WAIT_V(8); PG8_WAIT_L(0); PG8_BAR; PG8_MMA(0, 0, At, B0); PG8_MMA(0, 1, At, B1); PG8_BAR; PG8_SCHED;
	s_waitcnt lgkmcnt(0)
	v_mfma_f32_16x16x32_bf16 v[60:63], v[150:153], v[182:185], v[60:63]
	v_mfma_f32_16x16x32_bf16 v[56:59], v[158:161], v[182:185], v[56:59]
	v_mfma_f32_16x16x32_bf16 v[44:47], v[150:153], v[190:193], v[44:47]
	v_mfma_f32_16x16x32_bf16 v[40:43], v[158:161], v[190:193], v[40:43]
	v_mfma_f32_16x16x32_bf16 v[28:31], v[150:153], v[198:201], v[28:31]
	v_mfma_f32_16x16x32_bf16 v[24:27], v[158:161], v[198:201], v[24:27]
	v_mfma_f32_16x16x32_bf16 v[12:15], v[150:153], v[206:209], v[12:15]
	v_mfma_f32_16x16x32_bf16 v[8:11], v[158:161], v[206:209], v[8:11]
	v_mfma_f32_16x16x32_bf16 v[60:63], v[154:157], v[186:189], v[60:63]
	v_mfma_f32_16x16x32_bf16 v[56:59], v[162:165], v[186:189], v[56:59]
	v_mfma_f32_16x16x32_bf16 v[44:47], v[154:157], v[194:197], v[44:47]
	v_mfma_f32_16x16x32_bf16 v[40:43], v[162:165], v[194:197], v[40:43]
	v_mfma_f32_16x16x32_bf16 v[28:31], v[154:157], v[202:205], v[28:31]
	v_mfma_f32_16x16x32_bf16 v[24:27], v[162:165], v[202:205], v[24:27]
	v_mfma_f32_16x16x32_bf16 v[12:15], v[154:157], v[210:213], v[12:15]
	v_mfma_f32_16x16x32_bf16 v[8:11], v[162:165], v[210:213], v[8:11]
	v_mfma_f32_16x16x32_bf16 v[52:55], v[166:169], v[182:185], v[52:55]
	v_mfma_f32_16x16x32_bf16 v[48:51], v[174:177], v[182:185], v[48:51]
	v_mfma_f32_16x16x32_bf16 v[36:39], v[166:169], v[190:193], v[36:39]
	v_mfma_f32_16x16x32_bf16 v[32:35], v[174:177], v[190:193], v[32:35]
	v_mfma_f32_16x16x32_bf16 v[20:23], v[166:169], v[198:201], v[20:23]
	v_mfma_f32_16x16x32_bf16 v[16:19], v[174:177], v[198:201], v[16:19]
	v_mfma_f32_16x16x32_bf16 v[4:7], v[166:169], v[206:209], v[4:7]
	v_mfma_f32_16x16x32_bf16 v[0:3], v[174:177], v[206:209], v[0:3]
	v_mfma_f32_16x16x32_bf16 v[52:55], v[170:173], v[186:189], v[52:55]
	v_mfma_f32_16x16x32_bf16 v[48:51], v[178:181], v[186:189], v[48:51]
	v_mfma_f32_16x16x32_bf16 v[36:39], v[170:173], v[194:197], v[36:39]
	v_mfma_f32_16x16x32_bf16 v[32:35], v[178:181], v[194:197], v[32:35]
	v_mfma_f32_16x16x32_bf16 v[20:23], v[170:173], v[202:205], v[20:23]
	v_mfma_f32_16x16x32_bf16 v[16:19], v[178:181], v[202:205], v[16:19]
	v_mfma_f32_16x16x32_bf16 v[4:7], v[170:173], v[210:213], v[4:7]
	v_mfma_f32_16x16x32_bf16 v[0:3], v[178:181], v[210:213], v[0:3]
	s_barrier
	s_add_i32 s60, 0, 0x18000
	s_add_i32 s61, 0, 0x1c000
	v_add_u32_e32 v162, s60, v145
	v_add_u32_e32 v178, s61, v145
	ds_read_b128 v[150:153], v162
	ds_read_b128 v[154:157], v162 offset:1024
	ds_read_b128 v[158:161], v162 offset:2048
	ds_read_b128 v[162:165], v162 offset:3072
	ds_read_b128 v[166:169], v178
	ds_read_b128 v[170:173], v178 offset:1024
	ds_read_b128 v[174:177], v178 offset:2048
	ds_read_b128 v[178:181], v178 offset:3072
	s_add_u32 s38, s38, 0x80000
	s_addc_u32 s39, s39, 0
	s_mov_b32 m0, s45
	v_lshl_add_u64 v[222:223], s[38:39], 0, v[128:129]
	ds_read_b128 v[182:185], v149 offset:32768
	ds_read_b128 v[186:189], v149 offset:33792
	ds_read_b128 v[190:193], v149 offset:34816
	ds_read_b128 v[194:197], v149 offset:35840
	ds_read_b128 v[198:201], v149 offset:36864
	ds_read_b128 v[202:205], v149 offset:37888
	ds_read_b128 v[206:209], v149 offset:38912
	ds_read_b128 v[210:213], v149 offset:39936
	global_load_lds_dwordx4 v[222:223], off
	v_lshl_add_u64 v[222:223], s[38:39], 0, v[132:133]
	s_mov_b32 m0, s46
	s_nop 0
	global_load_lds_dwordx4 v[222:223], off
	s_waitcnt vmcnt(8)
	s_waitcnt lgkmcnt(0)
	s_barrier
	s_waitcnt lgkmcnt(0)
	v_mfma_f32_16x16x32_bf16 v[124:127], v[150:153], v[182:185], v[124:127]
	v_mfma_f32_16x16x32_bf16 v[120:123], v[158:161], v[182:185], v[120:123]
	v_mfma_f32_16x16x32_bf16 v[108:111], v[150:153], v[190:193], v[108:111]
	v_mfma_f32_16x16x32_bf16 v[104:107], v[158:161], v[190:193], v[104:107]
	v_mfma_f32_16x16x32_bf16 v[92:95], v[150:153], v[198:201], v[92:95]
	v_mfma_f32_16x16x32_bf16 v[88:91], v[158:161], v[198:201], v[88:91]
	v_mfma_f32_16x16x32_bf16 v[76:79], v[150:153], v[206:209], v[76:79]
	v_mfma_f32_16x16x32_bf16 v[72:75], v[158:161], v[206:209], v[72:75]
	v_mfma_f32_16x16x32_bf16 v[124:127], v[154:157], v[186:189], v[124:127]
	v_mfma_f32_16x16x32_bf16 v[120:123], v[162:165], v[186:189], v[120:123]
	v_mfma_f32_16x16x32_bf16 v[108:111], v[154:157], v[194:197], v[108:111]
	v_mfma_f32_16x16x32_bf16 v[104:107], v[162:165], v[194:197], v[104:107]
	v_mfma_f32_16x16x32_bf16 v[92:95], v[154:157], v[202:205], v[92:95]
	v_mfma_f32_16x16x32_bf16 v[88:91], v[162:165], v[202:205], v[88:91]
	v_mfma_f32_16x16x32_bf16 v[76:79], v[154:157], v[210:213], v[76:79]
	v_mfma_f32_16x16x32_bf16 v[72:75], v[162:165], v[210:213], v[72:75]
	v_mfma_f32_16x16x32_bf16 v[116:119], v[166:169], v[182:185], v[116:119]
	v_mfma_f32_16x16x32_bf16 v[112:115], v[174:177], v[182:185], v[112:115]
	v_mfma_f32_16x16x32_bf16 v[100:103], v[166:169], v[190:193], v[100:103]
	v_mfma_f32_16x16x32_bf16 v[96:99], v[174:177], v[190:193], v[96:99]
	v_mfma_f32_16x16x32_bf16 v[84:87], v[166:169], v[198:201], v[84:87]
	v_mfma_f32_16x16x32_bf16 v[80:83], v[174:177], v[198:201], v[80:83]
	v_mfma_f32_16x16x32_bf16 v[68:71], v[166:169], v[206:209], v[68:71]
	v_mfma_f32_16x16x32_bf16 v[64:67], v[174:177], v[206:209], v[64:67]
	v_mfma_f32_16x16x32_bf16 v[116:119], v[170:173], v[186:189], v[116:119]
	v_mfma_f32_16x16x32_bf16 v[112:115], v[178:181], v[186:189], v[112:115]
	v_mfma_f32_16x16x32_bf16 v[100:103], v[170:173], v[194:197], v[100:103]
	v_mfma_f32_16x16x32_bf16 v[96:99], v[178:181], v[194:197], v[96:99]
	v_mfma_f32_16x16x32_bf16 v[84:87], v[170:173], v[202:205], v[84:87]
	v_mfma_f32_16x16x32_bf16 v[80:83], v[178:181], v[202:205], v[80:83]
	v_mfma_f32_16x16x32_bf16 v[68:71], v[170:173], v[210:213], v[68:71]
	v_mfma_f32_16x16x32_bf16 v[64:67], v[178:181], v[210:213], v[64:67]
	s_barrier
; #define PG8_STAGE(bufoff, gbase, voff) do { _Pragma("unroll") for (int _i = 0; _i < 2; ++_i) \
;         __builtin_amdgcn_global_load_lds((const unsigned*)((const char*)(gbase) + (voff)[_i]), (LAS unsigned*)(lds + (bufoff) + ldsw + _i * 8192), 16, 0, 0); } while (0)
; #define PG8_LDA(dst, b, h) do { _Pragma("unroll") for (int m = 0; m < 4; ++m) _Pragma("unroll") for (int k = 0; k < 2; ++k) dst[m][k] = *(const LAS bf16x8*)(lds + PG8_SA(b, h) + aoff + m * 2048 + k * 1024); } while (0)
; #define PG8_MMA(ai, bj, At, Bt) do { __builtin_amdgcn_s_setprio(1); _Pragma("unroll") for (int m = 0; m < 4; ++m) _Pragma("unroll") for (int n = 0; n < 2; ++n) _Pragma("unroll") for (int k = 0; k < 2; ++k) \
;         acc[ai][bj][m][n] = __builtin_amdgcn_mfma_f32_16x16x32_bf16(Bt[n][k], At[m][k], acc[ai][bj][m][n], 0, 0, 0); __builtin_amdgcn_s_setprio(0); } while (0)
; #define PG8_WAIT_V(n) asm volatile("s_waitcnt vmcnt(" #n ")" ::: "memory")
; #define PG8_WAIT_L(n) asm volatile("s_waitcnt lgkmcnt(" #n ")" ::: "memory")
; #define PG8_BAR __builtin_amdgcn_s_barrier()
; #define PG8_SCHED __builtin_amdgcn_sched_barrier(0)
; template <class Epi>
; __device__ __forceinline__ void gemm_phase(LAS unsigned char* lds, const Gemm g, const StaticOrder& S, const Epi& E, int wave_s) {
;     ...
;             PG8_LDA(At, 1, 1); PG8_STAGE(PG8_SB(1, 0), b3, voffB); PG8_STAGE(PG8_SB(1, 1), b3 + hstepB, voffB); PG8_STAGE(PG8_SA(1, 0), a3, voffA);
;             PG8_WAIT_V(8); PG8_WAIT_L(0); PG8_BAR; PG8_MMA(1, 0, At, B0); PG8_MMA(1, 1, At, B1); PG8_BAR; PG8_SCHED;
;         }
	s_add_i32 s38, s60, s43
	v_lshl_add_u64 v[214:215], v[214:215], 0, s[10:11]
	s_mov_b32 m0, s38
	ds_read_b128 v[182:185], v149 offset:49152
	ds_read_b128 v[186:189], v149 offset:50176
	ds_read_b128 v[190:193], v149 offset:51200
	ds_read_b128 v[194:197], v149 offset:52224
	ds_read_b128 v[198:201], v149 offset:53248
	ds_read_b128 v[202:205], v149 offset:54272
	ds_read_b128 v[206:209], v149 offset:55296
	ds_read_b128 v[210:213], v149 offset:56320
	global_load_lds_dwordx4 v[214:215], off
	s_add_i32 m0, s38, 0x2000
	s_add_u32 s36, s36, 0x80080
	v_lshl_add_u64 v[214:215], v[216:217], 0, s[10:11]
	s_addc_u32 s37, s37, 0
	s_add_i32 s38, s61, s43
	global_load_lds_dwordx4 v[214:215], off
	v_lshl_add_u64 v[214:215], s[36:37], 0, v[130:131]
	s_mov_b32 m0, s38
	s_nop 0
	global_load_lds_dwordx4 v[214:215], off
	v_lshl_add_u64 v[214:215], s[36:37], 0, v[134:135]
	s_add_i32 m0, s38, 0x2000
	s_nop 0
	global_load_lds_dwordx4 v[214:215], off
	v_lshl_add_u64 v[214:215], v[218:219], 0, s[10:11]
	s_mov_b32 m0, s48
	s_nop 0
	global_load_lds_dwordx4 v[214:215], off
	v_lshl_add_u64 v[214:215], v[220:221], 0, s[10:11]
	s_mov_b32 m0, s49
	s_nop 0
	global_load_lds_dwordx4 v[214:215], off
	s_waitcnt vmcnt(8)
	s_waitcnt lgkmcnt(0)
	s_barrier
	s_waitcnt lgkmcnt(0)
	v_mfma_f32_16x16x32_bf16 v[60:63], v[150:153], v[182:185], v[60:63]
	v_mfma_f32_16x16x32_bf16 v[56:59], v[158:161], v[182:185], v[56:59]
	v_mfma_f32_16x16x32_bf16 v[44:47], v[150:153], v[190:193], v[44:47]
	v_mfma_f32_16x16x32_bf16 v[40:43], v[158:161], v[190:193], v[40:43]
	v_mfma_f32_16x16x32_bf16 v[28:31], v[150:153], v[198:201], v[28:31]
	v_mfma_f32_16x16x32_bf16 v[24:27], v[158:161], v[198:201], v[24:27]
	v_mfma_f32_16x16x32_bf16 v[12:15], v[150:153], v[206:209], v[12:15]
	v_mfma_f32_16x16x32_bf16 v[8:11], v[158:161], v[206:209], v[8:11]
	v_mfma_f32_16x16x32_bf16 v[60:63], v[154:157], v[186:189], v[60:63]
	v_mfma_f32_16x16x32_bf16 v[56:59], v[162:165], v[186:189], v[56:59]
	v_mfma_f32_16x16x32_bf16 v[44:47], v[154:157], v[194:197], v[44:47]
	v_mfma_f32_16x16x32_bf16 v[40:43], v[162:165], v[194:197], v[40:43]
	v_mfma_f32_16x16x32_bf16 v[28:31], v[154:157], v[202:205], v[28:31]
	v_mfma_f32_16x16x32_bf16 v[24:27], v[162:165], v[202:205], v[24:27]
	v_mfma_f32_16x16x32_bf16 v[12:15], v[154:157], v[210:213], v[12:15]
	v_mfma_f32_16x16x32_bf16 v[8:11], v[162:165], v[210:213], v[8:11]
	v_mfma_f32_16x16x32_bf16 v[52:55], v[166:169], v[182:185], v[52:55]
	v_mfma_f32_16x16x32_bf16 v[48:51], v[174:177], v[182:185], v[48:51]
	v_mfma_f32_16x16x32_bf16 v[36:39], v[166:169], v[190:193], v[36:39]
	v_mfma_f32_16x16x32_bf16 v[32:35], v[174:177], v[190:193], v[32:35]
	v_mfma_f32_16x16x32_bf16 v[20:23], v[166:169], v[198:201], v[20:23]
	v_mfma_f32_16x16x32_bf16 v[16:19], v[174:177], v[198:201], v[16:19]
	v_mfma_f32_16x16x32_bf16 v[4:7], v[166:169], v[206:209], v[4:7]
	v_mfma_f32_16x16x32_bf16 v[0:3], v[174:177], v[206:209], v[0:3]
	v_mfma_f32_16x16x32_bf16 v[52:55], v[170:173], v[186:189], v[52:55]
	v_mfma_f32_16x16x32_bf16 v[48:51], v[178:181], v[186:189], v[48:51]
	v_mfma_f32_16x16x32_bf16 v[36:39], v[170:173], v[194:197], v[36:39]
	v_mfma_f32_16x16x32_bf16 v[32:35], v[178:181], v[194:197], v[32:35]
	v_mfma_f32_16x16x32_bf16 v[20:23], v[170:173], v[202:205], v[20:23]
	v_mfma_f32_16x16x32_bf16 v[16:19], v[178:181], v[202:205], v[16:19]
	v_mfma_f32_16x16x32_bf16 v[4:7], v[170:173], v[210:213], v[4:7]
	v_mfma_f32_16x16x32_bf16 v[0:3], v[178:181], v[210:213], v[0:3]
	s_barrier
	s_add_i32 s59, s59, 2
	s_add_u32 s34, s34, 0x100
	s_addc_u32 s35, s35, 0
	s_add_u32 s57, s57, 0x100
	s_addc_u32 s58, s58, 0
	s_cmp_gt_u32 s59, 29
	s_cbranch_scc0 .LBB0_1228
	s_and_b64 vcc, exec, s[12:13]
	s_cbranch_vccz .LBB0_1231
	s_barrier

; #define PG8_STAGE(bufoff, gbase, voff) do { _Pragma("unroll") for (int _i = 0; _i < 2; ++_i) \
;         __builtin_amdgcn_global_load_lds((const unsigned*)((const char*)(gbase) + (voff)[_i]), (LAS unsigned*)(lds + (bufoff) + ldsw + _i * 8192), 16, 0, 0); } while (0)
; #define PG8_LDA(dst, b, h) do { _Pragma("unroll") for (int m = 0; m < 4; ++m) _Pragma("unroll") for (int k = 0; k < 2; ++k) dst[m][k] = *(const LAS bf16x8*)(lds + PG8_SA(b, h) + aoff + m * 2048 + k * 1024); } while (0)
; #define PG8_LDB(dst, b, h) do { _Pragma("unroll") for (int n = 0; n < 2; ++n) _Pragma("unroll") for (int k = 0; k < 2; ++k) dst[n][k] = *(const LAS bf16x8*)(lds + PG8_SB(b, h) + boff + n * 2048 + k * 1024); } while (0)
; #define PG8_MMA(ai, bj, At, Bt) do { __builtin_amdgcn_s_setprio(1); _Pragma("unroll") for (int m = 0; m < 4; ++m) _Pragma("unroll") for (int n = 0; n < 2; ++n) _Pragma("unroll") for (int k = 0; k < 2; ++k) \
;         acc[ai][bj][m][n] = __builtin_amdgcn_mfma_f32_16x16x32_bf16(Bt[n][k], At[m][k], acc[ai][bj][m][n], 0, 0, 0); __builtin_amdgcn_s_setprio(0); } while (0)
; #define PG8_WAIT_V(n) asm volatile("s_waitcnt vmcnt(" #n ")" ::: "memory")
; #define PG8_WAIT_L(n) asm volatile("s_waitcnt lgkmcnt(" #n ")" ::: "memory")
; #define PG8_BAR __builtin_amdgcn_s_barrier()
; #define PG8_SCHED __builtin_amdgcn_sched_barrier(0)
; template <class Epi>
; __device__ __forceinline__ void gemm_phase(LAS unsigned char* lds, const Gemm g, const StaticOrder& S, const Epi& E, int wave_s) {
;     ...
;         for (int t = 0; t < nt; t += 2) {
;             const bool last = (t == nt - 2);
;             const char* a1 = cA + (size_t)(t + 1) * kstep;
;             const char* a2 = last ? nA : cA + (size_t)(t + 2) * kstep; const char* b2 = last ? nB : cB + (size_t)(t + 2) * kstep;
;             const char* a3 = a2 + kstep; const char* b3 = b2 + kstep;
;             PG8_LDB(B0, 0, 0); PG8_LDB(B1, 0, 1); PG8_SCHED; PG8_LDA(At, 0, 0); PG8_STAGE(PG8_SA(1, 1), a1 + hstepA, voffA);
;             PG8_WAIT_V(8); PG8_WAIT_L(0); PG8_BAR; PG8_MMA(0, 0, At, B0); PG8_MMA(0, 1, At, B1); PG8_BAR; PG8_SCHED;
;             PG8_LDA(At, 0, 1); PG8_STAGE(PG8_SB(0, 0), b2, voffB); PG8_STAGE(PG8_SB(0, 1), b2 + hstepB, voffB); PG8_STAGE(PG8_SA(0, 0), a2, voffA);
.Lp9a_1348:
	ds_read_b128 v[0:3], v142
	ds_read_b128 v[4:7], v142 offset:1024
	ds_read_b128 v[8:11], v142 offset:2048
	ds_read_b128 v[12:15], v142 offset:3072
	ds_read_b128 v[16:19], v143
	ds_read_b128 v[20:23], v143 offset:1024
	ds_read_b128 v[24:27], v143 offset:2048
	ds_read_b128 v[28:31], v143 offset:3072
	s_ashr_i32 s41, s40, 31
	s_lshl_b64 s[42:43], s[40:41], 17
	s_add_u32 s42, s6, s42
	s_addc_u32 s43, s7, s43
	s_and_b64 s[44:45], s[0:1], exec
	s_cselect_b32 s53, s43, s47
	s_cselect_b32 s52, s42, s46
	s_ashr_i32 s37, s36, 31
	s_lshl_b64 s[44:45], s[36:37], 17
	s_add_u32 s44, s8, s44
	s_addc_u32 s45, s9, s45
	s_and_b64 s[50:51], s[0:1], exec
	s_cselect_b32 s51, s45, s49
	s_cselect_b32 s50, s44, s48
	s_add_u32 s68, s46, 0x10080
	s_addc_u32 s69, s47, 0
	s_mov_b32 m0, s59
	v_lshl_add_u64 v[64:65], s[68:69], 0, v[128:129]
	ds_read_b128 v[32:35], v144
	ds_read_b128 v[36:39], v144 offset:1024
	ds_read_b128 v[40:43], v144 offset:2048
	ds_read_b128 v[44:47], v144 offset:3072
	ds_read_b128 v[48:51], v144 offset:4096
	ds_read_b128 v[52:55], v144 offset:5120
	ds_read_b128 v[56:59], v144 offset:6144
	ds_read_b128 v[60:63], v144 offset:7168
	global_load_lds_dwordx4 v[64:65], off
	v_lshl_add_u64 v[64:65], s[68:69], 0, v[132:133]
	s_mov_b32 m0, s60
	s_nop 0
	global_load_lds_dwordx4 v[64:65], off
	s_waitcnt vmcnt(8)
	s_waitcnt lgkmcnt(0)
	s_barrier
	s_waitcnt lgkmcnt(0)
	v_mfma_f32_16x16x32_bf16 v[64:67], v[0:3], v[32:35], 0
	v_mfma_f32_16x16x32_bf16 v[68:71], v[8:11], v[32:35], 0
	v_mfma_f32_16x16x32_bf16 v[72:75], v[0:3], v[40:43], 0
	v_mfma_f32_16x16x32_bf16 v[76:79], v[8:11], v[40:43], 0
	v_mfma_f32_16x16x32_bf16 v[80:83], v[0:3], v[48:51], 0
	v_mfma_f32_16x16x32_bf16 v[84:87], v[8:11], v[48:51], 0
	v_mfma_f32_16x16x32_bf16 v[88:91], v[0:3], v[56:59], 0
	v_mfma_f32_16x16x32_bf16 v[92:95], v[8:11], v[56:59], 0
	v_mfma_f32_16x16x32_bf16 v[64:67], v[4:7], v[36:39], v[64:67]
	v_mfma_f32_16x16x32_bf16 v[68:71], v[12:15], v[36:39], v[68:71]
	v_mfma_f32_16x16x32_bf16 v[72:75], v[4:7], v[44:47], v[72:75]
	v_mfma_f32_16x16x32_bf16 v[76:79], v[12:15], v[44:47], v[76:79]
	v_mfma_f32_16x16x32_bf16 v[80:83], v[4:7], v[52:55], v[80:83]
	v_mfma_f32_16x16x32_bf16 v[84:87], v[12:15], v[52:55], v[84:87]
	v_mfma_f32_16x16x32_bf16 v[88:91], v[4:7], v[60:63], v[88:91]
	v_mfma_f32_16x16x32_bf16 v[92:95], v[12:15], v[60:63], v[92:95]
	v_mfma_f32_16x16x32_bf16 v[96:99], v[16:19], v[32:35], 0
	v_mfma_f32_16x16x32_bf16 v[32:35], v[24:27], v[32:35], 0
	v_mfma_f32_16x16x32_bf16 v[96:99], v[20:23], v[36:39], v[96:99]
	v_mfma_f32_16x16x32_bf16 v[32:35], v[28:31], v[36:39], v[32:35]
	v_mfma_f32_16x16x32_bf16 v[36:39], v[16:19], v[40:43], 0
	v_mfma_f32_16x16x32_bf16 v[40:43], v[24:27], v[40:43], 0
	v_mfma_f32_16x16x32_bf16 v[36:39], v[20:23], v[44:47], v[36:39]
	v_mfma_f32_16x16x32_bf16 v[40:43], v[28:31], v[44:47], v[40:43]
	v_mfma_f32_16x16x32_bf16 v[44:47], v[16:19], v[48:51], 0
	v_mfma_f32_16x16x32_bf16 v[48:51], v[24:27], v[48:51], 0
	v_mfma_f32_16x16x32_bf16 v[44:47], v[20:23], v[52:55], v[44:47]
	v_mfma_f32_16x16x32_bf16 v[48:51], v[28:31], v[52:55], v[48:51]
	v_mfma_f32_16x16x32_bf16 v[52:55], v[16:19], v[56:59], 0
	v_mfma_f32_16x16x32_bf16 v[56:59], v[24:27], v[56:59], 0
	v_mfma_f32_16x16x32_bf16 v[52:55], v[20:23], v[60:63], v[52:55]
	v_mfma_f32_16x16x32_bf16 v[56:59], v[28:31], v[60:63], v[56:59]
	s_barrier
	v_lshl_add_u64 v[212:213], s[48:49], 0, v[130:131]
	s_mov_b32 m0, s61
	v_lshl_add_u64 v[148:149], v[212:213], 0, s[30:31]
	v_lshl_add_u64 v[214:215], s[48:49], 0, v[134:135]
	s_add_u32 s68, s48, 0x10100
	ds_read_b128 v[60:63], v144 offset:16384
	ds_read_b128 v[100:103], v144 offset:17408
	ds_read_b128 v[104:107], v144 offset:18432
	ds_read_b128 v[108:111], v144 offset:19456
	ds_read_b128 v[112:115], v144 offset:20480
	ds_read_b128 v[116:119], v144 offset:21504
	ds_read_b128 v[120:123], v144 offset:22528
	ds_read_b128 v[124:127], v144 offset:23552
	global_load_lds_dwordx4 v[148:149], off
	v_lshl_add_u64 v[148:149], v[214:215], 0, s[30:31]
	s_mov_b32 m0, s62
	s_addc_u32 s69, s49, 0
	global_load_lds_dwordx4 v[148:149], off
	v_lshl_add_u64 v[148:149], s[68:69], 0, v[130:131]
	s_mov_b32 m0, s63
	v_lshl_add_u64 v[216:217], s[46:47], 0, v[128:129]
	global_load_lds_dwordx4 v[148:149], off
	v_lshl_add_u64 v[148:149], s[68:69], 0, v[134:135]
	s_mov_b32 m0, s64
	v_lshl_add_u64 v[218:219], s[46:47], 0, v[132:133]
	global_load_lds_dwordx4 v[148:149], off
	v_lshl_add_u64 v[148:149], v[216:217], 0, s[30:31]
	s_mov_b32 m0, s25
	s_nop 0
	global_load_lds_dwordx4 v[148:149], off
	v_lshl_add_u64 v[148:149], v[218:219], 0, s[30:31]
	s_mov_b32 m0, s39
	s_nop 0
	global_load_lds_dwordx4 v[148:149], off
	s_waitcnt vmcnt(8)
	s_waitcnt lgkmcnt(0)
	s_barrier
; #define PG8_STAGE(bufoff, gbase, voff) do { _Pragma("unroll") for (int _i = 0; _i < 2; ++_i) \
;         __builtin_amdgcn_global_load_lds((const unsigned*)((const char*)(gbase) + (voff)[_i]), (LAS unsigned*)(lds + (bufoff) + ldsw + _i * 8192), 16, 0, 0); } while (0)
; #define PG8_LDA(dst, b, h) do { _Pragma("unroll") for (int m = 0; m < 4; ++m) _Pragma("unroll") for (int k = 0; k < 2; ++k) dst[m][k] = *(const LAS bf16x8*)(lds + PG8_SA(b, h) + aoff + m * 2048 + k * 1024); } while (0)
; #define PG8_LDB(dst, b, h) do { _Pragma("unroll") for (int n = 0; n < 2; ++n) _Pragma("unroll") for (int k = 0; k < 2; ++k) dst[n][k] = *(const LAS bf16x8*)(lds + PG8_SB(b, h) + boff + n * 2048 + k * 1024); } while (0)
; #define PG8_MMA(ai, bj, At, Bt) do { __builtin_amdgcn_s_setprio(1); _Pragma("unroll") for (int m = 0; m < 4; ++m) _Pragma("unroll") for (int n = 0; n < 2; ++n) _Pragma("unroll") for (int k = 0; k < 2; ++k) \
;         acc[ai][bj][m][n] = __builtin_amdgcn_mfma_f32_16x16x32_bf16(Bt[n][k], At[m][k], acc[ai][bj][m][n], 0, 0, 0); __builtin_amdgcn_s_setprio(0); } while (0)
; #define PG8_WAIT_V(n) asm volatile("s_waitcnt vmcnt(" #n ")" ::: "memory")
; #define PG8_WAIT_L(n) asm volatile("s_waitcnt lgkmcnt(" #n ")" ::: "memory")
; #define PG8_BAR __builtin_amdgcn_s_barrier()
; #define PG8_SCHED __builtin_amdgcn_sched_barrier(0)
; template <class Epi>
; __device__ __forceinline__ void gemm_phase(LAS unsigned char* lds, const Gemm g, const StaticOrder& S, const Epi& E, int wave_s) {
;     ...
;             PG8_WAIT_V(8); PG8_WAIT_L(0); PG8_BAR; PG8_MMA(1, 0, At, B0); PG8_MMA(1, 1, At, B1); PG8_BAR; PG8_SCHED;
;             PG8_LDB(B0, 1, 0); PG8_LDB(B1, 1, 1); PG8_SCHED; PG8_LDA(At, 1, 0); PG8_STAGE(PG8_SA(0, 1), a2 + hstepA, voffA);
;             PG8_WAIT_V(8); PG8_WAIT_L(0); PG8_BAR; PG8_MMA(0, 0, At, B0); PG8_MMA(0, 1, At, B1); PG8_BAR; PG8_SCHED;
	s_waitcnt lgkmcnt(0)
	v_mfma_f32_16x16x32_bf16 v[148:151], v[0:3], v[60:63], 0
	v_mfma_f32_16x16x32_bf16 v[156:159], v[0:3], v[104:107], 0
	v_mfma_f32_16x16x32_bf16 v[164:167], v[0:3], v[112:115], 0
	v_mfma_f32_16x16x32_bf16 v[0:3], v[0:3], v[120:123], 0
	v_mfma_f32_16x16x32_bf16 v[148:151], v[4:7], v[100:103], v[148:151]
	v_mfma_f32_16x16x32_bf16 v[156:159], v[4:7], v[108:111], v[156:159]
	v_mfma_f32_16x16x32_bf16 v[164:167], v[4:7], v[116:119], v[164:167]
	v_mfma_f32_16x16x32_bf16 v[0:3], v[4:7], v[124:127], v[0:3]
	v_mfma_f32_16x16x32_bf16 v[4:7], v[8:11], v[120:123], 0
	v_mfma_f32_16x16x32_bf16 v[152:155], v[8:11], v[60:63], 0
	v_mfma_f32_16x16x32_bf16 v[160:163], v[8:11], v[104:107], 0
	v_mfma_f32_16x16x32_bf16 v[168:171], v[8:11], v[112:115], 0
	v_mfma_f32_16x16x32_bf16 v[4:7], v[12:15], v[124:127], v[4:7]
	v_mfma_f32_16x16x32_bf16 v[152:155], v[12:15], v[100:103], v[152:155]
	v_mfma_f32_16x16x32_bf16 v[160:163], v[12:15], v[108:111], v[160:163]
	v_mfma_f32_16x16x32_bf16 v[168:171], v[12:15], v[116:119], v[168:171]
	v_mfma_f32_16x16x32_bf16 v[8:11], v[16:19], v[60:63], 0
	v_mfma_f32_16x16x32_bf16 v[12:15], v[24:27], v[60:63], 0
	v_mfma_f32_16x16x32_bf16 v[8:11], v[20:23], v[100:103], v[8:11]
	v_mfma_f32_16x16x32_bf16 v[12:15], v[28:31], v[100:103], v[12:15]
	v_mfma_f32_16x16x32_bf16 v[60:63], v[16:19], v[104:107], 0
	v_mfma_f32_16x16x32_bf16 v[100:103], v[24:27], v[104:107], 0
	v_mfma_f32_16x16x32_bf16 v[104:107], v[16:19], v[112:115], 0
	v_mfma_f32_16x16x32_bf16 v[16:19], v[16:19], v[120:123], 0
	v_mfma_f32_16x16x32_bf16 v[60:63], v[20:23], v[108:111], v[60:63]
	v_mfma_f32_16x16x32_bf16 v[100:103], v[28:31], v[108:111], v[100:103]
	v_mfma_f32_16x16x32_bf16 v[104:107], v[20:23], v[116:119], v[104:107]
	v_mfma_f32_16x16x32_bf16 v[108:111], v[24:27], v[112:115], 0
	v_mfma_f32_16x16x32_bf16 v[16:19], v[20:23], v[124:127], v[16:19]
	v_mfma_f32_16x16x32_bf16 v[20:23], v[24:27], v[120:123], 0
	v_mfma_f32_16x16x32_bf16 v[108:111], v[28:31], v[116:119], v[108:111]
	v_mfma_f32_16x16x32_bf16 v[20:23], v[28:31], v[124:127], v[20:23]
	s_barrier
	ds_read_b128 v[24:27], v145
	ds_read_b128 v[28:31], v145 offset:1024
	ds_read_b128 v[112:115], v145 offset:2048
	ds_read_b128 v[116:119], v145 offset:3072
	ds_read_b128 v[120:123], v146
	ds_read_b128 v[124:127], v146 offset:1024
	ds_read_b128 v[172:175], v146 offset:2048
	ds_read_b128 v[176:179], v146 offset:3072
	s_add_u32 s68, s46, 0x10100
	s_addc_u32 s69, s47, 0
	s_mov_b32 m0, s54
	v_lshl_add_u64 v[220:221], s[68:69], 0, v[128:129]
	ds_read_b128 v[180:183], v144 offset:32768
	ds_read_b128 v[184:187], v144 offset:33792
	ds_read_b128 v[188:191], v144 offset:34816
	ds_read_b128 v[192:195], v144 offset:35840
	ds_read_b128 v[196:199], v144 offset:36864
	ds_read_b128 v[200:203], v144 offset:37888
	ds_read_b128 v[204:207], v144 offset:38912
	ds_read_b128 v[208:211], v144 offset:39936
	global_load_lds_dwordx4 v[220:221], off
	v_lshl_add_u64 v[220:221], s[68:69], 0, v[132:133]
	s_mov_b32 m0, s55
	s_nop 0
	global_load_lds_dwordx4 v[220:221], off
	s_waitcnt vmcnt(8)
	s_waitcnt lgkmcnt(0)
	s_barrier
	s_waitcnt lgkmcnt(0)
	v_mfma_f32_16x16x32_bf16 v[64:67], v[24:27], v[180:183], v[64:67]
	v_mfma_f32_16x16x32_bf16 v[68:71], v[112:115], v[180:183], v[68:71]
	v_mfma_f32_16x16x32_bf16 v[72:75], v[24:27], v[188:191], v[72:75]
	v_mfma_f32_16x16x32_bf16 v[76:79], v[112:115], v[188:191], v[76:79]
	v_mfma_f32_16x16x32_bf16 v[80:83], v[24:27], v[196:199], v[80:83]
	v_mfma_f32_16x16x32_bf16 v[84:87], v[112:115], v[196:199], v[84:87]
	v_mfma_f32_16x16x32_bf16 v[88:91], v[24:27], v[204:207], v[88:91]
	v_mfma_f32_16x16x32_bf16 v[92:95], v[112:115], v[204:207], v[92:95]
	v_mfma_f32_16x16x32_bf16 v[64:67], v[28:31], v[184:187], v[64:67]
	v_mfma_f32_16x16x32_bf16 v[68:71], v[116:119], v[184:187], v[68:71]
	v_mfma_f32_16x16x32_bf16 v[72:75], v[28:31], v[192:195], v[72:75]
	v_mfma_f32_16x16x32_bf16 v[76:79], v[116:119], v[192:195], v[76:79]
	v_mfma_f32_16x16x32_bf16 v[80:83], v[28:31], v[200:203], v[80:83]
	v_mfma_f32_16x16x32_bf16 v[84:87], v[116:119], v[200:203], v[84:87]
	v_mfma_f32_16x16x32_bf16 v[88:91], v[28:31], v[208:211], v[88:91]
	v_mfma_f32_16x16x32_bf16 v[92:95], v[116:119], v[208:211], v[92:95]
	v_mfma_f32_16x16x32_bf16 v[96:99], v[120:123], v[180:183], v[96:99]
	v_mfma_f32_16x16x32_bf16 v[32:35], v[172:175], v[180:183], v[32:35]
	v_mfma_f32_16x16x32_bf16 v[36:39], v[120:123], v[188:191], v[36:39]
	v_mfma_f32_16x16x32_bf16 v[40:43], v[172:175], v[188:191], v[40:43]
	v_mfma_f32_16x16x32_bf16 v[44:47], v[120:123], v[196:199], v[44:47]
	v_mfma_f32_16x16x32_bf16 v[48:51], v[172:175], v[196:199], v[48:51]
	v_mfma_f32_16x16x32_bf16 v[52:55], v[120:123], v[204:207], v[52:55]
	v_mfma_f32_16x16x32_bf16 v[56:59], v[172:175], v[204:207], v[56:59]
	v_mfma_f32_16x16x32_bf16 v[96:99], v[124:127], v[184:187], v[96:99]
	v_mfma_f32_16x16x32_bf16 v[32:35], v[176:179], v[184:187], v[32:35]
	v_mfma_f32_16x16x32_bf16 v[36:39], v[124:127], v[192:195], v[36:39]
	v_mfma_f32_16x16x32_bf16 v[40:43], v[176:179], v[192:195], v[40:43]
	v_mfma_f32_16x16x32_bf16 v[44:47], v[124:127], v[200:203], v[44:47]
	v_mfma_f32_16x16x32_bf16 v[48:51], v[176:179], v[200:203], v[48:51]
	v_mfma_f32_16x16x32_bf16 v[52:55], v[124:127], v[208:211], v[52:55]
	v_mfma_f32_16x16x32_bf16 v[56:59], v[176:179], v[208:211], v[56:59]
	s_barrier
; #define PG8_STAGE(bufoff, gbase, voff) do { _Pragma("unroll") for (int _i = 0; _i < 2; ++_i) \
;         __builtin_amdgcn_global_load_lds((const unsigned*)((const char*)(gbase) + (voff)[_i]), (LAS unsigned*)(lds + (bufoff) + ldsw + _i * 8192), 16, 0, 0); } while (0)
; #define PG8_LDA(dst, b, h) do { _Pragma("unroll") for (int m = 0; m < 4; ++m) _Pragma("unroll") for (int k = 0; k < 2; ++k) dst[m][k] = *(const LAS bf16x8*)(lds + PG8_SA(b, h) + aoff + m * 2048 + k * 1024); } while (0)
; #define PG8_LDB(dst, b, h) do { _Pragma("unroll") for (int n = 0; n < 2; ++n) _Pragma("unroll") for (int k = 0; k < 2; ++k) dst[n][k] = *(const LAS bf16x8*)(lds + PG8_SB(b, h) + boff + n * 2048 + k * 1024); } while (0)
; #define PG8_MMA(ai, bj, At, Bt) do { __builtin_amdgcn_s_setprio(1); _Pragma("unroll") for (int m = 0; m < 4; ++m) _Pragma("unroll") for (int n = 0; n < 2; ++n) _Pragma("unroll") for (int k = 0; k < 2; ++k) \
;         acc[ai][bj][m][n] = __builtin_amdgcn_mfma_f32_16x16x32_bf16(Bt[n][k], At[m][k], acc[ai][bj][m][n], 0, 0, 0); __builtin_amdgcn_s_setprio(0); } while (0)
; #define PG8_WAIT_V(n) asm volatile("s_waitcnt vmcnt(" #n ")" ::: "memory")
; #define PG8_WAIT_L(n) asm volatile("s_waitcnt lgkmcnt(" #n ")" ::: "memory")
; #define PG8_BAR __builtin_amdgcn_s_barrier()
; #define PG8_SCHED __builtin_amdgcn_sched_barrier(0)
; template <class Epi>
; __device__ __forceinline__ void gemm_phase(LAS unsigned char* lds, const Gemm g, const StaticOrder& S, const Epi& E, int wave_s) {
;     ...
;             PG8_LDB(B0, 0, 0); PG8_LDB(B1, 0, 1); PG8_SCHED; PG8_LDA(At, 0, 0); PG8_STAGE(PG8_SA(1, 1), a1 + hstepA, voffA);
;             PG8_WAIT_V(8); PG8_WAIT_L(0); PG8_BAR; PG8_MMA(0, 0, At, B0); PG8_MMA(0, 1, At, B1); PG8_BAR; PG8_SCHED;
;             PG8_LDA(At, 0, 1); PG8_STAGE(PG8_SB(0, 0), b2, voffB); PG8_STAGE(PG8_SB(0, 1), b2 + hstepB, voffB); PG8_STAGE(PG8_SA(0, 0), a2, voffA);
;     ...
;             PG8_LDA(At, 1, 1); PG8_STAGE(PG8_SB(1, 0), b3, voffB); PG8_STAGE(PG8_SB(1, 1), b3 + hstepB, voffB); PG8_STAGE(PG8_SA(1, 0), a3, voffA);
;             PG8_WAIT_V(8); PG8_WAIT_L(0); PG8_BAR; PG8_MMA(1, 0, At, B0); PG8_MMA(1, 1, At, B1); PG8_BAR; PG8_SCHED;
	s_add_i32 s68, s65, s3
	s_add_i32 s37, s68, 0x2000
	v_lshl_add_u64 v[212:213], v[212:213], 0, s[34:35]
	s_mov_b32 m0, s68
	s_add_u32 s48, s48, 0x10180
	ds_read_b128 v[180:183], v144 offset:49152
	ds_read_b128 v[184:187], v144 offset:50176
	ds_read_b128 v[188:191], v144 offset:51200
	ds_read_b128 v[192:195], v144 offset:52224
	ds_read_b128 v[196:199], v144 offset:53248
	ds_read_b128 v[200:203], v144 offset:54272
	ds_read_b128 v[204:207], v144 offset:55296
	ds_read_b128 v[208:211], v144 offset:56320
	global_load_lds_dwordx4 v[212:213], off
	v_lshl_add_u64 v[212:213], v[214:215], 0, s[34:35]
	s_mov_b32 m0, s37
	s_addc_u32 s49, s49, 0
	s_add_i32 s41, s66, s3
	global_load_lds_dwordx4 v[212:213], off
	v_lshl_add_u64 v[212:213], s[48:49], 0, v[130:131]
	s_mov_b32 m0, s41
	s_nop 0
	global_load_lds_dwordx4 v[212:213], off
	v_lshl_add_u64 v[212:213], s[48:49], 0, v[134:135]
	s_add_i32 s48, s41, 0x2000
	s_mov_b32 m0, s48
	s_nop 0
	global_load_lds_dwordx4 v[212:213], off
	v_lshl_add_u64 v[212:213], v[216:217], 0, s[34:35]
	s_mov_b32 m0, s56
	s_nop 0
	global_load_lds_dwordx4 v[212:213], off
	v_lshl_add_u64 v[212:213], v[218:219], 0, s[34:35]
	s_mov_b32 m0, s57
	s_nop 0
	global_load_lds_dwordx4 v[212:213], off
	s_waitcnt vmcnt(8)
	s_waitcnt lgkmcnt(0)
	s_barrier
	s_waitcnt lgkmcnt(0)
	v_mfma_f32_16x16x32_bf16 v[0:3], v[24:27], v[204:207], v[0:3]
	v_mfma_f32_16x16x32_bf16 v[4:7], v[112:115], v[204:207], v[4:7]
	v_mfma_f32_16x16x32_bf16 v[148:151], v[24:27], v[180:183], v[148:151]
	v_mfma_f32_16x16x32_bf16 v[152:155], v[112:115], v[180:183], v[152:155]
	v_mfma_f32_16x16x32_bf16 v[156:159], v[24:27], v[188:191], v[156:159]
	v_mfma_f32_16x16x32_bf16 v[160:163], v[112:115], v[188:191], v[160:163]
	v_mfma_f32_16x16x32_bf16 v[164:167], v[24:27], v[196:199], v[164:167]
	v_mfma_f32_16x16x32_bf16 v[168:171], v[112:115], v[196:199], v[168:171]
	v_mfma_f32_16x16x32_bf16 v[0:3], v[28:31], v[208:211], v[0:3]
	v_mfma_f32_16x16x32_bf16 v[4:7], v[116:119], v[208:211], v[4:7]
	v_mfma_f32_16x16x32_bf16 v[148:151], v[28:31], v[184:187], v[148:151]
	v_mfma_f32_16x16x32_bf16 v[152:155], v[116:119], v[184:187], v[152:155]
	v_mfma_f32_16x16x32_bf16 v[156:159], v[28:31], v[192:195], v[156:159]
	v_mfma_f32_16x16x32_bf16 v[160:163], v[116:119], v[192:195], v[160:163]
	v_mfma_f32_16x16x32_bf16 v[164:167], v[28:31], v[200:203], v[164:167]
	v_mfma_f32_16x16x32_bf16 v[168:171], v[116:119], v[200:203], v[168:171]
	v_mfma_f32_16x16x32_bf16 v[8:11], v[120:123], v[180:183], v[8:11]
	v_mfma_f32_16x16x32_bf16 v[12:15], v[172:175], v[180:183], v[12:15]
	v_mfma_f32_16x16x32_bf16 v[24:27], v[120:123], v[188:191], v[60:63]
	v_mfma_f32_16x16x32_bf16 v[28:31], v[172:175], v[188:191], v[100:103]
	v_mfma_f32_16x16x32_bf16 v[60:63], v[120:123], v[196:199], v[104:107]
	v_mfma_f32_16x16x32_bf16 v[100:103], v[172:175], v[196:199], v[108:111]
	v_mfma_f32_16x16x32_bf16 v[16:19], v[120:123], v[204:207], v[16:19]
	v_mfma_f32_16x16x32_bf16 v[20:23], v[172:175], v[204:207], v[20:23]
	v_mfma_f32_16x16x32_bf16 v[8:11], v[124:127], v[184:187], v[8:11]
	v_mfma_f32_16x16x32_bf16 v[12:15], v[176:179], v[184:187], v[12:15]
	v_mfma_f32_16x16x32_bf16 v[24:27], v[124:127], v[192:195], v[24:27]
	v_mfma_f32_16x16x32_bf16 v[28:31], v[176:179], v[192:195], v[28:31]
	v_mfma_f32_16x16x32_bf16 v[60:63], v[124:127], v[200:203], v[60:63]
	v_mfma_f32_16x16x32_bf16 v[100:103], v[176:179], v[200:203], v[100:103]
	v_mfma_f32_16x16x32_bf16 v[16:19], v[124:127], v[208:211], v[16:19]
	v_mfma_f32_16x16x32_bf16 v[20:23], v[176:179], v[208:211], v[20:23]
	s_barrier
	ds_read_b128 v[104:107], v142
	ds_read_b128 v[108:111], v142 offset:1024
	ds_read_b128 v[112:115], v142 offset:2048
	ds_read_b128 v[116:119], v142 offset:3072
	ds_read_b128 v[120:123], v143
	ds_read_b128 v[124:127], v143 offset:1024
	ds_read_b128 v[172:175], v143 offset:2048
	ds_read_b128 v[176:179], v143 offset:3072
	s_add_u32 s46, s46, 0x10180
	s_addc_u32 s47, s47, 0
	s_mov_b32 m0, s59
	v_lshl_add_u64 v[212:213], s[46:47], 0, v[128:129]
	ds_read_b128 v[180:183], v144
	ds_read_b128 v[184:187], v144 offset:1024
	ds_read_b128 v[188:191], v144 offset:2048
	ds_read_b128 v[192:195], v144 offset:3072
	ds_read_b128 v[196:199], v144 offset:4096
	ds_read_b128 v[200:203], v144 offset:5120
	ds_read_b128 v[204:207], v144 offset:6144
	ds_read_b128 v[208:211], v144 offset:7168
	global_load_lds_dwordx4 v[212:213], off
	v_lshl_add_u64 v[212:213], s[46:47], 0, v[132:133]
	s_mov_b32 m0, s60
	s_nop 0
	global_load_lds_dwordx4 v[212:213], off
	s_waitcnt vmcnt(8)
	s_waitcnt lgkmcnt(0)
	s_barrier
; #define PG8_STAGE(bufoff, gbase, voff) do { _Pragma("unroll") for (int _i = 0; _i < 2; ++_i) \
;         __builtin_amdgcn_global_load_lds((const unsigned*)((const char*)(gbase) + (voff)[_i]), (LAS unsigned*)(lds + (bufoff) + ldsw + _i * 8192), 16, 0, 0); } while (0)
; #define PG8_LDA(dst, b, h) do { _Pragma("unroll") for (int m = 0; m < 4; ++m) _Pragma("unroll") for (int k = 0; k < 2; ++k) dst[m][k] = *(const LAS bf16x8*)(lds + PG8_SA(b, h) + aoff + m * 2048 + k * 1024); } while (0)
; #define PG8_LDB(dst, b, h) do { _Pragma("unroll") for (int n = 0; n < 2; ++n) _Pragma("unroll") for (int k = 0; k < 2; ++k) dst[n][k] = *(const LAS bf16x8*)(lds + PG8_SB(b, h) + boff + n * 2048 + k * 1024); } while (0)
; #define PG8_MMA(ai, bj, At, Bt) do { __builtin_amdgcn_s_setprio(1); _Pragma("unroll") for (int m = 0; m < 4; ++m) _Pragma("unroll") for (int n = 0; n < 2; ++n) _Pragma("unroll") for (int k = 0; k < 2; ++k) \
;         acc[ai][bj][m][n] = __builtin_amdgcn_mfma_f32_16x16x32_bf16(Bt[n][k], At[m][k], acc[ai][bj][m][n], 0, 0, 0); __builtin_amdgcn_s_setprio(0); } while (0)
; #define PG8_WAIT_V(n) asm volatile("s_waitcnt vmcnt(" #n ")" ::: "memory")
; #define PG8_WAIT_L(n) asm volatile("s_waitcnt lgkmcnt(" #n ")" ::: "memory")
; #define PG8_BAR __builtin_amdgcn_s_barrier()
; #define PG8_SCHED __builtin_amdgcn_sched_barrier(0)
; template <class Epi>
; __device__ __forceinline__ void gemm_phase(LAS unsigned char* lds, const Gemm g, const StaticOrder& S, const Epi& E, int wave_s) {
;     ...
;             PG8_WAIT_V(8); PG8_WAIT_L(0); PG8_BAR; PG8_MMA(0, 0, At, B0); PG8_MMA(0, 1, At, B1); PG8_BAR; PG8_SCHED;
;             PG8_LDA(At, 0, 1); PG8_STAGE(PG8_SB(0, 0), b2, voffB); PG8_STAGE(PG8_SB(0, 1), b2 + hstepB, voffB); PG8_STAGE(PG8_SA(0, 0), a2, voffA);
;             PG8_WAIT_V(8); PG8_WAIT_L(0); PG8_BAR; PG8_MMA(1, 0, At, B0); PG8_MMA(1, 1, At, B1); PG8_BAR; PG8_SCHED;
;             PG8_LDB(B0, 1, 0); PG8_LDB(B1, 1, 1); PG8_SCHED; PG8_LDA(At, 1, 0); PG8_STAGE(PG8_SA(0, 1), a2 + hstepA, voffA);
;             PG8_WAIT_V(8); PG8_WAIT_L(0); PG8_BAR; PG8_MMA(0, 0, At, B0); PG8_MMA(0, 1, At, B1); PG8_BAR; PG8_SCHED;
	s_waitcnt lgkmcnt(0)
	v_mfma_f32_16x16x32_bf16 v[64:67], v[104:107], v[180:183], v[64:67]
	v_mfma_f32_16x16x32_bf16 v[68:71], v[112:115], v[180:183], v[68:71]
	v_mfma_f32_16x16x32_bf16 v[72:75], v[104:107], v[188:191], v[72:75]
	v_mfma_f32_16x16x32_bf16 v[76:79], v[112:115], v[188:191], v[76:79]
	v_mfma_f32_16x16x32_bf16 v[80:83], v[104:107], v[196:199], v[80:83]
	v_mfma_f32_16x16x32_bf16 v[84:87], v[112:115], v[196:199], v[84:87]
	v_mfma_f32_16x16x32_bf16 v[88:91], v[104:107], v[204:207], v[88:91]
	v_mfma_f32_16x16x32_bf16 v[92:95], v[112:115], v[204:207], v[92:95]
	v_mfma_f32_16x16x32_bf16 v[64:67], v[108:111], v[184:187], v[64:67]
	v_mfma_f32_16x16x32_bf16 v[68:71], v[116:119], v[184:187], v[68:71]
	v_mfma_f32_16x16x32_bf16 v[72:75], v[108:111], v[192:195], v[72:75]
	v_mfma_f32_16x16x32_bf16 v[76:79], v[116:119], v[192:195], v[76:79]
	v_mfma_f32_16x16x32_bf16 v[80:83], v[108:111], v[200:203], v[80:83]
	v_mfma_f32_16x16x32_bf16 v[84:87], v[116:119], v[200:203], v[84:87]
	v_mfma_f32_16x16x32_bf16 v[88:91], v[108:111], v[208:211], v[88:91]
	v_mfma_f32_16x16x32_bf16 v[92:95], v[116:119], v[208:211], v[92:95]
	v_mfma_f32_16x16x32_bf16 v[32:35], v[172:175], v[180:183], v[32:35]
	v_mfma_f32_16x16x32_bf16 v[96:99], v[120:123], v[180:183], v[96:99]
	v_mfma_f32_16x16x32_bf16 v[180:183], v[176:179], v[184:187], v[32:35]
	v_mfma_f32_16x16x32_bf16 v[32:35], v[120:123], v[188:191], v[36:39]
	v_mfma_f32_16x16x32_bf16 v[212:215], v[124:127], v[184:187], v[96:99]
	v_mfma_f32_16x16x32_bf16 v[184:187], v[124:127], v[192:195], v[32:35]
	v_mfma_f32_16x16x32_bf16 v[32:35], v[172:175], v[188:191], v[40:43]
	v_mfma_f32_16x16x32_bf16 v[40:43], v[176:179], v[192:195], v[32:35]
	v_mfma_f32_16x16x32_bf16 v[32:35], v[120:123], v[196:199], v[44:47]
	v_mfma_f32_16x16x32_bf16 v[44:47], v[124:127], v[200:203], v[32:35]
	v_mfma_f32_16x16x32_bf16 v[32:35], v[172:175], v[196:199], v[48:51]
	v_mfma_f32_16x16x32_bf16 v[48:51], v[176:179], v[200:203], v[32:35]
	v_mfma_f32_16x16x32_bf16 v[32:35], v[120:123], v[204:207], v[52:55]
	v_mfma_f32_16x16x32_bf16 v[52:55], v[124:127], v[208:211], v[32:35]
	v_mfma_f32_16x16x32_bf16 v[32:35], v[172:175], v[204:207], v[56:59]
	v_mfma_f32_16x16x32_bf16 v[56:59], v[176:179], v[208:211], v[32:35]
	s_barrier
	s_mov_b32 m0, s61
	v_lshl_add_u64 v[248:249], s[50:51], 0, v[130:131]
	s_add_u32 s46, s50, 0x10000
	s_nop 1
	ds_read_b128 v[32:35], v144 offset:16384
	ds_read_b128 v[36:39], v144 offset:17408
	ds_read_b128 v[96:99], v144 offset:18432
	ds_read_b128 v[188:191], v144 offset:19456
	ds_read_b128 v[192:195], v144 offset:20480
	ds_read_b128 v[196:199], v144 offset:21504
	ds_read_b128 v[200:203], v144 offset:22528
	ds_read_b128 v[204:207], v144 offset:23552
	global_load_lds_dwordx4 v[248:249], off
	v_lshl_add_u64 v[250:251], s[50:51], 0, v[134:135]
	s_mov_b32 m0, s62
	s_addc_u32 s47, s51, 0
	global_load_lds_dwordx4 v[250:251], off
	v_lshl_add_u64 v[208:209], s[46:47], 0, v[130:131]
	s_mov_b32 m0, s63
	v_lshl_add_u64 v[252:253], s[52:53], 0, v[128:129]
	global_load_lds_dwordx4 v[208:209], off
	v_lshl_add_u64 v[208:209], s[46:47], 0, v[134:135]
	s_mov_b32 m0, s64
	v_lshl_add_u64 v[136:137], s[52:53], 0, v[132:133]
	global_load_lds_dwordx4 v[208:209], off
	s_mov_b32 m0, s25
	s_nop 0
	global_load_lds_dwordx4 v[252:253], off
	s_mov_b32 m0, s39
	s_nop 0
	global_load_lds_dwordx4 v[136:137], off
	s_waitcnt vmcnt(8)
	s_waitcnt lgkmcnt(0)
	s_barrier
	s_waitcnt lgkmcnt(0)
	v_mfma_f32_16x16x32_bf16 v[0:3], v[104:107], v[200:203], v[0:3]
	v_mfma_f32_16x16x32_bf16 v[4:7], v[112:115], v[200:203], v[4:7]
	v_mfma_f32_16x16x32_bf16 v[148:151], v[104:107], v[32:35], v[148:151]
	v_mfma_f32_16x16x32_bf16 v[152:155], v[112:115], v[32:35], v[152:155]
	v_mfma_f32_16x16x32_bf16 v[156:159], v[104:107], v[96:99], v[156:159]
	v_mfma_f32_16x16x32_bf16 v[160:163], v[112:115], v[96:99], v[160:163]
	v_mfma_f32_16x16x32_bf16 v[164:167], v[104:107], v[192:195], v[164:167]
	v_mfma_f32_16x16x32_bf16 v[168:171], v[112:115], v[192:195], v[168:171]
	v_mfma_f32_16x16x32_bf16 v[0:3], v[108:111], v[204:207], v[0:3]
	v_mfma_f32_16x16x32_bf16 v[4:7], v[116:119], v[204:207], v[4:7]
	v_mfma_f32_16x16x32_bf16 v[148:151], v[108:111], v[36:39], v[148:151]
	v_mfma_f32_16x16x32_bf16 v[152:155], v[116:119], v[36:39], v[152:155]
	v_mfma_f32_16x16x32_bf16 v[156:159], v[108:111], v[188:191], v[156:159]
	v_mfma_f32_16x16x32_bf16 v[160:163], v[116:119], v[188:191], v[160:163]
	v_mfma_f32_16x16x32_bf16 v[164:167], v[108:111], v[196:199], v[164:167]
	v_mfma_f32_16x16x32_bf16 v[168:171], v[116:119], v[196:199], v[168:171]
	v_mfma_f32_16x16x32_bf16 v[8:11], v[120:123], v[32:35], v[8:11]
	v_mfma_f32_16x16x32_bf16 v[12:15], v[172:175], v[32:35], v[12:15]
	v_mfma_f32_16x16x32_bf16 v[24:27], v[120:123], v[96:99], v[24:27]
	v_mfma_f32_16x16x32_bf16 v[28:31], v[172:175], v[96:99], v[28:31]
	v_mfma_f32_16x16x32_bf16 v[32:35], v[120:123], v[192:195], v[60:63]
	v_mfma_f32_16x16x32_bf16 v[24:27], v[124:127], v[188:191], v[24:27]
	v_mfma_f32_16x16x32_bf16 v[28:31], v[176:179], v[188:191], v[28:31]
	v_mfma_f32_16x16x32_bf16 v[188:191], v[124:127], v[196:199], v[32:35]
	v_mfma_f32_16x16x32_bf16 v[32:35], v[172:175], v[192:195], v[100:103]
	v_mfma_f32_16x16x32_bf16 v[16:19], v[120:123], v[200:203], v[16:19]
	v_mfma_f32_16x16x32_bf16 v[8:11], v[124:127], v[36:39], v[8:11]
	v_mfma_f32_16x16x32_bf16 v[12:15], v[176:179], v[36:39], v[12:15]
	v_mfma_f32_16x16x32_bf16 v[192:195], v[176:179], v[196:199], v[32:35]
	v_mfma_f32_16x16x32_bf16 v[196:199], v[124:127], v[204:207], v[16:19]
	v_mfma_f32_16x16x32_bf16 v[16:19], v[172:175], v[200:203], v[20:23]
	v_mfma_f32_16x16x32_bf16 v[172:175], v[176:179], v[204:207], v[16:19]
	s_barrier
; #define PG8_STAGE(bufoff, gbase, voff) do { _Pragma("unroll") for (int _i = 0; _i < 2; ++_i) \
;         __builtin_amdgcn_global_load_lds((const unsigned*)((const char*)(gbase) + (voff)[_i]), (LAS unsigned*)(lds + (bufoff) + ldsw + _i * 8192), 16, 0, 0); } while (0)
; #define PG8_LDA(dst, b, h) do { _Pragma("unroll") for (int m = 0; m < 4; ++m) _Pragma("unroll") for (int k = 0; k < 2; ++k) dst[m][k] = *(const LAS bf16x8*)(lds + PG8_SA(b, h) + aoff + m * 2048 + k * 1024); } while (0)
; #define PG8_MMA(ai, bj, At, Bt) do { __builtin_amdgcn_s_setprio(1); _Pragma("unroll") for (int m = 0; m < 4; ++m) _Pragma("unroll") for (int n = 0; n < 2; ++n) _Pragma("unroll") for (int k = 0; k < 2; ++k) \
;         acc[ai][bj][m][n] = __builtin_amdgcn_mfma_f32_16x16x32_bf16(Bt[n][k], At[m][k], acc[ai][bj][m][n], 0, 0, 0); __builtin_amdgcn_s_setprio(0); } while (0)
; #define PG8_WAIT_V(n) asm volatile("s_waitcnt vmcnt(" #n ")" ::: "memory")
; #define PG8_WAIT_L(n) asm volatile("s_waitcnt lgkmcnt(" #n ")" ::: "memory")
; #define PG8_BAR __builtin_amdgcn_s_barrier()
; #define PG8_SCHED __builtin_amdgcn_sched_barrier(0)
; template <class Epi>
; __device__ __forceinline__ void gemm_phase(LAS unsigned char* lds, const Gemm g, const StaticOrder& S, const Epi& E, int wave_s) {
;     ...
;             PG8_WAIT_V(8); PG8_WAIT_L(0); PG8_BAR; PG8_MMA(0, 0, At, B0); PG8_MMA(0, 1, At, B1); PG8_BAR; PG8_SCHED;
;             PG8_LDA(At, 1, 1); PG8_STAGE(PG8_SB(1, 0), b3, voffB); PG8_STAGE(PG8_SB(1, 1), b3 + hstepB, voffB); PG8_STAGE(PG8_SA(1, 0), a3, voffA);
;             PG8_WAIT_V(8); PG8_WAIT_L(0); PG8_BAR; PG8_MMA(1, 0, At, B0); PG8_MMA(1, 1, At, B1); PG8_BAR; PG8_SCHED;
;         }
;         if (wr == 0) PG8_BAR;
;         E(acc, cur, wr, wc, fr, fq);
;         if (!has_next) break;
	ds_read_b128 v[60:63], v145
	ds_read_b128 v[176:179], v145 offset:1024
	ds_read_b128 v[200:203], v145 offset:2048
	ds_read_b128 v[204:207], v145 offset:3072
	ds_read_b128 v[208:211], v146
	ds_read_b128 v[216:219], v146 offset:1024
	ds_read_b128 v[220:223], v146 offset:2048
	ds_read_b128 v[224:227], v146 offset:3072
	s_add_u32 s46, s52, 0x10000
	s_addc_u32 s47, s53, 0
	s_mov_b32 m0, s54
	v_lshl_add_u64 v[32:33], s[46:47], 0, v[128:129]
	ds_read_b128 v[16:19], v144 offset:32768
	ds_read_b128 v[20:23], v144 offset:33792
	ds_read_b128 v[108:111], v144 offset:34816
	ds_read_b128 v[228:231], v144 offset:35840
	ds_read_b128 v[232:235], v144 offset:36864
	ds_read_b128 v[236:239], v144 offset:37888
	ds_read_b128 v[240:243], v144 offset:38912
	ds_read_b128 v[244:247], v144 offset:39936
	global_load_lds_dwordx4 v[32:33], off
	v_lshl_add_u64 v[32:33], s[46:47], 0, v[132:133]
	s_mov_b32 m0, s55
	s_nop 0
	global_load_lds_dwordx4 v[32:33], off
	s_waitcnt vmcnt(8)
	s_waitcnt lgkmcnt(0)
	s_barrier
	s_waitcnt lgkmcnt(0)
	v_mfma_f32_16x16x32_bf16 v[32:35], v[60:63], v[16:19], v[64:67]
	v_mfma_f32_16x16x32_bf16 v[112:115], v[176:179], v[20:23], v[32:35]
	v_mfma_f32_16x16x32_bf16 v[32:35], v[200:203], v[16:19], v[68:71]
	v_mfma_f32_16x16x32_bf16 v[116:119], v[204:207], v[20:23], v[32:35]
	v_mfma_f32_16x16x32_bf16 v[32:35], v[60:63], v[108:111], v[72:75]
	v_mfma_f32_16x16x32_bf16 v[96:99], v[176:179], v[228:231], v[32:35]
	v_mfma_f32_16x16x32_bf16 v[32:35], v[200:203], v[108:111], v[76:79]
	v_mfma_f32_16x16x32_bf16 v[100:103], v[204:207], v[228:231], v[32:35]
	v_mfma_f32_16x16x32_bf16 v[32:35], v[60:63], v[232:235], v[80:83]
	v_mfma_f32_16x16x32_bf16 v[64:67], v[176:179], v[236:239], v[32:35]
	v_mfma_f32_16x16x32_bf16 v[32:35], v[200:203], v[232:235], v[84:87]
	v_mfma_f32_16x16x32_bf16 v[68:71], v[204:207], v[236:239], v[32:35]
	v_mfma_f32_16x16x32_bf16 v[32:35], v[60:63], v[240:243], v[88:91]
	v_mfma_f32_16x16x32_bf16 v[36:39], v[200:203], v[240:243], v[92:95]
	v_mfma_f32_16x16x32_bf16 v[32:35], v[176:179], v[244:247], v[32:35]
	v_mfma_f32_16x16x32_bf16 v[36:39], v[204:207], v[244:247], v[36:39]
	v_mfma_f32_16x16x32_bf16 v[72:75], v[208:211], v[16:19], v[212:215]
	v_mfma_f32_16x16x32_bf16 v[16:19], v[220:223], v[16:19], v[180:183]
	v_mfma_f32_16x16x32_bf16 v[124:127], v[224:227], v[20:23], v[16:19]
	v_mfma_f32_16x16x32_bf16 v[16:19], v[208:211], v[108:111], v[184:187]
	v_mfma_f32_16x16x32_bf16 v[104:107], v[216:219], v[228:231], v[16:19]
	v_mfma_f32_16x16x32_bf16 v[16:19], v[220:223], v[108:111], v[40:43]
	v_mfma_f32_16x16x32_bf16 v[108:111], v[224:227], v[228:231], v[16:19]
	v_mfma_f32_16x16x32_bf16 v[16:19], v[208:211], v[232:235], v[44:47]
	v_mfma_f32_16x16x32_bf16 v[120:123], v[216:219], v[20:23], v[72:75]
	v_mfma_f32_16x16x32_bf16 v[72:75], v[216:219], v[236:239], v[16:19]
	v_mfma_f32_16x16x32_bf16 v[16:19], v[220:223], v[232:235], v[48:51]
	v_mfma_f32_16x16x32_bf16 v[76:79], v[224:227], v[236:239], v[16:19]
	v_mfma_f32_16x16x32_bf16 v[16:19], v[208:211], v[240:243], v[52:55]
	v_mfma_f32_16x16x32_bf16 v[40:43], v[216:219], v[244:247], v[16:19]
	v_mfma_f32_16x16x32_bf16 v[16:19], v[220:223], v[240:243], v[56:59]
	v_mfma_f32_16x16x32_bf16 v[44:47], v[224:227], v[244:247], v[16:19]
	s_barrier
	s_mov_b32 m0, s68
	s_nop 3
	v_lshl_add_u64 v[16:17], v[248:249], 0, s[14:15]
	s_add_u32 s46, s50, 0x10080
	ds_read_b128 v[56:59], v144 offset:49152
	ds_read_b128 v[92:95], v144 offset:50176
	ds_read_b128 v[180:183], v144 offset:51200
	ds_read_b128 v[184:187], v144 offset:52224
	ds_read_b128 v[212:215], v144 offset:53248
	ds_read_b128 v[228:231], v144 offset:54272
	ds_read_b128 v[232:235], v144 offset:55296
	ds_read_b128 v[236:239], v144 offset:56320
	global_load_lds_dwordx4 v[16:17], off
	v_lshl_add_u64 v[16:17], v[250:251], 0, s[14:15]
	s_mov_b32 m0, s37
	s_addc_u32 s47, s51, 0
	global_load_lds_dwordx4 v[16:17], off
	v_lshl_add_u64 v[16:17], s[46:47], 0, v[130:131]
	s_mov_b32 m0, s41
	s_nop 0
	global_load_lds_dwordx4 v[16:17], off
	v_lshl_add_u64 v[16:17], s[46:47], 0, v[134:135]
	s_mov_b32 m0, s48
	s_nop 0
	global_load_lds_dwordx4 v[16:17], off
	v_lshl_add_u64 v[16:17], v[252:253], 0, s[14:15]
	s_mov_b32 m0, s56
	s_nop 0
	global_load_lds_dwordx4 v[16:17], off
	v_lshl_add_u64 v[16:17], v[136:137], 0, s[14:15]
	s_mov_b32 m0, s57
	s_nop 0
	global_load_lds_dwordx4 v[16:17], off
	s_waitcnt vmcnt(8)
	s_waitcnt lgkmcnt(0)
	s_barrier
	s_waitcnt lgkmcnt(0)
	v_mfma_f32_16x16x32_bf16 v[16:19], v[60:63], v[56:59], v[148:151]
	v_mfma_f32_16x16x32_bf16 v[80:83], v[176:179], v[92:95], v[16:19]
	v_mfma_f32_16x16x32_bf16 v[16:19], v[200:203], v[56:59], v[152:155]
	v_mfma_f32_16x16x32_bf16 v[84:87], v[204:207], v[92:95], v[16:19]
	v_mfma_f32_16x16x32_bf16 v[16:19], v[60:63], v[180:183], v[156:159]
	v_mfma_f32_16x16x32_bf16 v[48:51], v[176:179], v[184:187], v[16:19]
	v_mfma_f32_16x16x32_bf16 v[16:19], v[200:203], v[180:183], v[160:163]
	v_mfma_f32_16x16x32_bf16 v[52:55], v[204:207], v[184:187], v[16:19]
	v_mfma_f32_16x16x32_bf16 v[16:19], v[60:63], v[212:215], v[164:167]
	v_mfma_f32_16x16x32_bf16 v[20:23], v[200:203], v[212:215], v[168:171]
	v_mfma_f32_16x16x32_bf16 v[0:3], v[60:63], v[232:235], v[0:3]
	v_mfma_f32_16x16x32_bf16 v[4:7], v[200:203], v[232:235], v[4:7]
	v_mfma_f32_16x16x32_bf16 v[16:19], v[176:179], v[228:231], v[16:19]
	v_mfma_f32_16x16x32_bf16 v[20:23], v[204:207], v[228:231], v[20:23]
	v_mfma_f32_16x16x32_bf16 v[0:3], v[176:179], v[236:239], v[0:3]
	v_mfma_f32_16x16x32_bf16 v[4:7], v[204:207], v[236:239], v[4:7]
	v_mfma_f32_16x16x32_bf16 v[8:11], v[208:211], v[56:59], v[8:11]
	v_mfma_f32_16x16x32_bf16 v[88:91], v[216:219], v[92:95], v[8:11]
	v_mfma_f32_16x16x32_bf16 v[8:11], v[220:223], v[56:59], v[12:15]
	v_mfma_f32_16x16x32_bf16 v[92:95], v[224:227], v[92:95], v[8:11]
	v_mfma_f32_16x16x32_bf16 v[8:11], v[208:211], v[180:183], v[24:27]
	v_mfma_f32_16x16x32_bf16 v[56:59], v[216:219], v[184:187], v[8:11]
	v_mfma_f32_16x16x32_bf16 v[8:11], v[220:223], v[180:183], v[28:31]
	v_mfma_f32_16x16x32_bf16 v[60:63], v[224:227], v[184:187], v[8:11]
	v_mfma_f32_16x16x32_bf16 v[8:11], v[208:211], v[212:215], v[188:191]
	v_mfma_f32_16x16x32_bf16 v[24:27], v[216:219], v[228:231], v[8:11]
	v_mfma_f32_16x16x32_bf16 v[8:11], v[220:223], v[212:215], v[192:195]
	v_mfma_f32_16x16x32_bf16 v[28:31], v[224:227], v[228:231], v[8:11]
	v_mfma_f32_16x16x32_bf16 v[8:11], v[208:211], v[232:235], v[196:199]
	v_mfma_f32_16x16x32_bf16 v[12:15], v[220:223], v[232:235], v[172:175]
	v_mfma_f32_16x16x32_bf16 v[8:11], v[216:219], v[236:239], v[8:11]
	v_mfma_f32_16x16x32_bf16 v[12:15], v[224:227], v[236:239], v[12:15]
	s_barrier
	s_andn2_b64 vcc, exec, s[16:17]
	s_cbranch_vccnz .Lp9a_1350
	s_barrier

; #define PG8_STAGE(bufoff, gbase, voff) do { _Pragma("unroll") for (int _i = 0; _i < 2; ++_i) \
;         __builtin_amdgcn_global_load_lds((const unsigned*)((const char*)(gbase) + (voff)[_i]), (LAS unsigned*)(lds + (bufoff) + ldsw + _i * 8192), 16, 0, 0); } while (0)
; #define PG8_LDA(dst, b, h) do { _Pragma("unroll") for (int m = 0; m < 4; ++m) _Pragma("unroll") for (int k = 0; k < 2; ++k) dst[m][k] = *(const LAS bf16x8*)(lds + PG8_SA(b, h) + aoff + m * 2048 + k * 1024); } while (0)
; #define PG8_LDB(dst, b, h) do { _Pragma("unroll") for (int n = 0; n < 2; ++n) _Pragma("unroll") for (int k = 0; k < 2; ++k) dst[n][k] = *(const LAS bf16x8*)(lds + PG8_SB(b, h) + boff + n * 2048 + k * 1024); } while (0)
; #define PG8_MMA(ai, bj, At, Bt) do { __builtin_amdgcn_s_setprio(1); _Pragma("unroll") for (int m = 0; m < 4; ++m) _Pragma("unroll") for (int n = 0; n < 2; ++n) _Pragma("unroll") for (int k = 0; k < 2; ++k) \
;         acc[ai][bj][m][n] = __builtin_amdgcn_mfma_f32_16x16x32_bf16(Bt[n][k], At[m][k], acc[ai][bj][m][n], 0, 0, 0); __builtin_amdgcn_s_setprio(0); } while (0)
; #define PG8_WAIT_V(n) asm volatile("s_waitcnt vmcnt(" #n ")" ::: "memory")
; #define PG8_WAIT_L(n) asm volatile("s_waitcnt lgkmcnt(" #n ")" ::: "memory")
; #define PG8_BAR __builtin_amdgcn_s_barrier()
; #define PG8_SCHED __builtin_amdgcn_sched_barrier(0)
; template <class Epi>
; __device__ __forceinline__ void gemm_phase(LAS unsigned char* lds, const Gemm g, const StaticOrder& S, const Epi& E, int wave_s) {
;     ...
;             PG8_LDB(B0, 0, 0); PG8_LDB(B1, 0, 1); PG8_SCHED; PG8_LDA(At, 0, 0); PG8_STAGE(PG8_SA(1, 1), a1 + hstepA, voffA);
;             PG8_WAIT_V(8); PG8_WAIT_L(0); PG8_BAR; PG8_MMA(0, 0, At, B0); PG8_MMA(0, 1, At, B1); PG8_BAR; PG8_SCHED;
;             PG8_LDA(At, 0, 1); PG8_STAGE(PG8_SB(0, 0), b2, voffB); PG8_STAGE(PG8_SB(0, 1), b2 + hstepB, voffB); PG8_STAGE(PG8_SA(0, 0), a2, voffA);
.LBB0_1288:
	ds_read_b128 v[128:131], v159
	ds_read_b128 v[132:135], v159 offset:1024
	ds_read_b128 v[152:155], v159 offset:2048
	ds_read_b128 v[162:165], v159 offset:3072
	ds_read_b128 v[166:169], v160
	ds_read_b128 v[170:173], v160 offset:1024
	ds_read_b128 v[174:177], v160 offset:2048
	ds_read_b128 v[178:181], v160 offset:3072
	s_add_u32 s34, s30, 0x100
	s_addc_u32 s35, s31, 0
	s_cmpk_eq_i32 s58, 0x54
	s_cselect_b32 s39, s5, s35
	s_cselect_b32 s38, s4, s34
	s_cselect_b32 s37, s29, s57
	s_cselect_b32 s36, s28, s56
	v_lshl_add_u64 v[214:215], s[30:31], 0, v[144:145]
	s_add_i32 m0, s42, 0xc000
	ds_read_b128 v[182:185], v161
	ds_read_b128 v[186:189], v161 offset:1024
	ds_read_b128 v[190:193], v161 offset:2048
	ds_read_b128 v[194:197], v161 offset:3072
	ds_read_b128 v[198:201], v161 offset:4096
	ds_read_b128 v[202:205], v161 offset:5120
	ds_read_b128 v[206:209], v161 offset:6144
	ds_read_b128 v[210:213], v161 offset:7168
	global_load_lds_dwordx4 v[214:215], off
	v_lshl_add_u64 v[214:215], s[30:31], 0, v[146:147]
	s_add_i32 m0, s42, 0xe000
	s_nop 0
	global_load_lds_dwordx4 v[214:215], off
	s_waitcnt vmcnt(8)
	s_waitcnt lgkmcnt(0)
	s_barrier
	s_waitcnt lgkmcnt(0)
	v_mfma_f32_16x16x32_bf16 v[124:127], v[128:131], v[182:185], v[124:127]
	v_mfma_f32_16x16x32_bf16 v[120:123], v[152:155], v[182:185], v[120:123]
	v_mfma_f32_16x16x32_bf16 v[116:119], v[128:131], v[190:193], v[116:119]
	v_mfma_f32_16x16x32_bf16 v[108:111], v[152:155], v[190:193], v[108:111]
	v_mfma_f32_16x16x32_bf16 v[100:103], v[128:131], v[198:201], v[100:103]
	v_mfma_f32_16x16x32_bf16 v[92:95], v[152:155], v[198:201], v[92:95]
	v_mfma_f32_16x16x32_bf16 v[84:87], v[128:131], v[206:209], v[84:87]
	v_mfma_f32_16x16x32_bf16 v[76:79], v[152:155], v[206:209], v[76:79]
	v_mfma_f32_16x16x32_bf16 v[124:127], v[132:135], v[186:189], v[124:127]
	v_mfma_f32_16x16x32_bf16 v[120:123], v[162:165], v[186:189], v[120:123]
	v_mfma_f32_16x16x32_bf16 v[116:119], v[132:135], v[194:197], v[116:119]
	v_mfma_f32_16x16x32_bf16 v[108:111], v[162:165], v[194:197], v[108:111]
	v_mfma_f32_16x16x32_bf16 v[100:103], v[132:135], v[202:205], v[100:103]
	v_mfma_f32_16x16x32_bf16 v[92:95], v[162:165], v[202:205], v[92:95]
	v_mfma_f32_16x16x32_bf16 v[84:87], v[132:135], v[210:213], v[84:87]
	v_mfma_f32_16x16x32_bf16 v[76:79], v[162:165], v[210:213], v[76:79]
	v_mfma_f32_16x16x32_bf16 v[112:115], v[166:169], v[182:185], v[112:115]
	v_mfma_f32_16x16x32_bf16 v[104:107], v[174:177], v[182:185], v[104:107]
	v_mfma_f32_16x16x32_bf16 v[96:99], v[166:169], v[190:193], v[96:99]
	v_mfma_f32_16x16x32_bf16 v[88:91], v[174:177], v[190:193], v[88:91]
	v_mfma_f32_16x16x32_bf16 v[80:83], v[166:169], v[198:201], v[80:83]
	v_mfma_f32_16x16x32_bf16 v[72:75], v[174:177], v[198:201], v[72:75]
	v_mfma_f32_16x16x32_bf16 v[68:71], v[166:169], v[206:209], v[68:71]
	v_mfma_f32_16x16x32_bf16 v[64:67], v[174:177], v[206:209], v[64:67]
	v_mfma_f32_16x16x32_bf16 v[112:115], v[170:173], v[186:189], v[112:115]
	v_mfma_f32_16x16x32_bf16 v[104:107], v[178:181], v[186:189], v[104:107]
	v_mfma_f32_16x16x32_bf16 v[96:99], v[170:173], v[194:197], v[96:99]
	v_mfma_f32_16x16x32_bf16 v[88:91], v[178:181], v[194:197], v[88:91]
	v_mfma_f32_16x16x32_bf16 v[80:83], v[170:173], v[202:205], v[80:83]
	v_mfma_f32_16x16x32_bf16 v[72:75], v[178:181], v[202:205], v[72:75]
	v_mfma_f32_16x16x32_bf16 v[68:71], v[170:173], v[210:213], v[68:71]
	v_mfma_f32_16x16x32_bf16 v[64:67], v[178:181], v[210:213], v[64:67]
	s_barrier
	s_add_i32 s30, s50, s41
	v_lshl_add_u64 v[214:215], s[36:37], 0, v[138:139]
	s_mov_b32 m0, s30
	ds_read_b128 v[182:185], v161 offset:16384
	ds_read_b128 v[186:189], v161 offset:17408
	ds_read_b128 v[190:193], v161 offset:18432
	ds_read_b128 v[194:197], v161 offset:19456
	ds_read_b128 v[198:201], v161 offset:20480
	ds_read_b128 v[202:205], v161 offset:21504
	ds_read_b128 v[206:209], v161 offset:22528
	ds_read_b128 v[210:213], v161 offset:23552
	global_load_lds_dwordx4 v[214:215], off
	s_add_i32 m0, s30, 0x2000
	s_add_u32 s30, s36, 0x160000
	v_lshl_add_u64 v[216:217], s[36:37], 0, v[142:143]
	s_addc_u32 s31, s37, 0
	s_add_i32 s59, s51, s41
	global_load_lds_dwordx4 v[216:217], off
	v_lshl_add_u64 v[218:219], s[30:31], 0, v[138:139]
	s_mov_b32 m0, s59
	v_lshl_add_u64 v[220:221], s[38:39], 0, v[140:141]
	global_load_lds_dwordx4 v[218:219], off
	v_lshl_add_u64 v[218:219], s[30:31], 0, v[142:143]
	s_add_i32 m0, s59, 0x2000
	s_nop 0
	global_load_lds_dwordx4 v[218:219], off
	v_lshl_add_u64 v[218:219], s[38:39], 0, v[136:137]
	s_mov_b32 m0, s42
	s_nop 0
	global_load_lds_dwordx4 v[218:219], off
	s_mov_b32 m0, s43
	s_nop 0
	global_load_lds_dwordx4 v[220:221], off
	s_waitcnt vmcnt(8)
	s_waitcnt lgkmcnt(0)
	s_barrier
; #define PG8_STAGE(bufoff, gbase, voff) do { _Pragma("unroll") for (int _i = 0; _i < 2; ++_i) \
;         __builtin_amdgcn_global_load_lds((const unsigned*)((const char*)(gbase) + (voff)[_i]), (LAS unsigned*)(lds + (bufoff) + ldsw + _i * 8192), 16, 0, 0); } while (0)
; #define PG8_LDA(dst, b, h) do { _Pragma("unroll") for (int m = 0; m < 4; ++m) _Pragma("unroll") for (int k = 0; k < 2; ++k) dst[m][k] = *(const LAS bf16x8*)(lds + PG8_SA(b, h) + aoff + m * 2048 + k * 1024); } while (0)
; #define PG8_LDB(dst, b, h) do { _Pragma("unroll") for (int n = 0; n < 2; ++n) _Pragma("unroll") for (int k = 0; k < 2; ++k) dst[n][k] = *(const LAS bf16x8*)(lds + PG8_SB(b, h) + boff + n * 2048 + k * 1024); } while (0)
; #define PG8_MMA(ai, bj, At, Bt) do { __builtin_amdgcn_s_setprio(1); _Pragma("unroll") for (int m = 0; m < 4; ++m) _Pragma("unroll") for (int n = 0; n < 2; ++n) _Pragma("unroll") for (int k = 0; k < 2; ++k) \
;         acc[ai][bj][m][n] = __builtin_amdgcn_mfma_f32_16x16x32_bf16(Bt[n][k], At[m][k], acc[ai][bj][m][n], 0, 0, 0); __builtin_amdgcn_s_setprio(0); } while (0)
; #define PG8_WAIT_V(n) asm volatile("s_waitcnt vmcnt(" #n ")" ::: "memory")
; #define PG8_WAIT_L(n) asm volatile("s_waitcnt lgkmcnt(" #n ")" ::: "memory")
; #define PG8_BAR __builtin_amdgcn_s_barrier()
; #define PG8_SCHED __builtin_amdgcn_sched_barrier(0)
; template <class Epi>
; __device__ __forceinline__ void gemm_phase(LAS unsigned char* lds, const Gemm g, const StaticOrder& S, const Epi& E, int wave_s) {
;     ...
;             PG8_WAIT_V(8); PG8_WAIT_L(0); PG8_BAR; PG8_MMA(1, 0, At, B0); PG8_MMA(1, 1, At, B1); PG8_BAR; PG8_SCHED;
;             PG8_LDB(B0, 1, 0); PG8_LDB(B1, 1, 1); PG8_SCHED; PG8_LDA(At, 1, 0); PG8_STAGE(PG8_SA(0, 1), a2 + hstepA, voffA);
;             PG8_WAIT_V(8); PG8_WAIT_L(0); PG8_BAR; PG8_MMA(0, 0, At, B0); PG8_MMA(0, 1, At, B1); PG8_BAR; PG8_SCHED;
	s_waitcnt lgkmcnt(0)
	v_mfma_f32_16x16x32_bf16 v[60:63], v[128:131], v[182:185], v[60:63]
	v_mfma_f32_16x16x32_bf16 v[56:59], v[152:155], v[182:185], v[56:59]
	v_mfma_f32_16x16x32_bf16 v[44:47], v[128:131], v[190:193], v[44:47]
	v_mfma_f32_16x16x32_bf16 v[40:43], v[152:155], v[190:193], v[40:43]
	v_mfma_f32_16x16x32_bf16 v[28:31], v[128:131], v[198:201], v[28:31]
	v_mfma_f32_16x16x32_bf16 v[24:27], v[152:155], v[198:201], v[24:27]
	v_mfma_f32_16x16x32_bf16 v[12:15], v[128:131], v[206:209], v[12:15]
	v_mfma_f32_16x16x32_bf16 v[8:11], v[152:155], v[206:209], v[8:11]
	v_mfma_f32_16x16x32_bf16 v[60:63], v[132:135], v[186:189], v[60:63]
	v_mfma_f32_16x16x32_bf16 v[56:59], v[162:165], v[186:189], v[56:59]
	v_mfma_f32_16x16x32_bf16 v[44:47], v[132:135], v[194:197], v[44:47]
	v_mfma_f32_16x16x32_bf16 v[40:43], v[162:165], v[194:197], v[40:43]
	v_mfma_f32_16x16x32_bf16 v[28:31], v[132:135], v[202:205], v[28:31]
	v_mfma_f32_16x16x32_bf16 v[24:27], v[162:165], v[202:205], v[24:27]
	v_mfma_f32_16x16x32_bf16 v[12:15], v[132:135], v[210:213], v[12:15]
	v_mfma_f32_16x16x32_bf16 v[8:11], v[162:165], v[210:213], v[8:11]
	v_mfma_f32_16x16x32_bf16 v[52:55], v[166:169], v[182:185], v[52:55]
	v_mfma_f32_16x16x32_bf16 v[48:51], v[174:177], v[182:185], v[48:51]
	v_mfma_f32_16x16x32_bf16 v[36:39], v[166:169], v[190:193], v[36:39]
	v_mfma_f32_16x16x32_bf16 v[32:35], v[174:177], v[190:193], v[32:35]
	v_mfma_f32_16x16x32_bf16 v[20:23], v[166:169], v[198:201], v[20:23]
	v_mfma_f32_16x16x32_bf16 v[16:19], v[174:177], v[198:201], v[16:19]
	v_mfma_f32_16x16x32_bf16 v[4:7], v[166:169], v[206:209], v[4:7]
	v_mfma_f32_16x16x32_bf16 v[0:3], v[174:177], v[206:209], v[0:3]
	v_mfma_f32_16x16x32_bf16 v[52:55], v[170:173], v[186:189], v[52:55]
	v_mfma_f32_16x16x32_bf16 v[48:51], v[178:181], v[186:189], v[48:51]
	v_mfma_f32_16x16x32_bf16 v[36:39], v[170:173], v[194:197], v[36:39]
	v_mfma_f32_16x16x32_bf16 v[32:35], v[178:181], v[194:197], v[32:35]
	v_mfma_f32_16x16x32_bf16 v[20:23], v[170:173], v[202:205], v[20:23]
	v_mfma_f32_16x16x32_bf16 v[16:19], v[178:181], v[202:205], v[16:19]
	v_mfma_f32_16x16x32_bf16 v[4:7], v[170:173], v[210:213], v[4:7]
	v_mfma_f32_16x16x32_bf16 v[0:3], v[178:181], v[210:213], v[0:3]
	s_barrier
	s_add_i32 s59, 0, 0x18000
	s_add_i32 s60, 0, 0x1c000
	v_add_u32_e32 v162, s59, v157
	v_add_u32_e32 v178, s60, v157
	ds_read_b128 v[128:131], v162
	ds_read_b128 v[132:135], v162 offset:1024
	ds_read_b128 v[152:155], v162 offset:2048
	ds_read_b128 v[162:165], v162 offset:3072
	ds_read_b128 v[166:169], v178
	ds_read_b128 v[170:173], v178 offset:1024
	ds_read_b128 v[174:177], v178 offset:2048
	ds_read_b128 v[178:181], v178 offset:3072
	s_add_u32 s30, s38, 0x160000
	s_addc_u32 s31, s39, 0
	s_mov_b32 m0, s44
	v_lshl_add_u64 v[222:223], s[30:31], 0, v[136:137]
	ds_read_b128 v[182:185], v161 offset:32768
	ds_read_b128 v[186:189], v161 offset:33792
	ds_read_b128 v[190:193], v161 offset:34816
	ds_read_b128 v[194:197], v161 offset:35840
	ds_read_b128 v[198:201], v161 offset:36864
	ds_read_b128 v[202:205], v161 offset:37888
	ds_read_b128 v[206:209], v161 offset:38912
	ds_read_b128 v[210:213], v161 offset:39936
	global_load_lds_dwordx4 v[222:223], off
	v_lshl_add_u64 v[222:223], s[30:31], 0, v[140:141]
	s_mov_b32 m0, s45
	s_nop 0
	global_load_lds_dwordx4 v[222:223], off
	s_waitcnt vmcnt(8)
	s_waitcnt lgkmcnt(0)
	s_barrier
	s_waitcnt lgkmcnt(0)
	v_mfma_f32_16x16x32_bf16 v[124:127], v[128:131], v[182:185], v[124:127]
	v_mfma_f32_16x16x32_bf16 v[120:123], v[152:155], v[182:185], v[120:123]
	v_mfma_f32_16x16x32_bf16 v[116:119], v[128:131], v[190:193], v[116:119]
	v_mfma_f32_16x16x32_bf16 v[108:111], v[152:155], v[190:193], v[108:111]
	v_mfma_f32_16x16x32_bf16 v[100:103], v[128:131], v[198:201], v[100:103]
	v_mfma_f32_16x16x32_bf16 v[92:95], v[152:155], v[198:201], v[92:95]
	v_mfma_f32_16x16x32_bf16 v[84:87], v[128:131], v[206:209], v[84:87]
	v_mfma_f32_16x16x32_bf16 v[76:79], v[152:155], v[206:209], v[76:79]
	v_mfma_f32_16x16x32_bf16 v[124:127], v[132:135], v[186:189], v[124:127]
	v_mfma_f32_16x16x32_bf16 v[120:123], v[162:165], v[186:189], v[120:123]
	v_mfma_f32_16x16x32_bf16 v[116:119], v[132:135], v[194:197], v[116:119]
	v_mfma_f32_16x16x32_bf16 v[108:111], v[162:165], v[194:197], v[108:111]
	v_mfma_f32_16x16x32_bf16 v[100:103], v[132:135], v[202:205], v[100:103]
	v_mfma_f32_16x16x32_bf16 v[92:95], v[162:165], v[202:205], v[92:95]
	v_mfma_f32_16x16x32_bf16 v[84:87], v[132:135], v[210:213], v[84:87]
	v_mfma_f32_16x16x32_bf16 v[76:79], v[162:165], v[210:213], v[76:79]
	v_mfma_f32_16x16x32_bf16 v[112:115], v[166:169], v[182:185], v[112:115]
	v_mfma_f32_16x16x32_bf16 v[104:107], v[174:177], v[182:185], v[104:107]
	v_mfma_f32_16x16x32_bf16 v[96:99], v[166:169], v[190:193], v[96:99]
	v_mfma_f32_16x16x32_bf16 v[88:91], v[174:177], v[190:193], v[88:91]
	v_mfma_f32_16x16x32_bf16 v[80:83], v[166:169], v[198:201], v[80:83]
	v_mfma_f32_16x16x32_bf16 v[72:75], v[174:177], v[198:201], v[72:75]
	v_mfma_f32_16x16x32_bf16 v[68:71], v[166:169], v[206:209], v[68:71]
	v_mfma_f32_16x16x32_bf16 v[64:67], v[174:177], v[206:209], v[64:67]
	v_mfma_f32_16x16x32_bf16 v[112:115], v[170:173], v[186:189], v[112:115]
	v_mfma_f32_16x16x32_bf16 v[104:107], v[178:181], v[186:189], v[104:107]
	v_mfma_f32_16x16x32_bf16 v[96:99], v[170:173], v[194:197], v[96:99]
	v_mfma_f32_16x16x32_bf16 v[88:91], v[178:181], v[194:197], v[88:91]
	v_mfma_f32_16x16x32_bf16 v[80:83], v[170:173], v[202:205], v[80:83]
	v_mfma_f32_16x16x32_bf16 v[72:75], v[178:181], v[202:205], v[72:75]
	v_mfma_f32_16x16x32_bf16 v[68:71], v[170:173], v[210:213], v[68:71]
	v_mfma_f32_16x16x32_bf16 v[64:67], v[178:181], v[210:213], v[64:67]
	s_barrier
; #define PG8_STAGE(bufoff, gbase, voff) do { _Pragma("unroll") for (int _i = 0; _i < 2; ++_i) \
;         __builtin_amdgcn_global_load_lds((const unsigned*)((const char*)(gbase) + (voff)[_i]), (LAS unsigned*)(lds + (bufoff) + ldsw + _i * 8192), 16, 0, 0); } while (0)
; #define PG8_LDA(dst, b, h) do { _Pragma("unroll") for (int m = 0; m < 4; ++m) _Pragma("unroll") for (int k = 0; k < 2; ++k) dst[m][k] = *(const LAS bf16x8*)(lds + PG8_SA(b, h) + aoff + m * 2048 + k * 1024); } while (0)
; #define PG8_MMA(ai, bj, At, Bt) do { __builtin_amdgcn_s_setprio(1); _Pragma("unroll") for (int m = 0; m < 4; ++m) _Pragma("unroll") for (int n = 0; n < 2; ++n) _Pragma("unroll") for (int k = 0; k < 2; ++k) \
;         acc[ai][bj][m][n] = __builtin_amdgcn_mfma_f32_16x16x32_bf16(Bt[n][k], At[m][k], acc[ai][bj][m][n], 0, 0, 0); __builtin_amdgcn_s_setprio(0); } while (0)
; #define PG8_WAIT_V(n) asm volatile("s_waitcnt vmcnt(" #n ")" ::: "memory")
; #define PG8_WAIT_L(n) asm volatile("s_waitcnt lgkmcnt(" #n ")" ::: "memory")
; #define PG8_BAR __builtin_amdgcn_s_barrier()
; #define PG8_SCHED __builtin_amdgcn_sched_barrier(0)
; template <class Epi>
; __device__ __forceinline__ void gemm_phase(LAS unsigned char* lds, const Gemm g, const StaticOrder& S, const Epi& E, int wave_s) {
;     ...
;             PG8_LDA(At, 1, 1); PG8_STAGE(PG8_SB(1, 0), b3, voffB); PG8_STAGE(PG8_SB(1, 1), b3 + hstepB, voffB); PG8_STAGE(PG8_SA(1, 0), a3, voffA);
;             PG8_WAIT_V(8); PG8_WAIT_L(0); PG8_BAR; PG8_MMA(1, 0, At, B0); PG8_MMA(1, 1, At, B1); PG8_BAR; PG8_SCHED;
;         }
	s_add_i32 s30, s59, s41
	v_lshl_add_u64 v[214:215], v[214:215], 0, s[16:17]
	s_mov_b32 m0, s30
	ds_read_b128 v[182:185], v161 offset:49152
	ds_read_b128 v[186:189], v161 offset:50176
	ds_read_b128 v[190:193], v161 offset:51200
	ds_read_b128 v[194:197], v161 offset:52224
	ds_read_b128 v[198:201], v161 offset:53248
	ds_read_b128 v[202:205], v161 offset:54272
	ds_read_b128 v[206:209], v161 offset:55296
	ds_read_b128 v[210:213], v161 offset:56320
	global_load_lds_dwordx4 v[214:215], off
	s_add_i32 m0, s30, 0x2000
	s_add_u32 s30, s36, 0x160080
	v_lshl_add_u64 v[214:215], v[216:217], 0, s[16:17]
	s_addc_u32 s31, s37, 0
	s_add_i32 s36, s60, s41
	global_load_lds_dwordx4 v[214:215], off
	v_lshl_add_u64 v[214:215], s[30:31], 0, v[138:139]
	s_mov_b32 m0, s36
	s_nop 0
	global_load_lds_dwordx4 v[214:215], off
	v_lshl_add_u64 v[214:215], s[30:31], 0, v[142:143]
	s_add_i32 m0, s36, 0x2000
	s_nop 0
	global_load_lds_dwordx4 v[214:215], off
	v_lshl_add_u64 v[214:215], v[218:219], 0, s[16:17]
	s_mov_b32 m0, s47
	s_nop 0
	global_load_lds_dwordx4 v[214:215], off
	v_lshl_add_u64 v[214:215], v[220:221], 0, s[16:17]
	s_mov_b32 m0, s48
	s_nop 0
	global_load_lds_dwordx4 v[214:215], off
	s_waitcnt vmcnt(8)
	s_waitcnt lgkmcnt(0)
	s_barrier
	s_waitcnt lgkmcnt(0)
	v_mfma_f32_16x16x32_bf16 v[60:63], v[128:131], v[182:185], v[60:63]
	v_mfma_f32_16x16x32_bf16 v[56:59], v[152:155], v[182:185], v[56:59]
	v_mfma_f32_16x16x32_bf16 v[44:47], v[128:131], v[190:193], v[44:47]
	v_mfma_f32_16x16x32_bf16 v[40:43], v[152:155], v[190:193], v[40:43]
	v_mfma_f32_16x16x32_bf16 v[28:31], v[128:131], v[198:201], v[28:31]
	v_mfma_f32_16x16x32_bf16 v[24:27], v[152:155], v[198:201], v[24:27]
	v_mfma_f32_16x16x32_bf16 v[12:15], v[128:131], v[206:209], v[12:15]
	v_mfma_f32_16x16x32_bf16 v[8:11], v[152:155], v[206:209], v[8:11]
	v_mfma_f32_16x16x32_bf16 v[60:63], v[132:135], v[186:189], v[60:63]
	v_mfma_f32_16x16x32_bf16 v[56:59], v[162:165], v[186:189], v[56:59]
	v_mfma_f32_16x16x32_bf16 v[44:47], v[132:135], v[194:197], v[44:47]
	v_mfma_f32_16x16x32_bf16 v[40:43], v[162:165], v[194:197], v[40:43]
	v_mfma_f32_16x16x32_bf16 v[28:31], v[132:135], v[202:205], v[28:31]
	v_mfma_f32_16x16x32_bf16 v[24:27], v[162:165], v[202:205], v[24:27]
	v_mfma_f32_16x16x32_bf16 v[12:15], v[132:135], v[210:213], v[12:15]
	v_mfma_f32_16x16x32_bf16 v[8:11], v[162:165], v[210:213], v[8:11]
	v_mfma_f32_16x16x32_bf16 v[52:55], v[166:169], v[182:185], v[52:55]
	v_mfma_f32_16x16x32_bf16 v[48:51], v[174:177], v[182:185], v[48:51]
	v_mfma_f32_16x16x32_bf16 v[36:39], v[166:169], v[190:193], v[36:39]
	v_mfma_f32_16x16x32_bf16 v[32:35], v[174:177], v[190:193], v[32:35]
	v_mfma_f32_16x16x32_bf16 v[20:23], v[166:169], v[198:201], v[20:23]
	v_mfma_f32_16x16x32_bf16 v[16:19], v[174:177], v[198:201], v[16:19]
	v_mfma_f32_16x16x32_bf16 v[4:7], v[166:169], v[206:209], v[4:7]
	v_mfma_f32_16x16x32_bf16 v[0:3], v[174:177], v[206:209], v[0:3]
	v_mfma_f32_16x16x32_bf16 v[52:55], v[170:173], v[186:189], v[52:55]
	v_mfma_f32_16x16x32_bf16 v[48:51], v[178:181], v[186:189], v[48:51]
	v_mfma_f32_16x16x32_bf16 v[36:39], v[170:173], v[194:197], v[36:39]
	v_mfma_f32_16x16x32_bf16 v[32:35], v[178:181], v[194:197], v[32:35]
	v_mfma_f32_16x16x32_bf16 v[20:23], v[170:173], v[202:205], v[20:23]
	v_mfma_f32_16x16x32_bf16 v[16:19], v[178:181], v[202:205], v[16:19]
	v_mfma_f32_16x16x32_bf16 v[4:7], v[170:173], v[210:213], v[4:7]
	v_mfma_f32_16x16x32_bf16 v[0:3], v[178:181], v[210:213], v[0:3]
	s_barrier
	s_add_i32 s58, s58, 2
	s_add_u32 s56, s56, 0x100
	s_addc_u32 s57, s57, 0
	s_cmpk_gt_u32 s58, 0x55
	s_mov_b64 s[30:31], s[34:35]
	s_cbranch_scc0 .LBB0_1288
	s_and_b64 vcc, exec, s[26:27]
	s_cbranch_vccz .LBB0_1291
	s_barrier

; #define PG8_STAGE(bufoff, gbase, voff) do { _Pragma("unroll") for (int _i = 0; _i < 2; ++_i) \
;         __builtin_amdgcn_global_load_lds((const unsigned*)((const char*)(gbase) + (voff)[_i]), (LAS unsigned*)(lds + (bufoff) + ldsw + _i * 8192), 16, 0, 0); } while (0)
; #define PG8_LDA(dst, b, h) do { _Pragma("unroll") for (int m = 0; m < 4; ++m) _Pragma("unroll") for (int k = 0; k < 2; ++k) dst[m][k] = *(const LAS bf16x8*)(lds + PG8_SA(b, h) + aoff + m * 2048 + k * 1024); } while (0)
; #define PG8_LDB(dst, b, h) do { _Pragma("unroll") for (int n = 0; n < 2; ++n) _Pragma("unroll") for (int k = 0; k < 2; ++k) dst[n][k] = *(const LAS bf16x8*)(lds + PG8_SB(b, h) + boff + n * 2048 + k * 1024); } while (0)
; #define PG8_MMA(ai, bj, At, Bt) do { __builtin_amdgcn_s_setprio(1); _Pragma("unroll") for (int m = 0; m < 4; ++m) _Pragma("unroll") for (int n = 0; n < 2; ++n) _Pragma("unroll") for (int k = 0; k < 2; ++k) \
;         acc[ai][bj][m][n] = __builtin_amdgcn_mfma_f32_16x16x32_bf16(Bt[n][k], At[m][k], acc[ai][bj][m][n], 0, 0, 0); __builtin_amdgcn_s_setprio(0); } while (0)
; #define PG8_WAIT_V(n) asm volatile("s_waitcnt vmcnt(" #n ")" ::: "memory")
; #define PG8_WAIT_L(n) asm volatile("s_waitcnt lgkmcnt(" #n ")" ::: "memory")
; #define PG8_BAR __builtin_amdgcn_s_barrier()
; #define PG8_SCHED __builtin_amdgcn_sched_barrier(0)
; template <class Epi>
; __device__ __forceinline__ void gemm_phase(LAS unsigned char* lds, const Gemm g, const StaticOrder& S, const Epi& E, int wave_s) {
;     ...
;             PG8_LDB(B0, 0, 0); PG8_LDB(B1, 0, 1); PG8_SCHED; PG8_LDA(At, 0, 0); PG8_STAGE(PG8_SA(1, 1), a1 + hstepA, voffA);
;             PG8_WAIT_V(8); PG8_WAIT_L(0); PG8_BAR; PG8_MMA(0, 0, At, B0); PG8_MMA(0, 1, At, B1); PG8_BAR; PG8_SCHED;
;             PG8_LDA(At, 0, 1); PG8_STAGE(PG8_SB(0, 0), b2, voffB); PG8_STAGE(PG8_SB(0, 1), b2 + hstepB, voffB); PG8_STAGE(PG8_SA(0, 0), a2, voffA);
.LBB0_1371:
	ds_read_b128 v[144:147], v151
	ds_read_b128 v[154:157], v151 offset:1024
	ds_read_b128 v[158:161], v151 offset:2048
	ds_read_b128 v[162:165], v151 offset:3072
	ds_read_b128 v[166:169], v152
	ds_read_b128 v[170:173], v152 offset:1024
	ds_read_b128 v[174:177], v152 offset:2048
	ds_read_b128 v[178:181], v152 offset:3072
	s_add_u32 s46, s44, 0xfff80080
	s_addc_u32 s47, s45, -1
	s_cmp_eq_u32 s64, 28
	s_cselect_b32 s49, s37, s47
	s_cselect_b32 s48, s60, s46
	s_cselect_b32 s47, s35, s63
	s_cselect_b32 s46, s61, s62
	v_lshl_add_u64 v[214:215], s[44:45], 0, v[136:137]
	s_add_i32 m0, s43, 0xc000
	ds_read_b128 v[182:185], v153
	ds_read_b128 v[186:189], v153 offset:1024
	ds_read_b128 v[190:193], v153 offset:2048
	ds_read_b128 v[194:197], v153 offset:3072
	ds_read_b128 v[198:201], v153 offset:4096
	ds_read_b128 v[202:205], v153 offset:5120
	ds_read_b128 v[206:209], v153 offset:6144
	ds_read_b128 v[210:213], v153 offset:7168
	global_load_lds_dwordx4 v[214:215], off
	v_lshl_add_u64 v[214:215], s[44:45], 0, v[138:139]
	s_add_i32 m0, s43, 0xe000
	s_nop 0
	global_load_lds_dwordx4 v[214:215], off
	s_waitcnt vmcnt(8)
	s_waitcnt lgkmcnt(0)
	s_barrier
	s_waitcnt lgkmcnt(0)
	v_mfma_f32_16x16x32_bf16 v[124:127], v[144:147], v[182:185], v[124:127]
	v_mfma_f32_16x16x32_bf16 v[120:123], v[158:161], v[182:185], v[120:123]
	v_mfma_f32_16x16x32_bf16 v[108:111], v[144:147], v[190:193], v[108:111]
	v_mfma_f32_16x16x32_bf16 v[104:107], v[158:161], v[190:193], v[104:107]
	v_mfma_f32_16x16x32_bf16 v[92:95], v[144:147], v[198:201], v[92:95]
	v_mfma_f32_16x16x32_bf16 v[88:91], v[158:161], v[198:201], v[88:91]
	v_mfma_f32_16x16x32_bf16 v[76:79], v[144:147], v[206:209], v[76:79]
	v_mfma_f32_16x16x32_bf16 v[72:75], v[158:161], v[206:209], v[72:75]
	v_mfma_f32_16x16x32_bf16 v[124:127], v[154:157], v[186:189], v[124:127]
	v_mfma_f32_16x16x32_bf16 v[120:123], v[162:165], v[186:189], v[120:123]
	v_mfma_f32_16x16x32_bf16 v[108:111], v[154:157], v[194:197], v[108:111]
	v_mfma_f32_16x16x32_bf16 v[104:107], v[162:165], v[194:197], v[104:107]
	v_mfma_f32_16x16x32_bf16 v[92:95], v[154:157], v[202:205], v[92:95]
	v_mfma_f32_16x16x32_bf16 v[88:91], v[162:165], v[202:205], v[88:91]
	v_mfma_f32_16x16x32_bf16 v[76:79], v[154:157], v[210:213], v[76:79]
	v_mfma_f32_16x16x32_bf16 v[72:75], v[162:165], v[210:213], v[72:75]
	v_mfma_f32_16x16x32_bf16 v[116:119], v[166:169], v[182:185], v[116:119]
	v_mfma_f32_16x16x32_bf16 v[112:115], v[174:177], v[182:185], v[112:115]
	v_mfma_f32_16x16x32_bf16 v[100:103], v[166:169], v[190:193], v[100:103]
	v_mfma_f32_16x16x32_bf16 v[96:99], v[174:177], v[190:193], v[96:99]
	v_mfma_f32_16x16x32_bf16 v[84:87], v[166:169], v[198:201], v[84:87]
	v_mfma_f32_16x16x32_bf16 v[80:83], v[174:177], v[198:201], v[80:83]
	v_mfma_f32_16x16x32_bf16 v[68:71], v[166:169], v[206:209], v[68:71]
	v_mfma_f32_16x16x32_bf16 v[64:67], v[174:177], v[206:209], v[64:67]
	v_mfma_f32_16x16x32_bf16 v[116:119], v[170:173], v[186:189], v[116:119]
	v_mfma_f32_16x16x32_bf16 v[112:115], v[178:181], v[186:189], v[112:115]
	v_mfma_f32_16x16x32_bf16 v[100:103], v[170:173], v[194:197], v[100:103]
	v_mfma_f32_16x16x32_bf16 v[96:99], v[178:181], v[194:197], v[96:99]
	v_mfma_f32_16x16x32_bf16 v[84:87], v[170:173], v[202:205], v[84:87]
	v_mfma_f32_16x16x32_bf16 v[80:83], v[178:181], v[202:205], v[80:83]
	v_mfma_f32_16x16x32_bf16 v[68:71], v[170:173], v[210:213], v[68:71]
	v_mfma_f32_16x16x32_bf16 v[64:67], v[178:181], v[210:213], v[64:67]
	s_barrier
	s_add_i32 s65, s57, s25
	v_lshl_add_u64 v[214:215], s[46:47], 0, v[130:131]
	s_mov_b32 m0, s65
	ds_read_b128 v[182:185], v153 offset:16384
	ds_read_b128 v[186:189], v153 offset:17408
	ds_read_b128 v[190:193], v153 offset:18432
	ds_read_b128 v[194:197], v153 offset:19456
	ds_read_b128 v[198:201], v153 offset:20480
	ds_read_b128 v[202:205], v153 offset:21504
	ds_read_b128 v[206:209], v153 offset:22528
	ds_read_b128 v[210:213], v153 offset:23552
	global_load_lds_dwordx4 v[214:215], off
	s_add_i32 m0, s65, 0x2000
	s_add_u32 s66, s46, 0x80000
	v_lshl_add_u64 v[216:217], s[46:47], 0, v[134:135]
	s_addc_u32 s67, s47, 0
	s_add_i32 s65, s58, s25
	global_load_lds_dwordx4 v[216:217], off
	v_lshl_add_u64 v[218:219], s[66:67], 0, v[130:131]
	s_mov_b32 m0, s65
	v_lshl_add_u64 v[220:221], s[48:49], 0, v[132:133]
	global_load_lds_dwordx4 v[218:219], off
	v_lshl_add_u64 v[218:219], s[66:67], 0, v[134:135]
	s_add_i32 m0, s65, 0x2000
	s_nop 0
	global_load_lds_dwordx4 v[218:219], off
	v_lshl_add_u64 v[218:219], s[48:49], 0, v[128:129]
	s_mov_b32 m0, s43
	s_nop 0
	global_load_lds_dwordx4 v[218:219], off
	s_mov_b32 m0, s50
	s_nop 0
	global_load_lds_dwordx4 v[220:221], off
	s_waitcnt vmcnt(8)
	s_waitcnt lgkmcnt(0)
	s_barrier
; #define PG8_STAGE(bufoff, gbase, voff) do { _Pragma("unroll") for (int _i = 0; _i < 2; ++_i) \
;         __builtin_amdgcn_global_load_lds((const unsigned*)((const char*)(gbase) + (voff)[_i]), (LAS unsigned*)(lds + (bufoff) + ldsw + _i * 8192), 16, 0, 0); } while (0)
; #define PG8_LDA(dst, b, h) do { _Pragma("unroll") for (int m = 0; m < 4; ++m) _Pragma("unroll") for (int k = 0; k < 2; ++k) dst[m][k] = *(const LAS bf16x8*)(lds + PG8_SA(b, h) + aoff + m * 2048 + k * 1024); } while (0)
; #define PG8_LDB(dst, b, h) do { _Pragma("unroll") for (int n = 0; n < 2; ++n) _Pragma("unroll") for (int k = 0; k < 2; ++k) dst[n][k] = *(const LAS bf16x8*)(lds + PG8_SB(b, h) + boff + n * 2048 + k * 1024); } while (0)
; #define PG8_MMA(ai, bj, At, Bt) do { __builtin_amdgcn_s_setprio(1); _Pragma("unroll") for (int m = 0; m < 4; ++m) _Pragma("unroll") for (int n = 0; n < 2; ++n) _Pragma("unroll") for (int k = 0; k < 2; ++k) \
;         acc[ai][bj][m][n] = __builtin_amdgcn_mfma_f32_16x16x32_bf16(Bt[n][k], At[m][k], acc[ai][bj][m][n], 0, 0, 0); __builtin_amdgcn_s_setprio(0); } while (0)
; #define PG8_WAIT_V(n) asm volatile("s_waitcnt vmcnt(" #n ")" ::: "memory")
; #define PG8_WAIT_L(n) asm volatile("s_waitcnt lgkmcnt(" #n ")" ::: "memory")
; #define PG8_BAR __builtin_amdgcn_s_barrier()
; #define PG8_SCHED __builtin_amdgcn_sched_barrier(0)
; template <class Epi>
; __device__ __forceinline__ void gemm_phase(LAS unsigned char* lds, const Gemm g, const StaticOrder& S, const Epi& E, int wave_s) {
;     ...
;             PG8_WAIT_V(8); PG8_WAIT_L(0); PG8_BAR; PG8_MMA(1, 0, At, B0); PG8_MMA(1, 1, At, B1); PG8_BAR; PG8_SCHED;
;             PG8_LDB(B0, 1, 0); PG8_LDB(B1, 1, 1); PG8_SCHED; PG8_LDA(At, 1, 0); PG8_STAGE(PG8_SA(0, 1), a2 + hstepA, voffA);
;             PG8_WAIT_V(8); PG8_WAIT_L(0); PG8_BAR; PG8_MMA(0, 0, At, B0); PG8_MMA(0, 1, At, B1); PG8_BAR; PG8_SCHED;
	s_waitcnt lgkmcnt(0)
	v_mfma_f32_16x16x32_bf16 v[60:63], v[144:147], v[182:185], v[60:63]
	v_mfma_f32_16x16x32_bf16 v[56:59], v[158:161], v[182:185], v[56:59]
	v_mfma_f32_16x16x32_bf16 v[44:47], v[144:147], v[190:193], v[44:47]
	v_mfma_f32_16x16x32_bf16 v[40:43], v[158:161], v[190:193], v[40:43]
	v_mfma_f32_16x16x32_bf16 v[28:31], v[144:147], v[198:201], v[28:31]
	v_mfma_f32_16x16x32_bf16 v[24:27], v[158:161], v[198:201], v[24:27]
	v_mfma_f32_16x16x32_bf16 v[12:15], v[144:147], v[206:209], v[12:15]
	v_mfma_f32_16x16x32_bf16 v[8:11], v[158:161], v[206:209], v[8:11]
	v_mfma_f32_16x16x32_bf16 v[60:63], v[154:157], v[186:189], v[60:63]
	v_mfma_f32_16x16x32_bf16 v[56:59], v[162:165], v[186:189], v[56:59]
	v_mfma_f32_16x16x32_bf16 v[44:47], v[154:157], v[194:197], v[44:47]
	v_mfma_f32_16x16x32_bf16 v[40:43], v[162:165], v[194:197], v[40:43]
	v_mfma_f32_16x16x32_bf16 v[28:31], v[154:157], v[202:205], v[28:31]
	v_mfma_f32_16x16x32_bf16 v[24:27], v[162:165], v[202:205], v[24:27]
	v_mfma_f32_16x16x32_bf16 v[12:15], v[154:157], v[210:213], v[12:15]
	v_mfma_f32_16x16x32_bf16 v[8:11], v[162:165], v[210:213], v[8:11]
	v_mfma_f32_16x16x32_bf16 v[52:55], v[166:169], v[182:185], v[52:55]
	v_mfma_f32_16x16x32_bf16 v[48:51], v[174:177], v[182:185], v[48:51]
	v_mfma_f32_16x16x32_bf16 v[36:39], v[166:169], v[190:193], v[36:39]
	v_mfma_f32_16x16x32_bf16 v[32:35], v[174:177], v[190:193], v[32:35]
	v_mfma_f32_16x16x32_bf16 v[20:23], v[166:169], v[198:201], v[20:23]
	v_mfma_f32_16x16x32_bf16 v[16:19], v[174:177], v[198:201], v[16:19]
	v_mfma_f32_16x16x32_bf16 v[4:7], v[166:169], v[206:209], v[4:7]
	v_mfma_f32_16x16x32_bf16 v[0:3], v[174:177], v[206:209], v[0:3]
	v_mfma_f32_16x16x32_bf16 v[52:55], v[170:173], v[186:189], v[52:55]
	v_mfma_f32_16x16x32_bf16 v[48:51], v[178:181], v[186:189], v[48:51]
	v_mfma_f32_16x16x32_bf16 v[36:39], v[170:173], v[194:197], v[36:39]
	v_mfma_f32_16x16x32_bf16 v[32:35], v[178:181], v[194:197], v[32:35]
	v_mfma_f32_16x16x32_bf16 v[20:23], v[170:173], v[202:205], v[20:23]
	v_mfma_f32_16x16x32_bf16 v[16:19], v[178:181], v[202:205], v[16:19]
	v_mfma_f32_16x16x32_bf16 v[4:7], v[170:173], v[210:213], v[4:7]
	v_mfma_f32_16x16x32_bf16 v[0:3], v[178:181], v[210:213], v[0:3]
	s_barrier
	s_add_i32 s65, 0, 0x18000
	s_add_i32 s66, 0, 0x1c000
	v_add_u32_e32 v162, s65, v149
	v_add_u32_e32 v178, s66, v149
	ds_read_b128 v[144:147], v162
	ds_read_b128 v[154:157], v162 offset:1024
	ds_read_b128 v[158:161], v162 offset:2048
	ds_read_b128 v[162:165], v162 offset:3072
	ds_read_b128 v[166:169], v178
	ds_read_b128 v[170:173], v178 offset:1024
	ds_read_b128 v[174:177], v178 offset:2048
	ds_read_b128 v[178:181], v178 offset:3072
	s_add_u32 s48, s48, 0x80000
	s_addc_u32 s49, s49, 0
	s_mov_b32 m0, s51
	v_lshl_add_u64 v[222:223], s[48:49], 0, v[128:129]
	ds_read_b128 v[182:185], v153 offset:32768
	ds_read_b128 v[186:189], v153 offset:33792
	ds_read_b128 v[190:193], v153 offset:34816
	ds_read_b128 v[194:197], v153 offset:35840
	ds_read_b128 v[198:201], v153 offset:36864
	ds_read_b128 v[202:205], v153 offset:37888
	ds_read_b128 v[206:209], v153 offset:38912
	ds_read_b128 v[210:213], v153 offset:39936
	global_load_lds_dwordx4 v[222:223], off
	v_lshl_add_u64 v[222:223], s[48:49], 0, v[132:133]
	s_mov_b32 m0, s52
	s_nop 0
	global_load_lds_dwordx4 v[222:223], off
	s_waitcnt vmcnt(8)
	s_waitcnt lgkmcnt(0)
	s_barrier
	s_waitcnt lgkmcnt(0)
	v_mfma_f32_16x16x32_bf16 v[124:127], v[144:147], v[182:185], v[124:127]
	v_mfma_f32_16x16x32_bf16 v[120:123], v[158:161], v[182:185], v[120:123]
	v_mfma_f32_16x16x32_bf16 v[108:111], v[144:147], v[190:193], v[108:111]
	v_mfma_f32_16x16x32_bf16 v[104:107], v[158:161], v[190:193], v[104:107]
	v_mfma_f32_16x16x32_bf16 v[92:95], v[144:147], v[198:201], v[92:95]
	v_mfma_f32_16x16x32_bf16 v[88:91], v[158:161], v[198:201], v[88:91]
	v_mfma_f32_16x16x32_bf16 v[76:79], v[144:147], v[206:209], v[76:79]
	v_mfma_f32_16x16x32_bf16 v[72:75], v[158:161], v[206:209], v[72:75]
	v_mfma_f32_16x16x32_bf16 v[124:127], v[154:157], v[186:189], v[124:127]
	v_mfma_f32_16x16x32_bf16 v[120:123], v[162:165], v[186:189], v[120:123]
	v_mfma_f32_16x16x32_bf16 v[108:111], v[154:157], v[194:197], v[108:111]
	v_mfma_f32_16x16x32_bf16 v[104:107], v[162:165], v[194:197], v[104:107]
	v_mfma_f32_16x16x32_bf16 v[92:95], v[154:157], v[202:205], v[92:95]
	v_mfma_f32_16x16x32_bf16 v[88:91], v[162:165], v[202:205], v[88:91]
	v_mfma_f32_16x16x32_bf16 v[76:79], v[154:157], v[210:213], v[76:79]
	v_mfma_f32_16x16x32_bf16 v[72:75], v[162:165], v[210:213], v[72:75]
	v_mfma_f32_16x16x32_bf16 v[116:119], v[166:169], v[182:185], v[116:119]
	v_mfma_f32_16x16x32_bf16 v[112:115], v[174:177], v[182:185], v[112:115]
	v_mfma_f32_16x16x32_bf16 v[100:103], v[166:169], v[190:193], v[100:103]
	v_mfma_f32_16x16x32_bf16 v[96:99], v[174:177], v[190:193], v[96:99]
	v_mfma_f32_16x16x32_bf16 v[84:87], v[166:169], v[198:201], v[84:87]
	v_mfma_f32_16x16x32_bf16 v[80:83], v[174:177], v[198:201], v[80:83]
	v_mfma_f32_16x16x32_bf16 v[68:71], v[166:169], v[206:209], v[68:71]
	v_mfma_f32_16x16x32_bf16 v[64:67], v[174:177], v[206:209], v[64:67]
	v_mfma_f32_16x16x32_bf16 v[116:119], v[170:173], v[186:189], v[116:119]
	v_mfma_f32_16x16x32_bf16 v[112:115], v[178:181], v[186:189], v[112:115]
	v_mfma_f32_16x16x32_bf16 v[100:103], v[170:173], v[194:197], v[100:103]
	v_mfma_f32_16x16x32_bf16 v[96:99], v[178:181], v[194:197], v[96:99]
	v_mfma_f32_16x16x32_bf16 v[84:87], v[170:173], v[202:205], v[84:87]
	v_mfma_f32_16x16x32_bf16 v[80:83], v[178:181], v[202:205], v[80:83]
	v_mfma_f32_16x16x32_bf16 v[68:71], v[170:173], v[210:213], v[68:71]
	v_mfma_f32_16x16x32_bf16 v[64:67], v[178:181], v[210:213], v[64:67]
	s_barrier
; #define PG8_STAGE(bufoff, gbase, voff) do { _Pragma("unroll") for (int _i = 0; _i < 2; ++_i) \
;         __builtin_amdgcn_global_load_lds((const unsigned*)((const char*)(gbase) + (voff)[_i]), (LAS unsigned*)(lds + (bufoff) + ldsw + _i * 8192), 16, 0, 0); } while (0)
; #define PG8_LDA(dst, b, h) do { _Pragma("unroll") for (int m = 0; m < 4; ++m) _Pragma("unroll") for (int k = 0; k < 2; ++k) dst[m][k] = *(const LAS bf16x8*)(lds + PG8_SA(b, h) + aoff + m * 2048 + k * 1024); } while (0)
; #define PG8_MMA(ai, bj, At, Bt) do { __builtin_amdgcn_s_setprio(1); _Pragma("unroll") for (int m = 0; m < 4; ++m) _Pragma("unroll") for (int n = 0; n < 2; ++n) _Pragma("unroll") for (int k = 0; k < 2; ++k) \
;         acc[ai][bj][m][n] = __builtin_amdgcn_mfma_f32_16x16x32_bf16(Bt[n][k], At[m][k], acc[ai][bj][m][n], 0, 0, 0); __builtin_amdgcn_s_setprio(0); } while (0)
; #define PG8_WAIT_V(n) asm volatile("s_waitcnt vmcnt(" #n ")" ::: "memory")
; #define PG8_WAIT_L(n) asm volatile("s_waitcnt lgkmcnt(" #n ")" ::: "memory")
; #define PG8_BAR __builtin_amdgcn_s_barrier()
; #define PG8_SCHED __builtin_amdgcn_sched_barrier(0)
; template <class Epi>
; __device__ __forceinline__ void gemm_phase(LAS unsigned char* lds, const Gemm g, const StaticOrder& S, const Epi& E, int wave_s) {
;     ...
;             PG8_LDA(At, 1, 1); PG8_STAGE(PG8_SB(1, 0), b3, voffB); PG8_STAGE(PG8_SB(1, 1), b3 + hstepB, voffB); PG8_STAGE(PG8_SA(1, 0), a3, voffA);
;             PG8_WAIT_V(8); PG8_WAIT_L(0); PG8_BAR; PG8_MMA(1, 0, At, B0); PG8_MMA(1, 1, At, B1); PG8_BAR; PG8_SCHED;
;         }
	s_add_i32 s48, s65, s25
	v_lshl_add_u64 v[214:215], v[214:215], 0, s[28:29]
	s_mov_b32 m0, s48
	ds_read_b128 v[182:185], v153 offset:49152
	ds_read_b128 v[186:189], v153 offset:50176
	ds_read_b128 v[190:193], v153 offset:51200
	ds_read_b128 v[194:197], v153 offset:52224
	ds_read_b128 v[198:201], v153 offset:53248
	ds_read_b128 v[202:205], v153 offset:54272
	ds_read_b128 v[206:209], v153 offset:55296
	ds_read_b128 v[210:213], v153 offset:56320
	global_load_lds_dwordx4 v[214:215], off
	s_add_i32 m0, s48, 0x2000
	s_add_u32 s46, s46, 0x80080
	v_lshl_add_u64 v[214:215], v[216:217], 0, s[28:29]
	s_addc_u32 s47, s47, 0
	s_add_i32 s48, s66, s25
	global_load_lds_dwordx4 v[214:215], off
	v_lshl_add_u64 v[214:215], s[46:47], 0, v[130:131]
	s_mov_b32 m0, s48
	s_nop 0
	global_load_lds_dwordx4 v[214:215], off
	v_lshl_add_u64 v[214:215], s[46:47], 0, v[134:135]
	s_add_i32 m0, s48, 0x2000
	s_nop 0
	global_load_lds_dwordx4 v[214:215], off
	v_lshl_add_u64 v[214:215], v[218:219], 0, s[28:29]
	s_mov_b32 m0, s54
	s_nop 0
	global_load_lds_dwordx4 v[214:215], off
	v_lshl_add_u64 v[214:215], v[220:221], 0, s[28:29]
	s_mov_b32 m0, s55
	s_nop 0
	global_load_lds_dwordx4 v[214:215], off
	s_waitcnt vmcnt(8)
	s_waitcnt lgkmcnt(0)
	s_barrier
	s_waitcnt lgkmcnt(0)
	v_mfma_f32_16x16x32_bf16 v[60:63], v[144:147], v[182:185], v[60:63]
	v_mfma_f32_16x16x32_bf16 v[56:59], v[158:161], v[182:185], v[56:59]
	v_mfma_f32_16x16x32_bf16 v[44:47], v[144:147], v[190:193], v[44:47]
	v_mfma_f32_16x16x32_bf16 v[40:43], v[158:161], v[190:193], v[40:43]
	v_mfma_f32_16x16x32_bf16 v[28:31], v[144:147], v[198:201], v[28:31]
	v_mfma_f32_16x16x32_bf16 v[24:27], v[158:161], v[198:201], v[24:27]
	v_mfma_f32_16x16x32_bf16 v[12:15], v[144:147], v[206:209], v[12:15]
	v_mfma_f32_16x16x32_bf16 v[8:11], v[158:161], v[206:209], v[8:11]
	v_mfma_f32_16x16x32_bf16 v[60:63], v[154:157], v[186:189], v[60:63]
	v_mfma_f32_16x16x32_bf16 v[56:59], v[162:165], v[186:189], v[56:59]
	v_mfma_f32_16x16x32_bf16 v[44:47], v[154:157], v[194:197], v[44:47]
	v_mfma_f32_16x16x32_bf16 v[40:43], v[162:165], v[194:197], v[40:43]
	v_mfma_f32_16x16x32_bf16 v[28:31], v[154:157], v[202:205], v[28:31]
	v_mfma_f32_16x16x32_bf16 v[24:27], v[162:165], v[202:205], v[24:27]
	v_mfma_f32_16x16x32_bf16 v[12:15], v[154:157], v[210:213], v[12:15]
	v_mfma_f32_16x16x32_bf16 v[8:11], v[162:165], v[210:213], v[8:11]
	v_mfma_f32_16x16x32_bf16 v[52:55], v[166:169], v[182:185], v[52:55]
	v_mfma_f32_16x16x32_bf16 v[48:51], v[174:177], v[182:185], v[48:51]
	v_mfma_f32_16x16x32_bf16 v[36:39], v[166:169], v[190:193], v[36:39]
	v_mfma_f32_16x16x32_bf16 v[32:35], v[174:177], v[190:193], v[32:35]
	v_mfma_f32_16x16x32_bf16 v[20:23], v[166:169], v[198:201], v[20:23]
	v_mfma_f32_16x16x32_bf16 v[16:19], v[174:177], v[198:201], v[16:19]
	v_mfma_f32_16x16x32_bf16 v[4:7], v[166:169], v[206:209], v[4:7]
	v_mfma_f32_16x16x32_bf16 v[0:3], v[174:177], v[206:209], v[0:3]
	v_mfma_f32_16x16x32_bf16 v[52:55], v[170:173], v[186:189], v[52:55]
	v_mfma_f32_16x16x32_bf16 v[48:51], v[178:181], v[186:189], v[48:51]
	v_mfma_f32_16x16x32_bf16 v[36:39], v[170:173], v[194:197], v[36:39]
	v_mfma_f32_16x16x32_bf16 v[32:35], v[178:181], v[194:197], v[32:35]
	v_mfma_f32_16x16x32_bf16 v[20:23], v[170:173], v[202:205], v[20:23]
	v_mfma_f32_16x16x32_bf16 v[16:19], v[178:181], v[202:205], v[16:19]
	v_mfma_f32_16x16x32_bf16 v[4:7], v[170:173], v[210:213], v[4:7]
	v_mfma_f32_16x16x32_bf16 v[0:3], v[178:181], v[210:213], v[0:3]
	s_barrier
	s_add_i32 s64, s64, 2
	s_add_u32 s44, s44, 0x100
	s_addc_u32 s45, s45, 0
	s_add_u32 s62, s62, 0x100
	s_addc_u32 s63, s63, 0
	s_cmp_gt_u32 s64, 29
	s_cbranch_scc0 .LBB0_1371
	s_and_b64 vcc, exec, s[30:31]
	s_cbranch_vccz .LBB0_1374
	s_barrier

; __device__ __forceinline__ float bflo(unsigned w) { return __uint_as_float(w << 16); }
; __device__ __forceinline__ float bfhi(unsigned w) { return __uint_as_float(w & 0xffff0000u); }
; __device__ __forceinline__ void rms_row_b2f(const bf16_t* xrow, const float* g, float* orow, int lane) {
;     const u32x4* xr = (const u32x4*)xrow + lane; u32x4 w[4]; float s = 0.f;
; #pragma unroll
;     for (int j = 0; j < 4; ++j) { w[j] = xr[64 * j];
;         const float a0 = bflo(w[j].x), a1 = bfhi(w[j].x), a2 = bflo(w[j].y), a3 = bfhi(w[j].y), a4 = bflo(w[j].z), a5 = bfhi(w[j].z), a6 = bflo(w[j].w), a7 = bfhi(w[j].w);
;         s += ((a0 * a0 + a1 * a1) + (a2 * a2 + a3 * a3)) + ((a4 * a4 + a5 * a5) + (a6 * a6 + a7 * a7)); }
;     const float rstd = rsqrtf(wave_sum(s) * (1.f / DM) + EPS);
;     f32x4* o = (f32x4*)orow;
; #pragma unroll
;     for (int j = 0; j < 4; ++j) { const int q = (64 * j + lane) * 2; const f32x4 g0 = ((const f32x4*)g)[q], g1 = ((const f32x4*)g)[q + 1];
;         __builtin_nontemporal_store((f32x4){bflo(w[j].x) * rstd * g0.x, bfhi(w[j].x) * rstd * g0.y, bflo(w[j].y) * rstd * g0.z, bfhi(w[j].y) * rstd * g0.w}, o + q);
;         __builtin_nontemporal_store((f32x4){bflo(w[j].z) * rstd * g1.x, bfhi(w[j].z) * rstd * g1.y, bflo(w[j].w) * rstd * g1.z, bfhi(w[j].w) * rstd * g1.w}, o + q + 1); }
; }
; __global__ void __launch_bounds__(512, 2) mega(Params p) {
;     ...
;         const int tid = opaque_tid(wave_s), lane = tid & 63, wave = tid >> 6;
;         const int gw = bx * 8 + wave, NGW = G * 8;
;         for (int m = gw; m < MR; m += NGW) {
;             float* dst = (m < MP) ? p.out + O_YP + (size_t)m * DM : p.out + O_YS + (size_t)(m - MP) * DM;
;             rms_row_b2f((const bf16_t*)(ws + WS_X1) + (size_t)m * DM, p.in[23], dst, lane);
;         }
.LBB0_1412:
	s_setprio 0
	s_cmp_lt_i32 s18, 11
	s_cselect_b64 s[4:5], -1, 0
	s_and_b64 s[0:1], s[4:5], s[0:1]
	s_andn2_b64 vcc, exec, s[0:1]
	s_cbranch_vccnz .LBB0_1418
	s_mov_b64 exec, -1
	v_mbcnt_lo_u32_b32 v0, -1, 0
	v_mbcnt_hi_u32_b32 v0, -1, v0
	s_lshr_b32 s84, s24, 6
	s_lshl_b32 s85, s2, 3
	s_add_i32 s85, s85, s84
	v_readlane_b32 s86, v254, 14
	v_readlane_b32 s87, v254, 15
	v_lshlrev_b32_e32 v1, 5, v0
	v_add_u32_e32 v2, 0x1000, v1
	v_lshlrev_b32_e32 v3, 4, v0
	s_nop 2
	global_load_dwordx4 v[64:67], v1, s[86:87]
	global_load_dwordx4 v[68:71], v1, s[86:87] offset:16
	global_load_dwordx4 v[72:75], v1, s[86:87] offset:2048
	global_load_dwordx4 v[76:79], v1, s[86:87] offset:2064
	global_load_dwordx4 v[80:83], v2, s[86:87]
	global_load_dwordx4 v[84:87], v2, s[86:87] offset:16
	global_load_dwordx4 v[88:91], v2, s[86:87] offset:2048
	global_load_dwordx4 v[92:95], v2, s[86:87] offset:2064
	s_lshl_b32 s88, s85, 12
	s_add_u32 s90, s22, 0x17d2a000
	s_addc_u32 s91, s23, 0
	s_add_u32 s90, s90, s88
	s_addc_u32 s91, s91, 0
	s_lshl_b32 s88, s85, 13
	s_add_u32 s92, s20, s88
	s_addc_u32 s93, s21, 0
	v_mov_b32_e32 v4, 0x358637bd
	v_xor_b32_e32 v5, 1, v0
	v_lshlrev_b32_e32 v5, 2, v5
	v_xor_b32_e32 v6, 2, v0
	v_lshlrev_b32_e32 v6, 2, v6
	v_xor_b32_e32 v7, 4, v0
	v_lshlrev_b32_e32 v7, 2, v7
	v_xor_b32_e32 v8, 8, v0
	v_lshlrev_b32_e32 v8, 2, v8
	v_xor_b32_e32 v9, 16, v0
	v_lshlrev_b32_e32 v9, 2, v9
	v_xor_b32_e32 v10, 32, v0
	v_lshlrev_b32_e32 v10, 2, v10
	global_load_dwordx4 v[24:27], v3, s[90:91]
	global_load_dwordx4 v[28:31], v3, s[90:91] offset:1024
	global_load_dwordx4 v[32:35], v3, s[90:91] offset:2048
	global_load_dwordx4 v[36:39], v3, s[90:91] offset:3072
	s_waitcnt vmcnt(0)
